# W6 scan (R prio, split barriers, cross-interval prefetch) + hand-pipelined adaLN norm phases (3 rows in flight, scalar addressing, DPP/readlane wave sum)
# speedup vs baseline: 1.0055x; 1.0055x over previous
; __device__ __forceinline__ int opaque_tid() { int t = threadIdx.x; asm volatile("" : "+v"(t)); return t; }
; __device__ __forceinline__ unsigned cvt_pk_bf16(float lo, float hi) { unsigned r; asm volatile("v_cvt_pk_bf16_f32 %0, %1, %2" : "=v"(r) : "v"(lo), "v"(hi)); return r; }
; __device__ __forceinline__ void phase_norm_mod(const float* x, const float* mod_shift, const float* mod_scale, bf16_t* H, int) {
;     const int tid = opaque_tid(), lane = tid & 63, wave = tid >> 6;
;     const int gw = blockIdx.x * NWAVES + wave, NGW = gridDim.x * NWAVES;
;     constexpr int NR = 4;
;     for (int m0 = gw; m0 < M; m0 += NR * NGW) {
;         f32x4 v[NR][4];
; #pragma unroll
;         for (int r = 0; r < NR; ++r) { const int m = M - 1 - (m0 + r * NGW < M ? m0 + r * NGW : m0); const f32x4* xr = (const f32x4*)(x + (size_t)m * D) + lane;
; #pragma unroll
;             for (int j = 0; j < 4; ++j) v[r][j] = xr[64 * j]; }
; #pragma unroll
;         for (int r = 0; r < NR; ++r) { const int m = M - 1 - (m0 + r * NGW); if (m >= 0) {
;             const int b = m >> 12; float s = 0.f;
; #pragma unroll
;             for (int j = 0; j < 4; ++j) s += (v[r][j].x * v[r][j].x + v[r][j].y * v[r][j].y) + (v[r][j].z * v[r][j].z + v[r][j].w * v[r][j].w);
;             const float rstd = 1.0f / sqrtf(wave_sum(s) * (1.f / D) + 1e-6f);
;             const f32x4* sh = (const f32x4*)(mod_shift + (size_t)b * 6144) + lane;
;             const f32x4* sc = (const f32x4*)(mod_scale + (size_t)b * 6144) + lane;
;             u32x2* o = (u32x2*)(H + (size_t)m * D) + lane;
; #pragma unroll
;             for (int j = 0; j < 4; ++j) { const f32x4 a = sh[64 * j], c = sc[64 * j]; const f32x4 h = v[r][j] * rstd * (c + 1.0f) + a;
;                 u32x2 w; w.x = cvt_pk_bf16(h.x, h.y); w.y = cvt_pk_bf16(h.z, h.w); o[64 * j] = w; } } }
.LBB0_1052:
	s_cmp_lt_i32 s90, 6
	s_cselect_b64 s[8:9], -1, 0
	s_and_b64 s[0:1], s[8:9], s[0:1]
	s_andn2_b64 vcc, exec, s[0:1]
	s_cbranch_vccnz .LBB0_1063
	s_mov_b64 s[10:11], exec
	v_lshrrev_b32_e32 v176, 6, v180
	v_and_b32_e32 v177, 63, v180
	v_readfirstlane_b32 s0, v176
	v_lshlrev_b32_e32 v176, 4, v177
	v_lshlrev_b32_e32 v177, 3, v177
	v_mov_b32_e32 v170, 0x358637bd
	v_mov_b32_e32 v171, 0x260
	s_lshl_b32 s1, s24, 3
	s_add_i32 s0, s0, s1
	s_lshl_b32 s2, s28, 3
	s_mul_i32 s1, s2, 3
	s_mov_b32 s18, s0
	s_add_i32 s19, s0, s2
	s_add_i32 s20, s19, s2
	s_cmp_lt_u32 s0, 0x10000
	s_cbranch_scc0 .LNa_done
	s_cmp_lt_u32 s18, 0x10000
	s_cselect_b32 s3, s18, s0
	s_sub_u32 s3, 0xffff, s3
	s_lshl_b32 s4, s3, 12
	s_add_u32 s6, s86, s4
	s_addc_u32 s7, s87, 0
	s_lshr_b32 s4, s3, 12
	s_mul_i32 s4, s4, 0x6000
	s_add_u32 s12, s88, s4
	s_addc_u32 s13, s89, 0
	s_add_u32 s14, s12, 0x104000
	s_addc_u32 s15, s13, 0
	s_add_u32 s12, s12, 0x103000
	s_addc_u32 s13, s13, 0
	global_load_dwordx4 v[0:3], v176, s[6:7]
	global_load_dwordx4 v[4:7], v176, s[6:7] offset:1024
	global_load_dwordx4 v[8:11], v176, s[6:7] offset:2048
	global_load_dwordx4 v[12:15], v176, s[6:7] offset:3072
	global_load_dwordx4 v[16:19], v176, s[14:15]
	global_load_dwordx4 v[20:23], v176, s[14:15] offset:1024
	global_load_dwordx4 v[24:27], v176, s[14:15] offset:2048
	global_load_dwordx4 v[28:31], v176, s[14:15] offset:3072
	global_load_dwordx4 v[32:35], v176, s[12:13]
	global_load_dwordx4 v[36:39], v176, s[12:13] offset:1024
	global_load_dwordx4 v[40:43], v176, s[12:13] offset:2048
	global_load_dwordx4 v[44:47], v176, s[12:13] offset:3072
	s_cmp_lt_u32 s19, 0x10000
	s_cselect_b32 s3, s19, s0
	s_sub_u32 s3, 0xffff, s3
	s_lshl_b32 s4, s3, 12
	s_add_u32 s6, s86, s4
	s_addc_u32 s7, s87, 0
	s_lshr_b32 s4, s3, 12
	s_mul_i32 s4, s4, 0x6000
	s_add_u32 s12, s88, s4
	s_addc_u32 s13, s89, 0
	s_add_u32 s14, s12, 0x104000
	s_addc_u32 s15, s13, 0
	s_add_u32 s12, s12, 0x103000
	s_addc_u32 s13, s13, 0
	global_load_dwordx4 v[48:51], v176, s[6:7]
	global_load_dwordx4 v[52:55], v176, s[6:7] offset:1024
	global_load_dwordx4 v[56:59], v176, s[6:7] offset:2048
	global_load_dwordx4 v[60:63], v176, s[6:7] offset:3072
	global_load_dwordx4 v[64:67], v176, s[14:15]
	global_load_dwordx4 v[68:71], v176, s[14:15] offset:1024
	global_load_dwordx4 v[72:75], v176, s[14:15] offset:2048
	global_load_dwordx4 v[76:79], v176, s[14:15] offset:3072
	global_load_dwordx4 v[80:83], v176, s[12:13]
	global_load_dwordx4 v[84:87], v176, s[12:13] offset:1024
	global_load_dwordx4 v[88:91], v176, s[12:13] offset:2048
	global_load_dwordx4 v[92:95], v176, s[12:13] offset:3072
	s_cmp_lt_u32 s20, 0x10000
	s_cselect_b32 s3, s20, s0
	s_sub_u32 s3, 0xffff, s3
	s_lshl_b32 s4, s3, 12
	s_add_u32 s6, s86, s4
	s_addc_u32 s7, s87, 0
	s_lshr_b32 s4, s3, 12
	s_mul_i32 s4, s4, 0x6000
	s_add_u32 s12, s88, s4
	s_addc_u32 s13, s89, 0
	s_add_u32 s14, s12, 0x104000
	s_addc_u32 s15, s13, 0
	s_add_u32 s12, s12, 0x103000
	s_addc_u32 s13, s13, 0
	global_load_dwordx4 v[96:99], v176, s[6:7]
	global_load_dwordx4 v[100:103], v176, s[6:7] offset:1024
	global_load_dwordx4 v[104:107], v176, s[6:7] offset:2048
	global_load_dwordx4 v[108:111], v176, s[6:7] offset:3072
	global_load_dwordx4 v[112:115], v176, s[14:15]
	global_load_dwordx4 v[116:119], v176, s[14:15] offset:1024
	global_load_dwordx4 v[120:123], v176, s[14:15] offset:2048
	global_load_dwordx4 v[124:127], v176, s[14:15] offset:3072
	global_load_dwordx4 v[128:131], v176, s[12:13]
	global_load_dwordx4 v[132:135], v176, s[12:13] offset:1024
	global_load_dwordx4 v[136:139], v176, s[12:13] offset:2048
	global_load_dwordx4 v[140:143], v176, s[12:13] offset:3072
.LNa_loop:
	s_cmp_lt_u32 s18, 0x10000
	s_cbranch_scc0 .LNa_done
	s_waitcnt vmcnt(24)
	v_pk_mul_f32 v[172:173], v[0:1], v[0:1]
	v_pk_mul_f32 v[174:175], v[2:3], v[2:3]
	v_pk_fma_f32 v[172:173], v[4:5], v[4:5], v[172:173]
	v_pk_fma_f32 v[174:175], v[6:7], v[6:7], v[174:175]
	v_pk_fma_f32 v[172:173], v[8:9], v[8:9], v[172:173]
	v_pk_fma_f32 v[174:175], v[10:11], v[10:11], v[174:175]
	v_pk_fma_f32 v[172:173], v[12:13], v[12:13], v[172:173]
	v_pk_fma_f32 v[174:175], v[14:15], v[14:15], v[174:175]
	v_pk_add_f32 v[172:173], v[172:173], v[174:175]
	s_sub_u32 s3, 0xffff, s18
	s_lshl_b32 s4, s3, 11
	v_add_f32_e32 v160, v172, v173
	s_add_u32 s16, s88, s4
	s_addc_u32 s17, s89, 0
	s_nop 1
	v_add_f32_dpp v160, v160, v160 quad_perm:[1,0,3,2] row_mask:0xf bank_mask:0xf bound_ctrl:1
	s_nop 1
	v_add_f32_dpp v160, v160, v160 quad_perm:[2,3,0,1] row_mask:0xf bank_mask:0xf bound_ctrl:1
	s_nop 1
	v_add_f32_dpp v160, v160, v160 row_half_mirror row_mask:0xf bank_mask:0xf bound_ctrl:1
	s_nop 1
	v_add_f32_dpp v160, v160, v160 row_mirror row_mask:0xf bank_mask:0xf bound_ctrl:1
	s_add_u32 s16, s16, 0x3c00000
	s_addc_u32 s17, s17, 0
	v_readlane_b32 s4, v160, 0
	v_readlane_b32 s5, v160, 16
	v_readlane_b32 s21, v160, 32
	v_readlane_b32 s22, v160, 48
	s_nop 1
	v_mov_b32_e32 v160, s4
	v_add_f32_e32 v160, s5, v160
	v_add_f32_e32 v160, s21, v160
	v_add_f32_e32 v160, s22, v160
	v_fmamk_f32 v160, v160, 0x3a800000, v170
	s_mov_b32 s23, 0xf800000
	v_mul_f32_e32 v161, 0x4f800000, v160
	v_cmp_gt_f32_e32 vcc, s23, v160
	s_nop 1
	v_cndmask_b32_e32 v162, v160, v161, vcc
	v_sqrt_f32_e32 v164, v162
	s_nop 0
	v_add_u32_e32 v165, -1, v164
	v_add_u32_e32 v166, 1, v164
	v_fma_f32 v167, -v165, v164, v162
	v_fma_f32 v168, -v166, v164, v162
	v_cmp_ge_f32_e64 s[4:5], 0, v167
	s_nop 1
	v_cndmask_b32_e64 v164, v164, v165, s[4:5]
	v_cmp_lt_f32_e64 s[4:5], 0, v168
	s_nop 1
	v_cndmask_b32_e64 v164, v164, v166, s[4:5]
	v_mul_f32_e32 v165, 0x37800000, v164
	v_cndmask_b32_e32 v164, v164, v165, vcc
	v_cmp_class_f32_e32 vcc, v162, v171
; __device__ __forceinline__ unsigned cvt_pk_bf16(float lo, float hi) { unsigned r; asm volatile("v_cvt_pk_bf16_f32 %0, %1, %2" : "=v"(r) : "v"(lo), "v"(hi)); return r; }
; __device__ __forceinline__ void phase_norm_mod(const float* x, const float* mod_shift, const float* mod_scale, bf16_t* H, int) {
;     ...
;         for (int r = 0; r < NR; ++r) { const int m = M - 1 - (m0 + r * NGW < M ? m0 + r * NGW : m0); const f32x4* xr = (const f32x4*)(x + (size_t)m * D) + lane;
; #pragma unroll
;             for (int j = 0; j < 4; ++j) v[r][j] = xr[64 * j]; }
;     ...
;         for (int r = 0; r < NR; ++r) { const int m = M - 1 - (m0 + r * NGW); if (m >= 0) {
;             const int b = m >> 12; float s = 0.f;
; #pragma unroll
;             for (int j = 0; j < 4; ++j) s += (v[r][j].x * v[r][j].x + v[r][j].y * v[r][j].y) + (v[r][j].z * v[r][j].z + v[r][j].w * v[r][j].w);
;             const float rstd = 1.0f / sqrtf(wave_sum(s) * (1.f / D) + 1e-6f);
;             const f32x4* sh = (const f32x4*)(mod_shift + (size_t)b * 6144) + lane;
;             const f32x4* sc = (const f32x4*)(mod_scale + (size_t)b * 6144) + lane;
;             u32x2* o = (u32x2*)(H + (size_t)m * D) + lane;
; #pragma unroll
;             for (int j = 0; j < 4; ++j) { const f32x4 a = sh[64 * j], c = sc[64 * j]; const f32x4 h = v[r][j] * rstd * (c + 1.0f) + a;
;                 u32x2 w; w.x = cvt_pk_bf16(h.x, h.y); w.y = cvt_pk_bf16(h.z, h.w); o[64 * j] = w; } } }
	s_nop 1
	v_cndmask_b32_e32 v162, v164, v162, vcc
	v_div_scale_f32 v164, s[4:5], v162, v162, 1.0
	v_rcp_f32_e32 v165, v164
	v_div_scale_f32 v166, vcc, 1.0, v162, 1.0
	v_fma_f32 v167, -v164, v165, 1.0
	v_fmac_f32_e32 v165, v167, v165
	v_mul_f32_e32 v167, v166, v165
	v_fma_f32 v168, -v164, v167, v166
	v_fmac_f32_e32 v167, v168, v165
	v_fma_f32 v164, -v164, v167, v166
	v_div_fmas_f32 v164, v164, v165, v167
	v_div_fixup_f32 v162, v164, v162, 1.0
	v_pk_mul_f32 v[0:1], v[0:1], v[162:163] op_sel_hi:[1,0]
	v_pk_mul_f32 v[2:3], v[2:3], v[162:163] op_sel_hi:[1,0]
	v_pk_add_f32 v[16:17], v[16:17], 1.0 op_sel_hi:[1,0]
	v_pk_add_f32 v[18:19], v[18:19], 1.0 op_sel_hi:[1,0]
	v_pk_fma_f32 v[0:1], v[16:17], v[0:1], v[32:33]
	v_pk_fma_f32 v[2:3], v[18:19], v[2:3], v[34:35]
	v_cvt_pk_bf16_f32 v152, v0, v1
	v_cvt_pk_bf16_f32 v153, v2, v3
	v_pk_mul_f32 v[4:5], v[4:5], v[162:163] op_sel_hi:[1,0]
	v_pk_mul_f32 v[6:7], v[6:7], v[162:163] op_sel_hi:[1,0]
	v_pk_add_f32 v[20:21], v[20:21], 1.0 op_sel_hi:[1,0]
	v_pk_add_f32 v[22:23], v[22:23], 1.0 op_sel_hi:[1,0]
	v_pk_fma_f32 v[4:5], v[20:21], v[4:5], v[36:37]
	v_pk_fma_f32 v[6:7], v[22:23], v[6:7], v[38:39]
	v_cvt_pk_bf16_f32 v154, v4, v5
	v_cvt_pk_bf16_f32 v155, v6, v7
	v_pk_mul_f32 v[8:9], v[8:9], v[162:163] op_sel_hi:[1,0]
	v_pk_mul_f32 v[10:11], v[10:11], v[162:163] op_sel_hi:[1,0]
	v_pk_add_f32 v[24:25], v[24:25], 1.0 op_sel_hi:[1,0]
	v_pk_add_f32 v[26:27], v[26:27], 1.0 op_sel_hi:[1,0]
	v_pk_fma_f32 v[8:9], v[24:25], v[8:9], v[40:41]
	v_pk_fma_f32 v[10:11], v[26:27], v[10:11], v[42:43]
	v_cvt_pk_bf16_f32 v156, v8, v9
	v_cvt_pk_bf16_f32 v157, v10, v11
	v_pk_mul_f32 v[12:13], v[12:13], v[162:163] op_sel_hi:[1,0]
	v_pk_mul_f32 v[14:15], v[14:15], v[162:163] op_sel_hi:[1,0]
	v_pk_add_f32 v[28:29], v[28:29], 1.0 op_sel_hi:[1,0]
	v_pk_add_f32 v[30:31], v[30:31], 1.0 op_sel_hi:[1,0]
	v_pk_fma_f32 v[12:13], v[28:29], v[12:13], v[44:45]
	v_pk_fma_f32 v[14:15], v[30:31], v[14:15], v[46:47]
	v_cvt_pk_bf16_f32 v158, v12, v13
	v_cvt_pk_bf16_f32 v159, v14, v15
	global_store_dwordx2 v177, v[152:153], s[16:17]
	global_store_dwordx2 v177, v[154:155], s[16:17] offset:512
	global_store_dwordx2 v177, v[156:157], s[16:17] offset:1024
	global_store_dwordx2 v177, v[158:159], s[16:17] offset:1536
	s_add_i32 s18, s18, s1
	s_cmp_lt_u32 s18, 0x10000
	s_cselect_b32 s3, s18, s0
	s_sub_u32 s3, 0xffff, s3
	s_lshl_b32 s4, s3, 12
	s_add_u32 s6, s86, s4
	s_addc_u32 s7, s87, 0
	s_lshr_b32 s4, s3, 12
	s_mul_i32 s4, s4, 0x6000
	s_add_u32 s12, s88, s4
	s_addc_u32 s13, s89, 0
	s_add_u32 s14, s12, 0x104000
	s_addc_u32 s15, s13, 0
	s_add_u32 s12, s12, 0x103000
	s_addc_u32 s13, s13, 0
	global_load_dwordx4 v[0:3], v176, s[6:7]
	global_load_dwordx4 v[4:7], v176, s[6:7] offset:1024
	global_load_dwordx4 v[8:11], v176, s[6:7] offset:2048
	global_load_dwordx4 v[12:15], v176, s[6:7] offset:3072
	global_load_dwordx4 v[16:19], v176, s[14:15]
	global_load_dwordx4 v[20:23], v176, s[14:15] offset:1024
	global_load_dwordx4 v[24:27], v176, s[14:15] offset:2048
	global_load_dwordx4 v[28:31], v176, s[14:15] offset:3072
	global_load_dwordx4 v[32:35], v176, s[12:13]
	global_load_dwordx4 v[36:39], v176, s[12:13] offset:1024
	global_load_dwordx4 v[40:43], v176, s[12:13] offset:2048
	global_load_dwordx4 v[44:47], v176, s[12:13] offset:3072
	s_cmp_lt_u32 s19, 0x10000
	s_cbranch_scc0 .LNa_done
	s_waitcnt vmcnt(24)
	v_pk_mul_f32 v[172:173], v[48:49], v[48:49]
	v_pk_mul_f32 v[174:175], v[50:51], v[50:51]
	v_pk_fma_f32 v[172:173], v[52:53], v[52:53], v[172:173]
	v_pk_fma_f32 v[174:175], v[54:55], v[54:55], v[174:175]
	v_pk_fma_f32 v[172:173], v[56:57], v[56:57], v[172:173]
	v_pk_fma_f32 v[174:175], v[58:59], v[58:59], v[174:175]
	v_pk_fma_f32 v[172:173], v[60:61], v[60:61], v[172:173]
	v_pk_fma_f32 v[174:175], v[62:63], v[62:63], v[174:175]
	v_pk_add_f32 v[172:173], v[172:173], v[174:175]
	s_sub_u32 s3, 0xffff, s19
	s_lshl_b32 s4, s3, 11
	v_add_f32_e32 v160, v172, v173
	s_add_u32 s16, s88, s4
	s_addc_u32 s17, s89, 0
	s_nop 1
	v_add_f32_dpp v160, v160, v160 quad_perm:[1,0,3,2] row_mask:0xf bank_mask:0xf bound_ctrl:1
	s_nop 1
	v_add_f32_dpp v160, v160, v160 quad_perm:[2,3,0,1] row_mask:0xf bank_mask:0xf bound_ctrl:1
	s_nop 1
	v_add_f32_dpp v160, v160, v160 row_half_mirror row_mask:0xf bank_mask:0xf bound_ctrl:1
	s_nop 1
	v_add_f32_dpp v160, v160, v160 row_mirror row_mask:0xf bank_mask:0xf bound_ctrl:1
	s_add_u32 s16, s16, 0x3c00000
	s_addc_u32 s17, s17, 0
	v_readlane_b32 s4, v160, 0
	v_readlane_b32 s5, v160, 16
	v_readlane_b32 s21, v160, 32
	v_readlane_b32 s22, v160, 48
	s_nop 1
	v_mov_b32_e32 v160, s4
	v_add_f32_e32 v160, s5, v160
	v_add_f32_e32 v160, s21, v160
	v_add_f32_e32 v160, s22, v160
	v_fmamk_f32 v160, v160, 0x3a800000, v170
	s_mov_b32 s23, 0xf800000
	v_mul_f32_e32 v161, 0x4f800000, v160
	v_cmp_gt_f32_e32 vcc, s23, v160
	s_nop 1
	v_cndmask_b32_e32 v162, v160, v161, vcc
	v_sqrt_f32_e32 v164, v162
	s_nop 0
	v_add_u32_e32 v165, -1, v164
	v_add_u32_e32 v166, 1, v164
	v_fma_f32 v167, -v165, v164, v162
	v_fma_f32 v168, -v166, v164, v162
	v_cmp_ge_f32_e64 s[4:5], 0, v167
	s_nop 1
	v_cndmask_b32_e64 v164, v164, v165, s[4:5]
	v_cmp_lt_f32_e64 s[4:5], 0, v168
	s_nop 1
	v_cndmask_b32_e64 v164, v164, v166, s[4:5]
	v_mul_f32_e32 v165, 0x37800000, v164
	v_cndmask_b32_e32 v164, v164, v165, vcc
	v_cmp_class_f32_e32 vcc, v162, v171
	s_nop 1
	v_cndmask_b32_e32 v162, v164, v162, vcc
	v_div_scale_f32 v164, s[4:5], v162, v162, 1.0
	v_rcp_f32_e32 v165, v164
	v_div_scale_f32 v166, vcc, 1.0, v162, 1.0
	v_fma_f32 v167, -v164, v165, 1.0
	v_fmac_f32_e32 v165, v167, v165
	v_mul_f32_e32 v167, v166, v165
	v_fma_f32 v168, -v164, v167, v166
	v_fmac_f32_e32 v167, v168, v165
	v_fma_f32 v164, -v164, v167, v166
; __device__ __forceinline__ unsigned cvt_pk_bf16(float lo, float hi) { unsigned r; asm volatile("v_cvt_pk_bf16_f32 %0, %1, %2" : "=v"(r) : "v"(lo), "v"(hi)); return r; }
; __device__ __forceinline__ void phase_norm_mod(const float* x, const float* mod_shift, const float* mod_scale, bf16_t* H, int) {
;     ...
;         for (int r = 0; r < NR; ++r) { const int m = M - 1 - (m0 + r * NGW < M ? m0 + r * NGW : m0); const f32x4* xr = (const f32x4*)(x + (size_t)m * D) + lane;
; #pragma unroll
;             for (int j = 0; j < 4; ++j) v[r][j] = xr[64 * j]; }
;     ...
;         for (int r = 0; r < NR; ++r) { const int m = M - 1 - (m0 + r * NGW); if (m >= 0) {
;             const int b = m >> 12; float s = 0.f;
; #pragma unroll
;             for (int j = 0; j < 4; ++j) s += (v[r][j].x * v[r][j].x + v[r][j].y * v[r][j].y) + (v[r][j].z * v[r][j].z + v[r][j].w * v[r][j].w);
;             const float rstd = 1.0f / sqrtf(wave_sum(s) * (1.f / D) + 1e-6f);
;             const f32x4* sh = (const f32x4*)(mod_shift + (size_t)b * 6144) + lane;
;             const f32x4* sc = (const f32x4*)(mod_scale + (size_t)b * 6144) + lane;
;             u32x2* o = (u32x2*)(H + (size_t)m * D) + lane;
; #pragma unroll
;             for (int j = 0; j < 4; ++j) { const f32x4 a = sh[64 * j], c = sc[64 * j]; const f32x4 h = v[r][j] * rstd * (c + 1.0f) + a;
;                 u32x2 w; w.x = cvt_pk_bf16(h.x, h.y); w.y = cvt_pk_bf16(h.z, h.w); o[64 * j] = w; } } }
	v_div_fmas_f32 v164, v164, v165, v167
	v_div_fixup_f32 v162, v164, v162, 1.0
	v_pk_mul_f32 v[48:49], v[48:49], v[162:163] op_sel_hi:[1,0]
	v_pk_mul_f32 v[50:51], v[50:51], v[162:163] op_sel_hi:[1,0]
	v_pk_add_f32 v[64:65], v[64:65], 1.0 op_sel_hi:[1,0]
	v_pk_add_f32 v[66:67], v[66:67], 1.0 op_sel_hi:[1,0]
	v_pk_fma_f32 v[48:49], v[64:65], v[48:49], v[80:81]
	v_pk_fma_f32 v[50:51], v[66:67], v[50:51], v[82:83]
	v_cvt_pk_bf16_f32 v152, v48, v49
	v_cvt_pk_bf16_f32 v153, v50, v51
	v_pk_mul_f32 v[52:53], v[52:53], v[162:163] op_sel_hi:[1,0]
	v_pk_mul_f32 v[54:55], v[54:55], v[162:163] op_sel_hi:[1,0]
	v_pk_add_f32 v[68:69], v[68:69], 1.0 op_sel_hi:[1,0]
	v_pk_add_f32 v[70:71], v[70:71], 1.0 op_sel_hi:[1,0]
	v_pk_fma_f32 v[52:53], v[68:69], v[52:53], v[84:85]
	v_pk_fma_f32 v[54:55], v[70:71], v[54:55], v[86:87]
	v_cvt_pk_bf16_f32 v154, v52, v53
	v_cvt_pk_bf16_f32 v155, v54, v55
	v_pk_mul_f32 v[56:57], v[56:57], v[162:163] op_sel_hi:[1,0]
	v_pk_mul_f32 v[58:59], v[58:59], v[162:163] op_sel_hi:[1,0]
	v_pk_add_f32 v[72:73], v[72:73], 1.0 op_sel_hi:[1,0]
	v_pk_add_f32 v[74:75], v[74:75], 1.0 op_sel_hi:[1,0]
	v_pk_fma_f32 v[56:57], v[72:73], v[56:57], v[88:89]
	v_pk_fma_f32 v[58:59], v[74:75], v[58:59], v[90:91]
	v_cvt_pk_bf16_f32 v156, v56, v57
	v_cvt_pk_bf16_f32 v157, v58, v59
	v_pk_mul_f32 v[60:61], v[60:61], v[162:163] op_sel_hi:[1,0]
	v_pk_mul_f32 v[62:63], v[62:63], v[162:163] op_sel_hi:[1,0]
	v_pk_add_f32 v[76:77], v[76:77], 1.0 op_sel_hi:[1,0]
	v_pk_add_f32 v[78:79], v[78:79], 1.0 op_sel_hi:[1,0]
	v_pk_fma_f32 v[60:61], v[76:77], v[60:61], v[92:93]
	v_pk_fma_f32 v[62:63], v[78:79], v[62:63], v[94:95]
	v_cvt_pk_bf16_f32 v158, v60, v61
	v_cvt_pk_bf16_f32 v159, v62, v63
	global_store_dwordx2 v177, v[152:153], s[16:17]
	global_store_dwordx2 v177, v[154:155], s[16:17] offset:512
	global_store_dwordx2 v177, v[156:157], s[16:17] offset:1024
	global_store_dwordx2 v177, v[158:159], s[16:17] offset:1536
	s_add_i32 s19, s19, s1
	s_cmp_lt_u32 s19, 0x10000
	s_cselect_b32 s3, s19, s0
	s_sub_u32 s3, 0xffff, s3
	s_lshl_b32 s4, s3, 12
	s_add_u32 s6, s86, s4
	s_addc_u32 s7, s87, 0
	s_lshr_b32 s4, s3, 12
	s_mul_i32 s4, s4, 0x6000
	s_add_u32 s12, s88, s4
	s_addc_u32 s13, s89, 0
	s_add_u32 s14, s12, 0x104000
	s_addc_u32 s15, s13, 0
	s_add_u32 s12, s12, 0x103000
	s_addc_u32 s13, s13, 0
	global_load_dwordx4 v[48:51], v176, s[6:7]
	global_load_dwordx4 v[52:55], v176, s[6:7] offset:1024
	global_load_dwordx4 v[56:59], v176, s[6:7] offset:2048
	global_load_dwordx4 v[60:63], v176, s[6:7] offset:3072
	global_load_dwordx4 v[64:67], v176, s[14:15]
	global_load_dwordx4 v[68:71], v176, s[14:15] offset:1024
	global_load_dwordx4 v[72:75], v176, s[14:15] offset:2048
	global_load_dwordx4 v[76:79], v176, s[14:15] offset:3072
	global_load_dwordx4 v[80:83], v176, s[12:13]
	global_load_dwordx4 v[84:87], v176, s[12:13] offset:1024
	global_load_dwordx4 v[88:91], v176, s[12:13] offset:2048
	global_load_dwordx4 v[92:95], v176, s[12:13] offset:3072
	s_cmp_lt_u32 s20, 0x10000
	s_cbranch_scc0 .LNa_done
; __device__ __forceinline__ unsigned cvt_pk_bf16(float lo, float hi) { unsigned r; asm volatile("v_cvt_pk_bf16_f32 %0, %1, %2" : "=v"(r) : "v"(lo), "v"(hi)); return r; }
; __device__ __forceinline__ void phase_norm_mod(const float* x, const float* mod_shift, const float* mod_scale, bf16_t* H, int) {
;     ...
;         for (int r = 0; r < NR; ++r) { const int m = M - 1 - (m0 + r * NGW < M ? m0 + r * NGW : m0); const f32x4* xr = (const f32x4*)(x + (size_t)m * D) + lane;
; #pragma unroll
;             for (int j = 0; j < 4; ++j) v[r][j] = xr[64 * j]; }
;     ...
;         for (int r = 0; r < NR; ++r) { const int m = M - 1 - (m0 + r * NGW); if (m >= 0) {
;             const int b = m >> 12; float s = 0.f;
; #pragma unroll
;             for (int j = 0; j < 4; ++j) s += (v[r][j].x * v[r][j].x + v[r][j].y * v[r][j].y) + (v[r][j].z * v[r][j].z + v[r][j].w * v[r][j].w);
;             const float rstd = 1.0f / sqrtf(wave_sum(s) * (1.f / D) + 1e-6f);
;             const f32x4* sh = (const f32x4*)(mod_shift + (size_t)b * 6144) + lane;
;             const f32x4* sc = (const f32x4*)(mod_scale + (size_t)b * 6144) + lane;
;             u32x2* o = (u32x2*)(H + (size_t)m * D) + lane;
; #pragma unroll
;             for (int j = 0; j < 4; ++j) { const f32x4 a = sh[64 * j], c = sc[64 * j]; const f32x4 h = v[r][j] * rstd * (c + 1.0f) + a;
;                 u32x2 w; w.x = cvt_pk_bf16(h.x, h.y); w.y = cvt_pk_bf16(h.z, h.w); o[64 * j] = w; } } }
	s_waitcnt vmcnt(24)
	v_pk_mul_f32 v[172:173], v[96:97], v[96:97]
	v_pk_mul_f32 v[174:175], v[98:99], v[98:99]
	v_pk_fma_f32 v[172:173], v[100:101], v[100:101], v[172:173]
	v_pk_fma_f32 v[174:175], v[102:103], v[102:103], v[174:175]
	v_pk_fma_f32 v[172:173], v[104:105], v[104:105], v[172:173]
	v_pk_fma_f32 v[174:175], v[106:107], v[106:107], v[174:175]
	v_pk_fma_f32 v[172:173], v[108:109], v[108:109], v[172:173]
	v_pk_fma_f32 v[174:175], v[110:111], v[110:111], v[174:175]
	v_pk_add_f32 v[172:173], v[172:173], v[174:175]
	s_sub_u32 s3, 0xffff, s20
	s_lshl_b32 s4, s3, 11
	v_add_f32_e32 v160, v172, v173
	s_add_u32 s16, s88, s4
	s_addc_u32 s17, s89, 0
	s_nop 1
	v_add_f32_dpp v160, v160, v160 quad_perm:[1,0,3,2] row_mask:0xf bank_mask:0xf bound_ctrl:1
	s_nop 1
	v_add_f32_dpp v160, v160, v160 quad_perm:[2,3,0,1] row_mask:0xf bank_mask:0xf bound_ctrl:1
	s_nop 1
	v_add_f32_dpp v160, v160, v160 row_half_mirror row_mask:0xf bank_mask:0xf bound_ctrl:1
	s_nop 1
	v_add_f32_dpp v160, v160, v160 row_mirror row_mask:0xf bank_mask:0xf bound_ctrl:1
	s_add_u32 s16, s16, 0x3c00000
	s_addc_u32 s17, s17, 0
	v_readlane_b32 s4, v160, 0
	v_readlane_b32 s5, v160, 16
	v_readlane_b32 s21, v160, 32
	v_readlane_b32 s22, v160, 48
	s_nop 1
	v_mov_b32_e32 v160, s4
	v_add_f32_e32 v160, s5, v160
	v_add_f32_e32 v160, s21, v160
	v_add_f32_e32 v160, s22, v160
	v_fmamk_f32 v160, v160, 0x3a800000, v170
	s_mov_b32 s23, 0xf800000
	v_mul_f32_e32 v161, 0x4f800000, v160
	v_cmp_gt_f32_e32 vcc, s23, v160
	s_nop 1
	v_cndmask_b32_e32 v162, v160, v161, vcc
	v_sqrt_f32_e32 v164, v162
	s_nop 0
	v_add_u32_e32 v165, -1, v164
	v_add_u32_e32 v166, 1, v164
	v_fma_f32 v167, -v165, v164, v162
	v_fma_f32 v168, -v166, v164, v162
	v_cmp_ge_f32_e64 s[4:5], 0, v167
	s_nop 1
	v_cndmask_b32_e64 v164, v164, v165, s[4:5]
	v_cmp_lt_f32_e64 s[4:5], 0, v168
	s_nop 1
	v_cndmask_b32_e64 v164, v164, v166, s[4:5]
	v_mul_f32_e32 v165, 0x37800000, v164
	v_cndmask_b32_e32 v164, v164, v165, vcc
	v_cmp_class_f32_e32 vcc, v162, v171
	s_nop 1
	v_cndmask_b32_e32 v162, v164, v162, vcc
	v_div_scale_f32 v164, s[4:5], v162, v162, 1.0
	v_rcp_f32_e32 v165, v164
	v_div_scale_f32 v166, vcc, 1.0, v162, 1.0
	v_fma_f32 v167, -v164, v165, 1.0
	v_fmac_f32_e32 v165, v167, v165
	v_mul_f32_e32 v167, v166, v165
	v_fma_f32 v168, -v164, v167, v166
	v_fmac_f32_e32 v167, v168, v165
	v_fma_f32 v164, -v164, v167, v166
	v_div_fmas_f32 v164, v164, v165, v167
	v_div_fixup_f32 v162, v164, v162, 1.0
	v_pk_mul_f32 v[96:97], v[96:97], v[162:163] op_sel_hi:[1,0]
	v_pk_mul_f32 v[98:99], v[98:99], v[162:163] op_sel_hi:[1,0]
	v_pk_add_f32 v[112:113], v[112:113], 1.0 op_sel_hi:[1,0]
	v_pk_add_f32 v[114:115], v[114:115], 1.0 op_sel_hi:[1,0]
	v_pk_fma_f32 v[96:97], v[112:113], v[96:97], v[128:129]
	v_pk_fma_f32 v[98:99], v[114:115], v[98:99], v[130:131]
	v_cvt_pk_bf16_f32 v152, v96, v97
	v_cvt_pk_bf16_f32 v153, v98, v99
	v_pk_mul_f32 v[100:101], v[100:101], v[162:163] op_sel_hi:[1,0]
	v_pk_mul_f32 v[102:103], v[102:103], v[162:163] op_sel_hi:[1,0]
	v_pk_add_f32 v[116:117], v[116:117], 1.0 op_sel_hi:[1,0]
	v_pk_add_f32 v[118:119], v[118:119], 1.0 op_sel_hi:[1,0]
	v_pk_fma_f32 v[100:101], v[116:117], v[100:101], v[132:133]
	v_pk_fma_f32 v[102:103], v[118:119], v[102:103], v[134:135]
	v_cvt_pk_bf16_f32 v154, v100, v101
	v_cvt_pk_bf16_f32 v155, v102, v103
	v_pk_mul_f32 v[104:105], v[104:105], v[162:163] op_sel_hi:[1,0]
	v_pk_mul_f32 v[106:107], v[106:107], v[162:163] op_sel_hi:[1,0]
	v_pk_add_f32 v[120:121], v[120:121], 1.0 op_sel_hi:[1,0]
	v_pk_add_f32 v[122:123], v[122:123], 1.0 op_sel_hi:[1,0]
	v_pk_fma_f32 v[104:105], v[120:121], v[104:105], v[136:137]
	v_pk_fma_f32 v[106:107], v[122:123], v[106:107], v[138:139]
	v_cvt_pk_bf16_f32 v156, v104, v105
	v_cvt_pk_bf16_f32 v157, v106, v107
	v_pk_mul_f32 v[108:109], v[108:109], v[162:163] op_sel_hi:[1,0]
	v_pk_mul_f32 v[110:111], v[110:111], v[162:163] op_sel_hi:[1,0]
	v_pk_add_f32 v[124:125], v[124:125], 1.0 op_sel_hi:[1,0]
	v_pk_add_f32 v[126:127], v[126:127], 1.0 op_sel_hi:[1,0]
	v_pk_fma_f32 v[108:109], v[124:125], v[108:109], v[140:141]
	v_pk_fma_f32 v[110:111], v[126:127], v[110:111], v[142:143]
	v_cvt_pk_bf16_f32 v158, v108, v109
	v_cvt_pk_bf16_f32 v159, v110, v111
	global_store_dwordx2 v177, v[152:153], s[16:17]
	global_store_dwordx2 v177, v[154:155], s[16:17] offset:512
	global_store_dwordx2 v177, v[156:157], s[16:17] offset:1024
	global_store_dwordx2 v177, v[158:159], s[16:17] offset:1536
	s_add_i32 s20, s20, s1
	s_cmp_lt_u32 s20, 0x10000
	s_cselect_b32 s3, s20, s0
	s_sub_u32 s3, 0xffff, s3
	s_lshl_b32 s4, s3, 12
	s_add_u32 s6, s86, s4
	s_addc_u32 s7, s87, 0
	s_lshr_b32 s4, s3, 12
	s_mul_i32 s4, s4, 0x6000
	s_add_u32 s12, s88, s4
	s_addc_u32 s13, s89, 0
	s_add_u32 s14, s12, 0x104000
	s_addc_u32 s15, s13, 0
	s_add_u32 s12, s12, 0x103000
	s_addc_u32 s13, s13, 0
	global_load_dwordx4 v[96:99], v176, s[6:7]
	global_load_dwordx4 v[100:103], v176, s[6:7] offset:1024
	global_load_dwordx4 v[104:107], v176, s[6:7] offset:2048
	global_load_dwordx4 v[108:111], v176, s[6:7] offset:3072
	global_load_dwordx4 v[112:115], v176, s[14:15]
	global_load_dwordx4 v[116:119], v176, s[14:15] offset:1024
	global_load_dwordx4 v[120:123], v176, s[14:15] offset:2048
	global_load_dwordx4 v[124:127], v176, s[14:15] offset:3072
	global_load_dwordx4 v[128:131], v176, s[12:13]
	global_load_dwordx4 v[132:135], v176, s[12:13] offset:1024
	global_load_dwordx4 v[136:139], v176, s[12:13] offset:2048
	global_load_dwordx4 v[140:143], v176, s[12:13] offset:3072
	s_branch .LNa_loop
.LNa_done:
.LBB0_1062:
	s_or_b64 exec, exec, s[10:11]

; __device__ __forceinline__ void phase_scan(const Args& a, LAS unsigned char* lds) {
;     ...
;     for (int hd = blockIdx.x; hd < NB * 16; hd += gridDim.x) {
;         const int b = hd >> 4, h = hd & 15;
;         const int ch = h * 64 + jg * 4;
;         const f32x4 kk4 = *(const f32x4*)(a.in[22] + ch), ka4 = *(const f32x4*)(a.in[23] + ch), rk4 = *(const f32x4*)(a.in[24] + ch);
;         const f32x4 lg4 = *(const f32x4*)(a.in[25] + ch), lb4 = *(const f32x4*)(a.in[26] + ch);
;         const size_t base = ((size_t)b * T) * D + ch;
;         f32x2 C0 = {0.f, 0.f}, C1 = {0.f, 0.f}, C2 = {0.f, 0.f}, C3 = {0.f, 0.f};
;         size_t off = base + (size_t)ts * D;
;         u32x2 pr = *(const u32x2*)(Rg + off), pk = *(const u32x2*)(Kg + off), pv = *(const u32x2*)(Vg + off);
;         const int chn = h * 64 + ntile * 16 + fr;
;         bf16x8 bw[2], ba[2], bg[5];
; #pragma unroll
;         for (int ks = 0; ks < 2; ++ks) { bw[ks] = *(const bf16x8*)(WL2 + (size_t)chn * 512 + ks * 32 + fq * 8); ba[ks] = *(const bf16x8*)(WL2 + (size_t)(1024 + chn) * 512 + 128 + ks * 32 + fq * 8); }
; #pragma unroll
;         for (int ks = 0; ks < 5; ++ks) bg[ks] = *(const bf16x8*)(WL2 + (size_t)(2048 + chn) * 512 + 256 + ks * 32 + fq * 8);
;         const float w0c = a.in[14][chn], a0c = a.in[17][chn];
;         bf16x8 aw[2], aa[2], ag[5];
;     ...
;         LORA_LOAD(0); LORA_RUN();
;         __syncthreads();
.LBB0_2063:
	v_cmp_lt_u32_e32 vcc, 0xff, v180
	s_cbranch_vccz .LW_rhead
	s_lshl_b32 s12, s22, 6
	s_ashr_i32 s18, s22, 4
	s_and_b32 s12, s12, 0x3c0
	s_ashr_i32 s19, s18, 31
	v_or_b32_e32 v24, s12, v182
	v_lshlrev_b32_e32 v144, 10, v24
	s_lshl_b64 s[26:27], s[18:19], 12
	v_lshl_add_u64 v[0:1], s[8:9], 0, v[144:145]
	v_lshl_add_u64 v[154:155], s[26:27], 0, v[146:147]
	v_lshl_add_u64 v[20:21], v[0:1], 0, v[152:153]
	v_lshlrev_b64 v[0:1], 10, v[154:155]
	v_lshl_add_u64 v[56:57], v[148:149], 0, v[0:1]
	global_load_dwordx4 v[32:35], v[56:57], off offset:512
	v_add_co_u32_e32 v0, vcc, s21, v20
	v_lshl_add_u64 v[58:59], v[20:21], 0, s[16:17]
	s_nop 0
	v_addc_co_u32_e32 v1, vcc, 0, v21, vcc
	v_add_co_u32_e32 v8, vcc, s20, v20
	global_load_dwordx4 v[0:3], v[0:1], off offset:512
	s_nop 0
	global_load_dwordx4 v[28:31], v[56:57], off
	global_load_dwordx4 v[4:7], v[20:21], off
	global_load_dwordx4 v[36:39], v[56:57], off offset:256
	v_addc_co_u32_e32 v9, vcc, 0, v21, vcc
	global_load_dwordx4 v[8:11], v[8:9], off offset:256
	s_nop 0
	global_load_dwordx4 v[44:47], v[56:57], off offset:576
	global_load_dwordx4 v[12:15], v[58:59], off offset:64
	global_load_dwordx4 v[40:43], v[56:57], off offset:64
	global_load_dwordx4 v[16:19], v[20:21], off offset:64
	global_load_dwordx4 v[48:51], v[56:57], off offset:320
	v_lshl_add_u64 v[20:21], v[20:21], 0, s[14:15]
	global_load_dwordx4 v[20:23], v[20:21], off offset:64
	s_nop 0
	global_load_dwordx4 v[60:63], v[56:57], off offset:640
	v_lshlrev_b32_e32 v52, 2, v24
	global_load_dwordx4 v[24:27], v[58:59], off offset:128
	global_load_dword v199, v52, s[48:49]
	v_readlane_b32 s36, v234, 4
	v_readlane_b32 s38, v234, 6
	v_readlane_b32 s39, v234, 7
	s_nop 4
	global_load_dword v200, v52, s[38:39]
	global_load_dwordx4 v[84:87], v[56:57], off offset:704
	s_nop 0
	global_load_dwordx4 v[52:55], v[58:59], off offset:192
	global_load_dwordx4 v[88:91], v[56:57], off offset:768
	v_or_b32_e32 v64, s12, v181
	s_lshl_b64 s[18:19], s[18:19], 22
	v_readlane_b32 s48, v234, 16
	v_readlane_b32 s49, v234, 17
	v_lshlrev_b32_e32 v104, 2, v64
	v_or_b32_e32 v156, s18, v64
	v_mov_b32_e32 v157, s19
	v_readlane_b32 s50, v234, 18
	v_readlane_b32 s51, v234, 19
	global_load_dwordx4 v[56:59], v[58:59], off offset:256
	s_nop 0
	global_load_dwordx4 v[64:67], v104, s[48:49]
	s_nop 1
	global_load_dwordx4 v[68:71], v104, s[50:51]
	global_load_dwordx4 v[72:75], v104, s[52:53]
	global_load_dwordx4 v[76:79], v104, s[54:55]
	v_mov_b32_e32 v144, v145
	v_lshl_add_u64 v[164:165], v[156:157], 1, s[10:11]
	v_mov_b64_e32 v[172:173], v[144:145]
	v_mov_b64_e32 v[170:171], v[144:145]
	v_mov_b64_e32 v[166:167], v[144:145]
	v_mov_b64_e32 v[168:169], v[144:145]
	s_mov_b32 s12, s13
	v_readlane_b32 s37, v234, 5
	v_readlane_b32 s40, v234, 8
	v_readlane_b32 s41, v234, 9
	v_readlane_b32 s42, v234, 10
	v_readlane_b32 s43, v234, 11
	v_readlane_b32 s44, v234, 12
	v_readlane_b32 s45, v234, 13
	v_readlane_b32 s46, v234, 14
	v_readlane_b32 s47, v234, 15
	s_waitcnt vmcnt(0)
	v_mfma_f32_16x16x32_bf16 v[92:95], v[28:31], v[4:7], 0
	v_mfma_f32_16x16x32_bf16 v[80:83], v[32:35], v[0:3], 0
	v_mfma_f32_16x16x32_bf16 v[100:103], v[44:47], v[12:15], v[80:83]
	v_mfma_f32_16x16x32_bf16 v[92:95], v[40:43], v[16:19], v[92:95]
	s_nop 5
	global_load_dwordx4 v[80:83], v104, s[56:57]
	v_lshl_add_u64 v[104:105], v[156:157], 0, v[142:143]
	v_lshlrev_b64 v[104:105], 1, v[104:105]
	v_lshl_add_u64 v[106:107], s[2:3], 0, v[104:105]
	v_lshl_add_u64 v[108:109], s[4:5], 0, v[104:105]
	v_lshl_add_u64 v[104:105], s[6:7], 0, v[104:105]
	global_load_dwordx2 v[158:159], v[106:107], off
	global_load_dwordx2 v[160:161], v[108:109], off
	global_load_dwordx2 v[162:163], v[104:105], off
	v_mfma_f32_16x16x32_bf16 v[96:99], v[36:39], v[8:11], 0
	v_add_f32_e32 v92, v199, v92
	v_add_f32_e32 v93, v199, v93
	v_mul_f32_e32 v92, 0xbfb8aa3b, v92
	v_mul_f32_e32 v93, 0xbfb8aa3b, v93
	v_mfma_f32_16x16x32_bf16 v[100:103], v[60:63], v[24:27], v[100:103]
	v_exp_f32_e32 v104, v92
	v_exp_f32_e32 v105, v93
	v_add_f32_e32 v94, v199, v94
	v_mfma_f32_16x16x32_bf16 v[96:99], v[48:51], v[20:23], v[96:99]
	v_add_f32_e32 v95, v199, v95
	v_mul_f32_e32 v94, 0xbfb8aa3b, v94
	v_mul_f32_e32 v95, 0xbfb8aa3b, v95
	v_exp_f32_e32 v106, v94
	v_exp_f32_e32 v107, v95
	v_mfma_f32_16x16x32_bf16 v[92:95], v[84:87], v[52:55], v[100:103]
	s_nop 1
	v_add_f32_e32 v96, v200, v96
	v_add_f32_e32 v97, v200, v97
	v_mul_f32_e32 v96, 0xbfb8aa3b, v96
	v_add_f32_e32 v100, 1.0, v104
	v_add_f32_e32 v101, 1.0, v105
	v_rcp_f32_e32 v100, v100
	v_rcp_f32_e32 v101, v101
	v_mul_f32_e32 v97, 0xbfb8aa3b, v97
	v_exp_f32_e32 v96, v96
	v_exp_f32_e32 v97, v97
	v_add_f32_e32 v98, v200, v98
	v_add_f32_e32 v99, v200, v99
	v_add_f32_e32 v102, 1.0, v106
	v_add_f32_e32 v103, 1.0, v107
	v_mul_f32_e32 v100, 0xbf60029d, v100
	v_mul_f32_e32 v101, 0xbf60029d, v101
	v_mul_f32_e32 v98, 0xbfb8aa3b, v98
	v_mul_f32_e32 v99, 0xbfb8aa3b, v99
	v_rcp_f32_e32 v102, v102
	v_rcp_f32_e32 v103, v103
	v_exp_f32_e32 v100, v100
	v_exp_f32_e32 v101, v101
	v_exp_f32_e32 v98, v98
	v_exp_f32_e32 v99, v99
	v_add_f32_e32 v96, 1.0, v96
	v_add_f32_e32 v97, 1.0, v97
	v_rcp_f32_e32 v96, v96
	v_rcp_f32_e32 v97, v97
	v_mfma_f32_16x16x32_bf16 v[92:95], v[88:91], v[56:59], v[92:95]
	v_mul_f32_e32 v102, 0xbf60029d, v102
	ds_write2_b32 v191, v100, v101 offset1:68
	v_mul_f32_e32 v100, 0xbf60029d, v103
	v_add_f32_e32 v98, 1.0, v98
	v_exp_f32_e32 v102, v102
	v_exp_f32_e32 v100, v100
	v_add_f32_e32 v99, 1.0, v99
	v_rcp_f32_e32 v98, v98
	v_rcp_f32_e32 v99, v99
	ds_write2_b32 v196, v96, v97 offset0:128 offset1:196
	ds_write2_b32 v197, v92, v93 offset1:68
	ds_write2_b32 v191, v102, v100 offset0:136 offset1:204
	ds_write2_b32 v198, v98, v99 offset0:8 offset1:76
	ds_write2_b32 v197, v94, v95 offset0:136 offset1:204
	v_mov_b32_e32 v100, 0
	v_mov_b32_e32 v101, v145
	s_waitcnt lgkmcnt(0)
	s_barrier
; #define LAS __attribute__((address_space(3)))
; __device__ __forceinline__ void phase_scan(const Args& a, LAS unsigned char* lds) {
;     ...
;         for (int c = 0; c < T / TC; ++c) {
;             const f32x4 r4 = {bf_lo(pr.x), bf_hi(pr.x), bf_lo(pr.y), bf_hi(pr.y)};
;             const f32x4 k4 = {bf_lo(pk.x), bf_hi(pk.x), bf_lo(pk.y), bf_hi(pk.y)};
;             const f32x4 v4 = {bf_lo(pv.x), bf_hi(pv.x), bf_lo(pv.y), bf_hi(pv.y)};
;             const f32x4 w4 = *(const LAS f32x4*)(xb + ts * XS + jg * 4), a4 = *(const LAS f32x4*)(xb + TC * XS + ts * XS + jg * 4), g4 = *(const LAS f32x4*)(xb + 2 * TC * XS + ts * XS + jg * 4);
;             const f32x4 kkx = k4 * kk4;
;             const float ss = reduce16((kkx.x * kkx.x + kkx.y * kkx.y) + (kkx.z * kkx.z + kkx.w * kkx.w));
;             const float inv = __builtin_amdgcn_rsqf(fmaxf(ss, 1e-24f));
;             const f32x4 kk = kkx * inv;
;             const f32x4 kf = k4 * ((a4 - 1.0f) * ka4 + 1.0f);
;             const f32x4 am = -kk, bm = kk * a4;
;             const f32x4 rkr = r4 * kf * rk4;
;             const float ct = reduce16((rkr.x + rkr.y) + (rkr.z + rkr.w));
;             {
;                 LAS f32x4* o = (LAS f32x4*)(op + (ts * 16 + jg) * 20);
;                 o[0] = w4; o[1] = am; o[2] = bm; o[3] = kf; o[4] = r4;
;                 *(LAS f32x4*)(vb + ts * 64 + jg * 4) = v4;
;             }
;             __syncthreads();
;             if (c > 0) *(u32x2*)(YG + base + (size_t)((c - 1) * TC + ts) * D) = ypend;
;             if (c + 1 < T / TC) { off = base + (size_t)((c + 1) * TC + ts) * D;
;                 pr = *(const u32x2*)(Rg + off); pk = *(const u32x2*)(Kg + off); pv = *(const u32x2*)(Vg + off);
;                 LORA_LOAD(c + 1); }
	s_mov_b32 s40, 0x3300
	s_mov_b32 s41, 0x3300
	s_mov_b32 s42, 0x5500
	s_mov_b32 s43, 0x1100
	s_mov_b32 s44, 0x8000
	v_add_u32_e32 v191, s41, v191
	v_add_u32_e32 v196, s41, v196
	v_add_u32_e32 v197, s41, v197
	v_add_u32_e32 v198, s41, v198
	s_sub_i32 s41, 0, s41
	s_mov_b32 s12, 16
	v_lshl_add_u64 v[28:29], v[154:155], 0, s[12:13]
	v_lshlrev_b64 v[28:29], 10, v[28:29]
	v_lshl_add_u64 v[88:89], v[148:149], 0, v[28:29]
	global_load_dwordx4 v[28:31], v[88:89], off
	global_load_dwordx4 v[40:43], v[88:89], off offset:64
	global_load_dwordx4 v[36:39], v[88:89], off offset:256
	global_load_dwordx4 v[48:51], v[88:89], off offset:320
	global_load_dwordx4 v[32:35], v[88:89], off offset:512
	global_load_dwordx4 v[44:47], v[88:89], off offset:576
	global_load_dwordx4 v[60:63], v[88:89], off offset:640
	global_load_dwordx4 v[84:87], v[88:89], off offset:704
	s_nop 0
	global_load_dwordx4 v[88:91], v[88:89], off offset:768
	s_waitcnt vmcnt(1)
	v_lshlrev_b32_e32 v114, 16, v160
	v_and_b32_e32 v115, 0xffff0000, v160
	v_lshlrev_b32_e32 v116, 16, v161
	v_and_b32_e32 v117, 0xffff0000, v161
	v_pk_mul_f32 v[118:119], v[64:65], v[114:115]
	v_pk_mul_f32 v[120:121], v[66:67], v[116:117]
	v_pk_mul_f32 v[124:125], v[118:119], v[118:119]
	v_pk_mul_f32 v[122:123], v[120:121], v[120:121]
	ds_read_b128 v[106:109], v183
	ds_read_b128 v[110:113], v184
	ds_read_b128 v[96:99], v185
	v_pk_mov_b32 v[126:127], v[124:125], v[122:123] op_sel:[1,0]
	v_mov_b32_e32 v125, v123
	v_pk_add_f32 v[122:123], v[126:127], v[124:125]
	s_waitcnt lgkmcnt(1)
	v_pk_add_f32 v[124:125], v[112:113], -1.0 op_sel_hi:[1,0]
	v_add_f32_e32 v122, v122, v123
	v_pk_add_f32 v[126:127], v[110:111], -1.0 op_sel_hi:[1,0]
	v_pk_fma_f32 v[124:125], v[70:71], v[124:125], 1.0 op_sel_hi:[1,1,0]
	v_add_f32_dpp v122, v122, v122 quad_perm:[1,0,3,2] row_mask:0xf bank_mask:0xf bound_ctrl:1
	v_pk_fma_f32 v[126:127], v[68:69], v[126:127], 1.0 op_sel_hi:[1,1,0]
	v_lshlrev_b32_e32 v102, 16, v158
	v_add_f32_dpp v122, v122, v122 quad_perm:[2,3,0,1] row_mask:0xf bank_mask:0xf bound_ctrl:1
	v_and_b32_e32 v103, 0xffff0000, v158
	v_lshlrev_b32_e32 v104, 16, v159
	v_add_f32_dpp v122, v122, v122 row_half_mirror row_mask:0xf bank_mask:0xf bound_ctrl:1
	v_and_b32_e32 v105, 0xffff0000, v159
	v_pk_mul_f32 v[116:117], v[124:125], v[116:117]
	v_add_f32_dpp v122, v122, v122 row_mirror row_mask:0xf bank_mask:0xf bound_ctrl:1
	v_max_f32_e32 v122, 0x179abe15, v122
	v_rsq_f32_e32 v122, v122
	v_pk_mul_f32 v[114:115], v[126:127], v[114:115]
	v_pk_mul_f32 v[124:125], v[116:117], v[104:105]
	s_waitcnt vmcnt(0)
	v_lshlrev_b32_e32 v92, 16, v162
	v_pk_mul_f32 v[120:121], v[120:121], v[122:123] op_sel_hi:[1,0] neg_lo:[0,1] neg_hi:[0,1]
	v_pk_mul_f32 v[118:119], v[118:119], v[122:123] op_sel_hi:[1,0] neg_lo:[0,1] neg_hi:[0,1]
	v_pk_mul_f32 v[122:123], v[114:115], v[102:103]
	v_pk_mul_f32 v[124:125], v[74:75], v[124:125]
	v_pk_mul_f32 v[122:123], v[72:73], v[122:123]
	v_and_b32_e32 v93, 0xffff0000, v162
	v_add_f32_e32 v122, v122, v123
	v_add_f32_e32 v123, v124, v125
	v_add_f32_e32 v122, v122, v123
	v_lshlrev_b32_e32 v94, 16, v163
	v_and_b32_e32 v95, 0xffff0000, v163
	v_add_f32_dpp v122, v122, v122 quad_perm:[1,0,3,2] row_mask:0xf bank_mask:0xf bound_ctrl:1
	v_pk_mul_f32 v[112:113], v[112:113], v[120:121] neg_lo:[0,1] neg_hi:[0,1]
	v_add_f32_dpp v122, v122, v122 quad_perm:[2,3,0,1] row_mask:0xf bank_mask:0xf bound_ctrl:1
	v_pk_mul_f32 v[110:111], v[110:111], v[118:119] neg_lo:[0,1] neg_hi:[0,1]
	ds_write_b128 v192, v[106:109]
	ds_write_b128 v192, v[118:121] offset:16
	ds_write_b128 v192, v[110:113] offset:32
	ds_write_b128 v192, v[114:117] offset:48
	ds_write_b128 v192, v[102:105] offset:64
	ds_write_b128 v186, v[92:95] offset:43520
	v_add_f32_dpp v144, v122, v122 row_half_mirror row_mask:0xf bank_mask:0xf bound_ctrl:1
	s_nop 1
	v_mov_b32_dpp v201, v144 row_mirror row_mask:0xf bank_mask:0xf bound_ctrl:1
	v_mov_b32_e32 v246, v236
	v_mov_b32_e32 v247, v237
	v_mov_b32_e32 v248, v238
	v_mov_b32_e32 v249, v239
	v_mov_b32_e32 v250, v240
	v_mov_b32_e32 v251, v241
	v_mov_b32_e32 v252, v242
	v_mov_b32_e32 v253, v243
	v_mov_b32_e32 v254, v244
	v_mov_b32_e32 v255, v245
	v_mov_b32_e32 v236, v92
	v_mov_b32_e32 v237, v93
	v_mov_b32_e32 v238, v94
	v_mov_b32_e32 v239, v95
	v_mov_b32_e32 v240, v96
	v_mov_b32_e32 v241, v97
	v_mov_b32_e32 v242, v98
	v_mov_b32_e32 v243, v99
	v_mov_b32_e32 v244, v144
	v_mov_b32_e32 v245, v201
	v_add_u32_e32 v192, s42, v192
	v_add_u32_e32 v186, s43, v186
	v_add_u32_e32 v183, s40, v183
	v_add_u32_e32 v184, s40, v184
	v_add_u32_e32 v185, s40, v185
	s_sub_i32 s42, 0, s42
	s_sub_i32 s43, 0, s43
	s_sub_i32 s40, 0, s40
	s_waitcnt vmcnt(8)
	v_mfma_f32_16x16x32_bf16 v[92:95], v[28:31], v[4:7], 0
	s_waitcnt vmcnt(7)
	v_mfma_f32_16x16x32_bf16 v[92:95], v[40:43], v[16:19], v[92:95]
	s_waitcnt vmcnt(6)
	v_mfma_f32_16x16x32_bf16 v[96:99], v[36:39], v[8:11], 0
	s_waitcnt vmcnt(4)
	v_mfma_f32_16x16x32_bf16 v[102:105], v[32:35], v[0:3], 0
	s_nop 3
	v_add_f32_e32 v92, v199, v92
	v_add_f32_e32 v93, v199, v93
	v_mul_f32_e32 v92, 0xbfb8aa3b, v92
	v_mul_f32_e32 v93, 0xbfb8aa3b, v93
	v_exp_f32_e32 v92, v92
	v_exp_f32_e32 v93, v93
	v_mfma_f32_16x16x32_bf16 v[96:99], v[48:51], v[20:23], v[96:99]
	v_add_f32_e32 v95, v199, v95
	v_add_f32_e32 v92, 1.0, v92
	v_add_f32_e32 v93, 1.0, v93
	v_rcp_f32_e32 v92, v92
	v_rcp_f32_e32 v93, v93
	s_waitcnt vmcnt(3)
	v_mfma_f32_16x16x32_bf16 v[102:105], v[44:47], v[12:15], v[102:105]
	v_mul_f32_e32 v95, 0xbfb8aa3b, v95
	v_mul_f32_e32 v92, 0xbf60029d, v92
	v_mul_f32_e32 v93, 0xbf60029d, v93
	v_exp_f32_e32 v92, v92
	v_exp_f32_e32 v93, v93
	v_exp_f32_e32 v95, v95
	v_add_f32_e32 v96, v200, v96
	s_waitcnt vmcnt(2)
; #define LAS __attribute__((address_space(3)))
; __device__ __forceinline__ unsigned cvt_pk_bf16(float lo, float hi) { unsigned r; asm volatile("v_cvt_pk_bf16_f32 %0, %1, %2" : "=v"(r) : "v"(lo), "v"(hi)); return r; }
; __device__ __forceinline__ void phase_scan(const Args& a, LAS unsigned char* lds) {
;     ...
;             {
;                 const LAS f32x4* yq = (const LAS f32x4*)(yb + (ts * 32 + 2 * jg) * 16);
;                 const f32x4 A = (yq[0] + yq[1]) + (yq[2] + yq[3]), B = (yq[4] + yq[5]) + (yq[6] + yq[7]);
;                 const f32x4 y4 = {A.x + A.z, A.y + A.w, B.x + B.z, B.y + B.w};
;                 const float mean = reduce16((y4.x + y4.y) + (y4.z + y4.w)) * (1.f / 64.f);
;                 const f32x4 d = y4 - mean;
;                 const float var = reduce16((d.x * d.x + d.y * d.y) + (d.z * d.z + d.w * d.w)) * (1.f / 64.f);
;                 const float rstd = __builtin_amdgcn_rsqf(var + 64e-5f);
;                 const f32x4 o = ((d * rstd) * lg4 + lb4 + v4 * ct) * g4;
;                 u32x2 w; w.x = cvt_pk_bf16(o.x, o.y); w.y = cvt_pk_bf16(o.z, o.w);
;                 ypend = w;
	v_mfma_f32_16x16x32_bf16 v[102:105], v[60:63], v[24:27], v[102:105]
	ds_write2_b32 v191, v92, v93 offset1:68
	v_add_f32_e32 v93, v199, v94
	v_mul_f32_e32 v93, 0xbfb8aa3b, v93
	v_exp_f32_e32 v93, v93
	v_add_f32_e32 v92, v200, v97
	v_mul_f32_e32 v96, 0xbfb8aa3b, v96
	v_mul_f32_e32 v92, 0xbfb8aa3b, v92
	v_exp_f32_e32 v96, v96
	v_exp_f32_e32 v92, v92
	v_add_f32_e32 v93, 1.0, v93
	v_add_f32_e32 v94, v200, v98
	v_add_f32_e32 v95, 1.0, v95
	v_add_f32_e32 v97, v200, v99
	s_waitcnt vmcnt(1)
	v_mfma_f32_16x16x32_bf16 v[102:105], v[84:87], v[52:55], v[102:105]
	v_rcp_f32_e32 v93, v93
	v_mul_f32_e32 v94, 0xbfb8aa3b, v94
	v_rcp_f32_e32 v95, v95
	v_mul_f32_e32 v97, 0xbfb8aa3b, v97
	v_exp_f32_e32 v94, v94
	v_exp_f32_e32 v97, v97
	v_add_f32_e32 v96, 1.0, v96
	v_add_f32_e32 v92, 1.0, v92
	v_rcp_f32_e32 v96, v96
	v_rcp_f32_e32 v92, v92
	s_waitcnt vmcnt(0)
	v_mfma_f32_16x16x32_bf16 v[102:105], v[88:91], v[56:59], v[102:105]
	v_mul_f32_e32 v93, 0xbf60029d, v93
	v_mul_f32_e32 v95, 0xbf60029d, v95
	v_exp_f32_e32 v93, v93
	v_add_f32_e32 v94, 1.0, v94
	v_exp_f32_e32 v95, v95
	v_add_f32_e32 v97, 1.0, v97
	v_rcp_f32_e32 v94, v94
	v_rcp_f32_e32 v97, v97
	ds_write2_b32 v196, v96, v92 offset0:128 offset1:196
	ds_write2_b32 v197, v102, v103 offset1:68
	ds_write2_b32 v191, v93, v95 offset0:136 offset1:204
	ds_write2_b32 v198, v94, v97 offset0:8 offset1:76
	ds_write2_b32 v197, v104, v105 offset0:136 offset1:204
	v_add_u32_e32 v191, s41, v191
	v_add_u32_e32 v196, s41, v196
	v_add_u32_e32 v197, s41, v197
	v_add_u32_e32 v198, s41, v198
	s_sub_i32 s41, 0, s41
	s_mov_b32 s12, 16
	v_add_u32_e32 v28, s12, v140
	v_ashrrev_i32_e32 v29, 31, v28
	v_lshlrev_b64 v[28:29], 10, v[28:29]
	v_lshl_add_u64 v[28:29], v[28:29], 0, v[156:157]
	v_lshlrev_b64 v[28:29], 1, v[28:29]
	v_lshl_add_u64 v[30:31], s[2:3], 0, v[28:29]
	v_lshl_add_u64 v[32:33], s[4:5], 0, v[28:29]
	v_lshl_add_u64 v[28:29], s[6:7], 0, v[28:29]
	global_load_dwordx2 v[158:159], v[30:31], off
	global_load_dwordx2 v[160:161], v[32:33], off
	global_load_dwordx2 v[162:163], v[28:29], off
	s_mov_b32 s12, 32
	v_lshl_add_u64 v[28:29], v[154:155], 0, s[12:13]
	v_lshlrev_b64 v[28:29], 10, v[28:29]
	v_lshl_add_u64 v[88:89], v[148:149], 0, v[28:29]
	global_load_dwordx4 v[28:31], v[88:89], off
	global_load_dwordx4 v[40:43], v[88:89], off offset:64
	global_load_dwordx4 v[36:39], v[88:89], off offset:256
	global_load_dwordx4 v[48:51], v[88:89], off offset:320
	global_load_dwordx4 v[32:35], v[88:89], off offset:512
	global_load_dwordx4 v[44:47], v[88:89], off offset:576
	global_load_dwordx4 v[60:63], v[88:89], off offset:640
	global_load_dwordx4 v[84:87], v[88:89], off offset:704
	s_nop 0
	global_load_dwordx4 v[88:91], v[88:89], off offset:768
	s_waitcnt lgkmcnt(0)
	s_barrier
	s_mov_b32 s23, 0
.LW_hloop:
	s_cmp_eq_u32 s23, 0
	s_cbranch_scc1 .LW_h1
	ds_read_b128 v[100:103], v194 offset:52224
	ds_read_b128 v[104:107], v194 offset:52240
	ds_read_b128 v[108:111], v194 offset:52256
	ds_read_b128 v[112:115], v194 offset:52272
	s_waitcnt lgkmcnt(2)
	v_pk_add_f32 v[116:117], v[102:103], v[106:107]
	v_pk_add_f32 v[118:119], v[100:101], v[104:105]
	s_waitcnt lgkmcnt(0)
	v_pk_add_f32 v[120:121], v[110:111], v[114:115]
	v_pk_add_f32 v[122:123], v[108:109], v[112:113]
	ds_read_b128 v[100:103], v194 offset:52288
	ds_read_b128 v[104:107], v194 offset:52304
	ds_read_b128 v[108:111], v194 offset:52320
	ds_read_b128 v[112:115], v194 offset:52336
	v_pk_add_f32 v[116:117], v[116:117], v[120:121]
	v_pk_add_f32 v[118:119], v[118:119], v[122:123]
	s_waitcnt lgkmcnt(2)
	v_pk_add_f32 v[102:103], v[102:103], v[106:107]
	v_pk_add_f32 v[100:101], v[100:101], v[104:105]
	s_waitcnt lgkmcnt(0)
	v_pk_add_f32 v[104:105], v[110:111], v[114:115]
	v_pk_add_f32 v[106:107], v[108:109], v[112:113]
	v_pk_add_f32 v[102:103], v[102:103], v[104:105]
	v_pk_add_f32 v[100:101], v[100:101], v[106:107]
	v_pk_add_f32 v[104:105], v[118:119], v[116:117]
	v_pk_add_f32 v[100:101], v[100:101], v[102:103]
	v_mov_b32_e32 v102, v104
	v_mov_b32_e32 v103, v100
	v_mov_b32_e32 v106, v105
	v_mov_b32_e32 v107, v101
	v_pk_add_f32 v[102:103], v[102:103], v[106:107]
	s_nop 0
	v_add_f32_e32 v102, v102, v103
	s_nop 1
	v_add_f32_dpp v102, v102, v102 quad_perm:[1,0,3,2] row_mask:0xf bank_mask:0xf bound_ctrl:1
	s_nop 1
	v_add_f32_dpp v102, v102, v102 quad_perm:[2,3,0,1] row_mask:0xf bank_mask:0xf bound_ctrl:1
	s_nop 1
	v_add_f32_dpp v102, v102, v102 row_half_mirror row_mask:0xf bank_mask:0xf bound_ctrl:1
	s_nop 1
	v_add_f32_dpp v102, v102, v102 row_mirror row_mask:0xf bank_mask:0xf bound_ctrl:1
	v_fmamk_f32 v105, v102, 0xbc800000, v105
	v_fmac_f32_e32 v104, 0xbc800000, v102
	v_fmamk_f32 v101, v102, 0xbc800000, v101
	v_fmac_f32_e32 v100, 0xbc800000, v102
	v_pk_mul_f32 v[102:103], v[100:101], v[100:101]
	v_pk_mul_f32 v[106:107], v[104:105], v[104:105]
	s_nop 0
	v_pk_mov_b32 v[108:109], v[106:107], v[102:103] op_sel:[1,0]
	v_mov_b32_e32 v107, v103
	v_pk_add_f32 v[102:103], v[108:109], v[106:107]
	v_add_f32_e32 v106, v254, v255
	v_add_f32_e32 v102, v102, v103
	s_nop 1
	v_add_f32_dpp v102, v102, v102 quad_perm:[1,0,3,2] row_mask:0xf bank_mask:0xf bound_ctrl:1
	s_nop 1
	v_add_f32_dpp v102, v102, v102 quad_perm:[2,3,0,1] row_mask:0xf bank_mask:0xf bound_ctrl:1
	s_nop 1
	v_add_f32_dpp v102, v102, v102 row_half_mirror row_mask:0xf bank_mask:0xf bound_ctrl:1
	s_nop 1
	v_add_f32_dpp v102, v102, v102 row_mirror row_mask:0xf bank_mask:0xf bound_ctrl:1
	v_fmamk_f32 v102, v102, 0x3c800000, v195
	v_rsq_f32_e32 v102, v102
	s_nop 0
	v_pk_mul_f32 v[104:105], v[104:105], v[102:103] op_sel_hi:[1,0]
	v_pk_mul_f32 v[100:101], v[100:101], v[102:103] op_sel_hi:[1,0]
	v_pk_fma_f32 v[102:103], v[76:77], v[104:105], v[80:81]
	v_pk_fma_f32 v[100:101], v[78:79], v[100:101], v[82:83]
	v_pk_fma_f32 v[246:247], v[106:107], v[246:247], v[102:103] op_sel_hi:[0,1,1]
	v_pk_fma_f32 v[248:249], v[106:107], v[248:249], v[100:101] op_sel_hi:[0,1,1]
	v_pk_mul_f32 v[248:249], v[252:253], v[248:249]
	v_pk_mul_f32 v[246:247], v[250:251], v[246:247]
	s_nop 0
	v_cvt_pk_bf16_f32 v176, v246, v247
	v_cvt_pk_bf16_f32 v177, v248, v249
	v_add_u32_e32 v194, s44, v194
	s_sub_i32 s44, 0, s44

.LW_h2:
	v_mov_b32_e32 v246, v236
	v_mov_b32_e32 v247, v237
	v_mov_b32_e32 v248, v238
	v_mov_b32_e32 v249, v239
	v_mov_b32_e32 v250, v240
	v_mov_b32_e32 v251, v241
	v_mov_b32_e32 v252, v242
	v_mov_b32_e32 v253, v243
	v_mov_b32_e32 v254, v244
	v_mov_b32_e32 v255, v245
	v_mov_b32_e32 v236, v92
	v_mov_b32_e32 v237, v93
	v_mov_b32_e32 v238, v94
	v_mov_b32_e32 v239, v95
	v_mov_b32_e32 v240, v96
	v_mov_b32_e32 v241, v97
	v_mov_b32_e32 v242, v98
	v_mov_b32_e32 v243, v99
	v_mov_b32_e32 v244, v144
	v_mov_b32_e32 v245, v201
	v_add_u32_e32 v192, s42, v192
	v_add_u32_e32 v186, s43, v186
	v_add_u32_e32 v183, s40, v183
	v_add_u32_e32 v184, s40, v184
	v_add_u32_e32 v185, s40, v185
	s_sub_i32 s42, 0, s42
	s_sub_i32 s43, 0, s43
	s_sub_i32 s40, 0, s40
	s_waitcnt lgkmcnt(0)
	s_barrier
	s_cmpk_gt_u32 s23, 0xfd
	s_cbranch_scc1 .LW_h3
	s_waitcnt vmcnt(8)
	v_mfma_f32_16x16x32_bf16 v[92:95], v[28:31], v[4:7], 0
	s_waitcnt vmcnt(7)
	v_mfma_f32_16x16x32_bf16 v[92:95], v[40:43], v[16:19], v[92:95]
	s_waitcnt vmcnt(6)
	v_mfma_f32_16x16x32_bf16 v[96:99], v[36:39], v[8:11], 0
	s_waitcnt vmcnt(4)
	v_mfma_f32_16x16x32_bf16 v[102:105], v[32:35], v[0:3], 0
	s_nop 3
	v_add_f32_e32 v92, v199, v92
	v_add_f32_e32 v93, v199, v93
	v_mul_f32_e32 v92, 0xbfb8aa3b, v92
	v_mul_f32_e32 v93, 0xbfb8aa3b, v93
	v_exp_f32_e32 v92, v92
	v_exp_f32_e32 v93, v93
	v_mfma_f32_16x16x32_bf16 v[96:99], v[48:51], v[20:23], v[96:99]
	v_add_f32_e32 v95, v199, v95
	v_add_f32_e32 v92, 1.0, v92
	v_add_f32_e32 v93, 1.0, v93
	v_rcp_f32_e32 v92, v92
	v_rcp_f32_e32 v93, v93
	s_waitcnt vmcnt(3)
	v_mfma_f32_16x16x32_bf16 v[102:105], v[44:47], v[12:15], v[102:105]
	v_mul_f32_e32 v95, 0xbfb8aa3b, v95
	v_mul_f32_e32 v92, 0xbf60029d, v92
	v_mul_f32_e32 v93, 0xbf60029d, v93
	v_exp_f32_e32 v92, v92
	v_exp_f32_e32 v93, v93
	v_exp_f32_e32 v95, v95
	v_add_f32_e32 v96, v200, v96
	s_waitcnt vmcnt(2)
	v_mfma_f32_16x16x32_bf16 v[102:105], v[60:63], v[24:27], v[102:105]
	ds_write2_b32 v191, v92, v93 offset1:68
	v_add_f32_e32 v93, v199, v94
	v_mul_f32_e32 v93, 0xbfb8aa3b, v93
	v_exp_f32_e32 v93, v93
	v_add_f32_e32 v92, v200, v97
	v_mul_f32_e32 v96, 0xbfb8aa3b, v96
	v_mul_f32_e32 v92, 0xbfb8aa3b, v92
	v_exp_f32_e32 v96, v96
	v_exp_f32_e32 v92, v92
	v_add_f32_e32 v93, 1.0, v93
	v_add_f32_e32 v94, v200, v98
	v_add_f32_e32 v95, 1.0, v95
	v_add_f32_e32 v97, v200, v99
	s_waitcnt vmcnt(1)
	v_mfma_f32_16x16x32_bf16 v[102:105], v[84:87], v[52:55], v[102:105]
	v_rcp_f32_e32 v93, v93
	v_mul_f32_e32 v94, 0xbfb8aa3b, v94
	v_rcp_f32_e32 v95, v95
	v_mul_f32_e32 v97, 0xbfb8aa3b, v97
	v_exp_f32_e32 v94, v94
	v_exp_f32_e32 v97, v97
	v_add_f32_e32 v96, 1.0, v96
	v_add_f32_e32 v92, 1.0, v92
	v_rcp_f32_e32 v96, v96
	v_rcp_f32_e32 v92, v92
	s_waitcnt vmcnt(0)
	v_mfma_f32_16x16x32_bf16 v[102:105], v[88:91], v[56:59], v[102:105]
	v_mul_f32_e32 v93, 0xbf60029d, v93
	v_mul_f32_e32 v95, 0xbf60029d, v95
	v_exp_f32_e32 v93, v93
	v_add_f32_e32 v94, 1.0, v94
	v_exp_f32_e32 v95, v95
	v_add_f32_e32 v97, 1.0, v97
	v_rcp_f32_e32 v94, v94
	v_rcp_f32_e32 v97, v97
	ds_write2_b32 v196, v96, v92 offset0:128 offset1:196
	ds_write2_b32 v197, v102, v103 offset1:68
	ds_write2_b32 v191, v93, v95 offset0:136 offset1:204
	ds_write2_b32 v198, v94, v97 offset0:8 offset1:76
	ds_write2_b32 v197, v104, v105 offset0:136 offset1:204
	v_add_u32_e32 v191, s41, v191
	v_add_u32_e32 v196, s41, v196
	v_add_u32_e32 v197, s41, v197
	v_add_u32_e32 v198, s41, v198
	s_sub_i32 s41, 0, s41

; #define LAS __attribute__((address_space(3)))
; template <int CTRL> __device__ __forceinline__ float dppf(float v) { return __builtin_bit_cast(float, __builtin_amdgcn_update_dpp(0, __builtin_bit_cast(int, v), CTRL, 0xF, 0xF, true)); }
; __device__ __forceinline__ void phase_scan(const Args& a, LAS unsigned char* lds) {
;     ...
;             {
;                 const LAS float* obase = op + (lane & 15) * 20;
;                 const LAS float* vbase = vb + r0;
;                 f32x4 ow = *(const LAS f32x4*)(obase), oa = *(const LAS f32x4*)(obase + 4), ob = *(const LAS f32x4*)(obase + 8), ok = *(const LAS f32x4*)(obase + 12), orr = *(const LAS f32x4*)(obase + 16);
;                 f32x2 vv = *(const LAS f32x2*)(vbase);
; #pragma unroll 4
;                 for (int s = 0; s < TC; ++s) {
;                     const LAS float* o = obase + (s + 1) * 320;
;                     const f32x4 now = *(const LAS f32x4*)(o), noa = *(const LAS f32x4*)(o + 4), nob = *(const LAS f32x4*)(o + 8), nok = *(const LAS f32x4*)(o + 12), norr = *(const LAS f32x4*)(o + 16);
;                     const f32x2 nvv = *(const LAS f32x2*)(vbase + (s + 1) * 64);
;                     const f32x2 p = pkfma_b<1>(C3, HI2(oa), pkfma_b<0>(C2, HI2(oa), pkfma_b<1>(C1, LO2(oa), pkmul_b<0>(C0, LO2(oa)))));
;                     float sa0 = p.x, sa1 = p.y;
;                     sa0 = reduce16(sa0); asm volatile("" : "+v"(sa0)); sa1 = reduce16(sa1);
;                     const f32x2 sap = {sa0, sa1};
;                     C0 = pkfma_b<0>(vv, LO2(ok), pkfma_b<0>(sap, LO2(ob), pkmul_b<0>(C0, LO2(ow))));
;                     C1 = pkfma_b<1>(vv, LO2(ok), pkfma_b<1>(sap, LO2(ob), pkmul_b<1>(C1, LO2(ow))));
;                     C2 = pkfma_b<0>(vv, HI2(ok), pkfma_b<0>(sap, HI2(ob), pkmul_b<0>(C2, HI2(ow))));
;                     C3 = pkfma_b<1>(vv, HI2(ok), pkfma_b<1>(sap, HI2(ob), pkmul_b<1>(C3, HI2(ow))));
;                     const f32x2 q = pkfma_b<1>(C3, HI2(orr), pkfma_b<0>(C2, HI2(orr), pkfma_b<1>(C1, LO2(orr), pkmul_b<0>(C0, LO2(orr)))));
;                     float y0 = q.x, y1 = q.y;
;                     y0 += dppf<0xB1>(y0); y1 += dppf<0xB1>(y1);
;                     *(LAS f32x2*)(yb + ((s * 32 + (r0 >> 1)) * 8 + ((lane >> 1) & 7)) * 2) = (f32x2){y0, y1};
;                     ow = now; oa = noa; ob = nob; ok = nok; orr = norr; vv = nvv;
;                 }
.LW_rhead:
	s_setprio 3
	v_mov_b32_e32 v236, 0
	v_mov_b32_e32 v237, 0
	v_mov_b32_e32 v238, 0
	v_mov_b32_e32 v239, 0
	v_mov_b32_e32 v240, 0
	v_mov_b32_e32 v241, 0
	v_mov_b32_e32 v242, 0
	v_mov_b32_e32 v243, 0
	v_mov_b32_e32 v244, 0
	v_mov_b32_e32 v245, 0
	v_mov_b32_e32 v246, 0
	v_mov_b32_e32 v247, 0
	v_mov_b32_e32 v248, 0
	v_mov_b32_e32 v249, 0
	v_mov_b32_e32 v250, 0
	v_mov_b32_e32 v251, 0
	s_mov_b32 s42, 0x5500
	s_mov_b32 s43, 0x1100
	s_mov_b32 s44, 0x8000
	v_add_u32_e32 v176, 0x5500, v252
	v_add_u32_e32 v177, 0x1100, v253
	s_barrier
	s_barrier
	s_mov_b32 s23, 0
	ds_read_b128 v[100:103], v252 offset:16
	ds_read_b128 v[104:107], v252 offset:96
	ds_read_b128 v[108:111], v252
	ds_read_b128 v[112:115], v252 offset:80
	ds_read_b128 v[116:119], v252 offset:32
	ds_read_b128 v[120:123], v252 offset:112
	ds_read_b128 v[124:127], v252 offset:48
	ds_read_b128 v[128:131], v252 offset:128
	ds_read_b64 v[166:167], v253
	ds_read_b128 v[132:135], v252 offset:64
	ds_read_b128 v[136:139], v252 offset:144
	s_waitcnt lgkmcnt(0)
.LW_rloop:
	s_waitcnt lgkmcnt(10)
	v_pk_mul_f32 v[168:169], v[236:237], v[100:101] op_sel_hi:[1,0]
	v_pk_mul_f32 v[170:171], v[238:239], v[100:101] op_sel:[0,1]
	v_pk_fma_f32 v[168:169], v[240:241], v[102:103], v[168:169] op_sel_hi:[1,0,1]
	v_pk_fma_f32 v[170:171], v[242:243], v[102:103], v[170:171] op_sel:[0,1,0]
	v_pk_fma_f32 v[168:169], v[244:245], v[104:105], v[168:169] op_sel_hi:[1,0,1]
	v_pk_fma_f32 v[170:171], v[246:247], v[104:105], v[170:171] op_sel:[0,1,0]
	v_pk_fma_f32 v[168:169], v[248:249], v[106:107], v[168:169] op_sel_hi:[1,0,1]
	v_pk_fma_f32 v[170:171], v[250:251], v[106:107], v[170:171] op_sel:[0,1,0]
	ds_read_b128 v[100:103], v252 offset:1296
	ds_read_b128 v[104:107], v252 offset:1376
	v_pk_add_f32 v[168:169], v[168:169], v[170:171]
	s_waitcnt lgkmcnt(10)
	v_pk_mul_f32 v[236:237], v[236:237], v[108:109] op_sel_hi:[1,0]
	v_pk_mul_f32 v[238:239], v[238:239], v[108:109] op_sel:[0,1]
	v_pk_mul_f32 v[240:241], v[240:241], v[110:111] op_sel_hi:[1,0]
	v_pk_mul_f32 v[242:243], v[242:243], v[110:111] op_sel:[0,1]
	v_pk_mul_f32 v[244:245], v[244:245], v[112:113] op_sel_hi:[1,0]
	v_pk_mul_f32 v[246:247], v[246:247], v[112:113] op_sel:[0,1]
	v_pk_mul_f32 v[248:249], v[248:249], v[114:115] op_sel_hi:[1,0]
	v_pk_mul_f32 v[250:251], v[250:251], v[114:115] op_sel:[0,1]
	v_add_f32_dpp v168, v168, v168 quad_perm:[1,0,3,2] row_mask:0xf bank_mask:0xf bound_ctrl:1
	v_add_f32_dpp v169, v169, v169 quad_perm:[1,0,3,2] row_mask:0xf bank_mask:0xf bound_ctrl:1
	ds_read_b128 v[108:111], v252 offset:1280
	v_add_f32_dpp v168, v168, v168 quad_perm:[2,3,0,1] row_mask:0xf bank_mask:0xf bound_ctrl:1
	v_add_f32_dpp v169, v169, v169 quad_perm:[2,3,0,1] row_mask:0xf bank_mask:0xf bound_ctrl:1
	ds_read_b128 v[112:115], v252 offset:1360
	v_add_f32_dpp v168, v168, v168 row_half_mirror row_mask:0xf bank_mask:0xf bound_ctrl:1
	v_add_f32_dpp v169, v169, v169 row_half_mirror row_mask:0xf bank_mask:0xf bound_ctrl:1
	s_waitcnt lgkmcnt(10)
	v_pk_fma_f32 v[236:237], v[168:169], v[116:117], v[236:237] op_sel_hi:[1,0,1]
	v_pk_fma_f32 v[238:239], v[168:169], v[116:117], v[238:239] op_sel:[0,1,0]
	v_pk_fma_f32 v[240:241], v[168:169], v[118:119], v[240:241] op_sel_hi:[1,0,1]
	v_pk_fma_f32 v[242:243], v[168:169], v[118:119], v[242:243] op_sel:[0,1,0]
	v_pk_fma_f32 v[244:245], v[168:169], v[120:121], v[244:245] op_sel_hi:[1,0,1]
	v_pk_fma_f32 v[246:247], v[168:169], v[120:121], v[246:247] op_sel:[0,1,0]
	v_pk_fma_f32 v[248:249], v[168:169], v[122:123], v[248:249] op_sel_hi:[1,0,1]
	v_pk_fma_f32 v[250:251], v[168:169], v[122:123], v[250:251] op_sel:[0,1,0]
	ds_read_b128 v[116:119], v252 offset:1312
	ds_read_b128 v[120:123], v252 offset:1392
	s_waitcnt lgkmcnt(9)
	v_pk_fma_f32 v[236:237], v[166:167], v[124:125], v[236:237] op_sel_hi:[1,0,1]
	v_pk_fma_f32 v[238:239], v[166:167], v[124:125], v[238:239] op_sel:[0,1,0]
	v_pk_fma_f32 v[240:241], v[166:167], v[126:127], v[240:241] op_sel_hi:[1,0,1]
	v_pk_fma_f32 v[242:243], v[166:167], v[126:127], v[242:243] op_sel:[0,1,0]
	v_pk_fma_f32 v[244:245], v[166:167], v[128:129], v[244:245] op_sel_hi:[1,0,1]
	v_pk_fma_f32 v[246:247], v[166:167], v[128:129], v[246:247] op_sel:[0,1,0]
	v_pk_fma_f32 v[248:249], v[166:167], v[130:131], v[248:249] op_sel_hi:[1,0,1]
	v_pk_fma_f32 v[250:251], v[166:167], v[130:131], v[250:251] op_sel:[0,1,0]
	ds_read_b128 v[124:127], v252 offset:1328
	ds_read_b128 v[128:131], v252 offset:1408
	ds_read_b64 v[166:167], v253 offset:256
	s_waitcnt lgkmcnt(10)
	v_pk_mul_f32 v[172:173], v[236:237], v[132:133] op_sel_hi:[1,0]
	v_pk_mul_f32 v[174:175], v[238:239], v[132:133] op_sel:[0,1]
	v_pk_fma_f32 v[172:173], v[240:241], v[134:135], v[172:173] op_sel_hi:[1,0,1]
	v_pk_fma_f32 v[174:175], v[242:243], v[134:135], v[174:175] op_sel:[0,1,0]
	v_pk_fma_f32 v[172:173], v[244:245], v[136:137], v[172:173] op_sel_hi:[1,0,1]
	v_pk_fma_f32 v[174:175], v[246:247], v[136:137], v[174:175] op_sel:[0,1,0]
	v_pk_fma_f32 v[172:173], v[248:249], v[138:139], v[172:173] op_sel_hi:[1,0,1]
	v_pk_fma_f32 v[174:175], v[250:251], v[138:139], v[174:175] op_sel:[0,1,0]
	ds_read_b128 v[132:135], v252 offset:1344
	ds_read_b128 v[136:139], v252 offset:1424
	v_pk_add_f32 v[172:173], v[172:173], v[174:175]
	ds_write_b64 v254, v[172:173]
	s_waitcnt lgkmcnt(10)
	v_pk_mul_f32 v[168:169], v[236:237], v[100:101] op_sel_hi:[1,0]
	v_pk_mul_f32 v[170:171], v[238:239], v[100:101] op_sel:[0,1]
	v_pk_fma_f32 v[168:169], v[240:241], v[102:103], v[168:169] op_sel_hi:[1,0,1]
	v_pk_fma_f32 v[170:171], v[242:243], v[102:103], v[170:171] op_sel:[0,1,0]
	v_pk_fma_f32 v[168:169], v[244:245], v[104:105], v[168:169] op_sel_hi:[1,0,1]
	v_pk_fma_f32 v[170:171], v[246:247], v[104:105], v[170:171] op_sel:[0,1,0]
	v_pk_fma_f32 v[168:169], v[248:249], v[106:107], v[168:169] op_sel_hi:[1,0,1]
	v_pk_fma_f32 v[170:171], v[250:251], v[106:107], v[170:171] op_sel:[0,1,0]
	ds_read_b128 v[100:103], v252 offset:2576
	ds_read_b128 v[104:107], v252 offset:2656
	v_pk_add_f32 v[168:169], v[168:169], v[170:171]
	s_waitcnt lgkmcnt(10)
; #define LAS __attribute__((address_space(3)))
; template <int CTRL> __device__ __forceinline__ float dppf(float v) { return __builtin_bit_cast(float, __builtin_amdgcn_update_dpp(0, __builtin_bit_cast(int, v), CTRL, 0xF, 0xF, true)); }
; #define LO2(v) __builtin_shufflevector(v, v, 0, 1)
; #define HI2(v) __builtin_shufflevector(v, v, 2, 3)
; __device__ __forceinline__ void phase_scan(const Args& a, LAS unsigned char* lds) {
;     ...
;                 for (int s = 0; s < TC; ++s) {
;                     const LAS float* o = obase + (s + 1) * 320;
;                     const f32x4 now = *(const LAS f32x4*)(o), noa = *(const LAS f32x4*)(o + 4), nob = *(const LAS f32x4*)(o + 8), nok = *(const LAS f32x4*)(o + 12), norr = *(const LAS f32x4*)(o + 16);
;                     const f32x2 nvv = *(const LAS f32x2*)(vbase + (s + 1) * 64);
;                     const f32x2 p = pkfma_b<1>(C3, HI2(oa), pkfma_b<0>(C2, HI2(oa), pkfma_b<1>(C1, LO2(oa), pkmul_b<0>(C0, LO2(oa)))));
;                     float sa0 = p.x, sa1 = p.y;
;                     sa0 = reduce16(sa0); asm volatile("" : "+v"(sa0)); sa1 = reduce16(sa1);
;                     const f32x2 sap = {sa0, sa1};
;                     C0 = pkfma_b<0>(vv, LO2(ok), pkfma_b<0>(sap, LO2(ob), pkmul_b<0>(C0, LO2(ow))));
;                     C1 = pkfma_b<1>(vv, LO2(ok), pkfma_b<1>(sap, LO2(ob), pkmul_b<1>(C1, LO2(ow))));
;                     C2 = pkfma_b<0>(vv, HI2(ok), pkfma_b<0>(sap, HI2(ob), pkmul_b<0>(C2, HI2(ow))));
;                     C3 = pkfma_b<1>(vv, HI2(ok), pkfma_b<1>(sap, HI2(ob), pkmul_b<1>(C3, HI2(ow))));
;                     const f32x2 q = pkfma_b<1>(C3, HI2(orr), pkfma_b<0>(C2, HI2(orr), pkfma_b<1>(C1, LO2(orr), pkmul_b<0>(C0, LO2(orr)))));
;                     float y0 = q.x, y1 = q.y;
;                     y0 += dppf<0xB1>(y0); y1 += dppf<0xB1>(y1);
;                     *(LAS f32x2*)(yb + ((s * 32 + (r0 >> 1)) * 8 + ((lane >> 1) & 7)) * 2) = (f32x2){y0, y1};
;                     ow = now; oa = noa; ob = nob; ok = nok; orr = norr; vv = nvv;
;                 }
	v_pk_mul_f32 v[236:237], v[236:237], v[108:109] op_sel_hi:[1,0]
	v_pk_mul_f32 v[238:239], v[238:239], v[108:109] op_sel:[0,1]
	v_pk_mul_f32 v[240:241], v[240:241], v[110:111] op_sel_hi:[1,0]
	v_pk_mul_f32 v[242:243], v[242:243], v[110:111] op_sel:[0,1]
	v_pk_mul_f32 v[244:245], v[244:245], v[112:113] op_sel_hi:[1,0]
	v_pk_mul_f32 v[246:247], v[246:247], v[112:113] op_sel:[0,1]
	v_pk_mul_f32 v[248:249], v[248:249], v[114:115] op_sel_hi:[1,0]
	v_pk_mul_f32 v[250:251], v[250:251], v[114:115] op_sel:[0,1]
	v_add_f32_dpp v168, v168, v168 quad_perm:[1,0,3,2] row_mask:0xf bank_mask:0xf bound_ctrl:1
	v_add_f32_dpp v169, v169, v169 quad_perm:[1,0,3,2] row_mask:0xf bank_mask:0xf bound_ctrl:1
	ds_read_b128 v[108:111], v252 offset:2560
	v_add_f32_dpp v168, v168, v168 quad_perm:[2,3,0,1] row_mask:0xf bank_mask:0xf bound_ctrl:1
	v_add_f32_dpp v169, v169, v169 quad_perm:[2,3,0,1] row_mask:0xf bank_mask:0xf bound_ctrl:1
	ds_read_b128 v[112:115], v252 offset:2640
	v_add_f32_dpp v168, v168, v168 row_half_mirror row_mask:0xf bank_mask:0xf bound_ctrl:1
	v_add_f32_dpp v169, v169, v169 row_half_mirror row_mask:0xf bank_mask:0xf bound_ctrl:1
	s_waitcnt lgkmcnt(10)
	v_pk_fma_f32 v[236:237], v[168:169], v[116:117], v[236:237] op_sel_hi:[1,0,1]
	v_pk_fma_f32 v[238:239], v[168:169], v[116:117], v[238:239] op_sel:[0,1,0]
	v_pk_fma_f32 v[240:241], v[168:169], v[118:119], v[240:241] op_sel_hi:[1,0,1]
	v_pk_fma_f32 v[242:243], v[168:169], v[118:119], v[242:243] op_sel:[0,1,0]
	v_pk_fma_f32 v[244:245], v[168:169], v[120:121], v[244:245] op_sel_hi:[1,0,1]
	v_pk_fma_f32 v[246:247], v[168:169], v[120:121], v[246:247] op_sel:[0,1,0]
	v_pk_fma_f32 v[248:249], v[168:169], v[122:123], v[248:249] op_sel_hi:[1,0,1]
	v_pk_fma_f32 v[250:251], v[168:169], v[122:123], v[250:251] op_sel:[0,1,0]
	ds_read_b128 v[116:119], v252 offset:2592
	ds_read_b128 v[120:123], v252 offset:2672
	s_waitcnt lgkmcnt(9)
	v_pk_fma_f32 v[236:237], v[166:167], v[124:125], v[236:237] op_sel_hi:[1,0,1]
	v_pk_fma_f32 v[238:239], v[166:167], v[124:125], v[238:239] op_sel:[0,1,0]
	v_pk_fma_f32 v[240:241], v[166:167], v[126:127], v[240:241] op_sel_hi:[1,0,1]
	v_pk_fma_f32 v[242:243], v[166:167], v[126:127], v[242:243] op_sel:[0,1,0]
	v_pk_fma_f32 v[244:245], v[166:167], v[128:129], v[244:245] op_sel_hi:[1,0,1]
	v_pk_fma_f32 v[246:247], v[166:167], v[128:129], v[246:247] op_sel:[0,1,0]
	v_pk_fma_f32 v[248:249], v[166:167], v[130:131], v[248:249] op_sel_hi:[1,0,1]
	v_pk_fma_f32 v[250:251], v[166:167], v[130:131], v[250:251] op_sel:[0,1,0]
	ds_read_b128 v[124:127], v252 offset:2608
	ds_read_b128 v[128:131], v252 offset:2688
	ds_read_b64 v[166:167], v253 offset:512
	s_waitcnt lgkmcnt(10)
	v_pk_mul_f32 v[172:173], v[236:237], v[132:133] op_sel_hi:[1,0]
	v_pk_mul_f32 v[174:175], v[238:239], v[132:133] op_sel:[0,1]
	v_pk_fma_f32 v[172:173], v[240:241], v[134:135], v[172:173] op_sel_hi:[1,0,1]
	v_pk_fma_f32 v[174:175], v[242:243], v[134:135], v[174:175] op_sel:[0,1,0]
	v_pk_fma_f32 v[172:173], v[244:245], v[136:137], v[172:173] op_sel_hi:[1,0,1]
	v_pk_fma_f32 v[174:175], v[246:247], v[136:137], v[174:175] op_sel:[0,1,0]
	v_pk_fma_f32 v[172:173], v[248:249], v[138:139], v[172:173] op_sel_hi:[1,0,1]
	v_pk_fma_f32 v[174:175], v[250:251], v[138:139], v[174:175] op_sel:[0,1,0]
	ds_read_b128 v[132:135], v252 offset:2624
	ds_read_b128 v[136:139], v252 offset:2704
	v_pk_add_f32 v[172:173], v[172:173], v[174:175]
	ds_write_b64 v254, v[172:173] offset:2048
	s_waitcnt lgkmcnt(10)
	v_pk_mul_f32 v[168:169], v[236:237], v[100:101] op_sel_hi:[1,0]
	v_pk_mul_f32 v[170:171], v[238:239], v[100:101] op_sel:[0,1]
	v_pk_fma_f32 v[168:169], v[240:241], v[102:103], v[168:169] op_sel_hi:[1,0,1]
	v_pk_fma_f32 v[170:171], v[242:243], v[102:103], v[170:171] op_sel:[0,1,0]
	v_pk_fma_f32 v[168:169], v[244:245], v[104:105], v[168:169] op_sel_hi:[1,0,1]
	v_pk_fma_f32 v[170:171], v[246:247], v[104:105], v[170:171] op_sel:[0,1,0]
	v_pk_fma_f32 v[168:169], v[248:249], v[106:107], v[168:169] op_sel_hi:[1,0,1]
	v_pk_fma_f32 v[170:171], v[250:251], v[106:107], v[170:171] op_sel:[0,1,0]
	ds_read_b128 v[100:103], v252 offset:3856
	ds_read_b128 v[104:107], v252 offset:3936
	v_pk_add_f32 v[168:169], v[168:169], v[170:171]
	s_waitcnt lgkmcnt(10)
	v_pk_mul_f32 v[236:237], v[236:237], v[108:109] op_sel_hi:[1,0]
	v_pk_mul_f32 v[238:239], v[238:239], v[108:109] op_sel:[0,1]
	v_pk_mul_f32 v[240:241], v[240:241], v[110:111] op_sel_hi:[1,0]
	v_pk_mul_f32 v[242:243], v[242:243], v[110:111] op_sel:[0,1]
	v_pk_mul_f32 v[244:245], v[244:245], v[112:113] op_sel_hi:[1,0]
	v_pk_mul_f32 v[246:247], v[246:247], v[112:113] op_sel:[0,1]
	v_pk_mul_f32 v[248:249], v[248:249], v[114:115] op_sel_hi:[1,0]
	v_pk_mul_f32 v[250:251], v[250:251], v[114:115] op_sel:[0,1]
	v_add_f32_dpp v168, v168, v168 quad_perm:[1,0,3,2] row_mask:0xf bank_mask:0xf bound_ctrl:1
	v_add_f32_dpp v169, v169, v169 quad_perm:[1,0,3,2] row_mask:0xf bank_mask:0xf bound_ctrl:1
	ds_read_b128 v[108:111], v252 offset:3840
	v_add_f32_dpp v168, v168, v168 quad_perm:[2,3,0,1] row_mask:0xf bank_mask:0xf bound_ctrl:1
	v_add_f32_dpp v169, v169, v169 quad_perm:[2,3,0,1] row_mask:0xf bank_mask:0xf bound_ctrl:1
	ds_read_b128 v[112:115], v252 offset:3920
	v_add_f32_dpp v168, v168, v168 row_half_mirror row_mask:0xf bank_mask:0xf bound_ctrl:1
	v_add_f32_dpp v169, v169, v169 row_half_mirror row_mask:0xf bank_mask:0xf bound_ctrl:1
	s_waitcnt lgkmcnt(10)
; #define LAS __attribute__((address_space(3)))
; template <int CTRL> __device__ __forceinline__ float dppf(float v) { return __builtin_bit_cast(float, __builtin_amdgcn_update_dpp(0, __builtin_bit_cast(int, v), CTRL, 0xF, 0xF, true)); }
; #define LO2(v) __builtin_shufflevector(v, v, 0, 1)
; #define HI2(v) __builtin_shufflevector(v, v, 2, 3)
; __device__ __forceinline__ void phase_scan(const Args& a, LAS unsigned char* lds) {
;     ...
;                 for (int s = 0; s < TC; ++s) {
;                     const LAS float* o = obase + (s + 1) * 320;
;                     const f32x4 now = *(const LAS f32x4*)(o), noa = *(const LAS f32x4*)(o + 4), nob = *(const LAS f32x4*)(o + 8), nok = *(const LAS f32x4*)(o + 12), norr = *(const LAS f32x4*)(o + 16);
;                     const f32x2 nvv = *(const LAS f32x2*)(vbase + (s + 1) * 64);
;                     const f32x2 p = pkfma_b<1>(C3, HI2(oa), pkfma_b<0>(C2, HI2(oa), pkfma_b<1>(C1, LO2(oa), pkmul_b<0>(C0, LO2(oa)))));
;                     float sa0 = p.x, sa1 = p.y;
;                     sa0 = reduce16(sa0); asm volatile("" : "+v"(sa0)); sa1 = reduce16(sa1);
;                     const f32x2 sap = {sa0, sa1};
;                     C0 = pkfma_b<0>(vv, LO2(ok), pkfma_b<0>(sap, LO2(ob), pkmul_b<0>(C0, LO2(ow))));
;                     C1 = pkfma_b<1>(vv, LO2(ok), pkfma_b<1>(sap, LO2(ob), pkmul_b<1>(C1, LO2(ow))));
;                     C2 = pkfma_b<0>(vv, HI2(ok), pkfma_b<0>(sap, HI2(ob), pkmul_b<0>(C2, HI2(ow))));
;                     C3 = pkfma_b<1>(vv, HI2(ok), pkfma_b<1>(sap, HI2(ob), pkmul_b<1>(C3, HI2(ow))));
;                     const f32x2 q = pkfma_b<1>(C3, HI2(orr), pkfma_b<0>(C2, HI2(orr), pkfma_b<1>(C1, LO2(orr), pkmul_b<0>(C0, LO2(orr)))));
;                     float y0 = q.x, y1 = q.y;
;                     y0 += dppf<0xB1>(y0); y1 += dppf<0xB1>(y1);
;                     *(LAS f32x2*)(yb + ((s * 32 + (r0 >> 1)) * 8 + ((lane >> 1) & 7)) * 2) = (f32x2){y0, y1};
;                     ow = now; oa = noa; ob = nob; ok = nok; orr = norr; vv = nvv;
;                 }
	v_pk_fma_f32 v[236:237], v[168:169], v[116:117], v[236:237] op_sel_hi:[1,0,1]
	v_pk_fma_f32 v[238:239], v[168:169], v[116:117], v[238:239] op_sel:[0,1,0]
	v_pk_fma_f32 v[240:241], v[168:169], v[118:119], v[240:241] op_sel_hi:[1,0,1]
	v_pk_fma_f32 v[242:243], v[168:169], v[118:119], v[242:243] op_sel:[0,1,0]
	v_pk_fma_f32 v[244:245], v[168:169], v[120:121], v[244:245] op_sel_hi:[1,0,1]
	v_pk_fma_f32 v[246:247], v[168:169], v[120:121], v[246:247] op_sel:[0,1,0]
	v_pk_fma_f32 v[248:249], v[168:169], v[122:123], v[248:249] op_sel_hi:[1,0,1]
	v_pk_fma_f32 v[250:251], v[168:169], v[122:123], v[250:251] op_sel:[0,1,0]
	ds_read_b128 v[116:119], v252 offset:3872
	ds_read_b128 v[120:123], v252 offset:3952
	s_waitcnt lgkmcnt(9)
	v_pk_fma_f32 v[236:237], v[166:167], v[124:125], v[236:237] op_sel_hi:[1,0,1]
	v_pk_fma_f32 v[238:239], v[166:167], v[124:125], v[238:239] op_sel:[0,1,0]
	v_pk_fma_f32 v[240:241], v[166:167], v[126:127], v[240:241] op_sel_hi:[1,0,1]
	v_pk_fma_f32 v[242:243], v[166:167], v[126:127], v[242:243] op_sel:[0,1,0]
	v_pk_fma_f32 v[244:245], v[166:167], v[128:129], v[244:245] op_sel_hi:[1,0,1]
	v_pk_fma_f32 v[246:247], v[166:167], v[128:129], v[246:247] op_sel:[0,1,0]
	v_pk_fma_f32 v[248:249], v[166:167], v[130:131], v[248:249] op_sel_hi:[1,0,1]
	v_pk_fma_f32 v[250:251], v[166:167], v[130:131], v[250:251] op_sel:[0,1,0]
	ds_read_b128 v[124:127], v252 offset:3888
	ds_read_b128 v[128:131], v252 offset:3968
	ds_read_b64 v[166:167], v253 offset:768
	s_waitcnt lgkmcnt(10)
	v_pk_mul_f32 v[172:173], v[236:237], v[132:133] op_sel_hi:[1,0]
	v_pk_mul_f32 v[174:175], v[238:239], v[132:133] op_sel:[0,1]
	v_pk_fma_f32 v[172:173], v[240:241], v[134:135], v[172:173] op_sel_hi:[1,0,1]
	v_pk_fma_f32 v[174:175], v[242:243], v[134:135], v[174:175] op_sel:[0,1,0]
	v_pk_fma_f32 v[172:173], v[244:245], v[136:137], v[172:173] op_sel_hi:[1,0,1]
	v_pk_fma_f32 v[174:175], v[246:247], v[136:137], v[174:175] op_sel:[0,1,0]
	v_pk_fma_f32 v[172:173], v[248:249], v[138:139], v[172:173] op_sel_hi:[1,0,1]
	v_pk_fma_f32 v[174:175], v[250:251], v[138:139], v[174:175] op_sel:[0,1,0]
	ds_read_b128 v[132:135], v252 offset:3904
	ds_read_b128 v[136:139], v252 offset:3984
	v_pk_add_f32 v[172:173], v[172:173], v[174:175]
	ds_write_b64 v254, v[172:173] offset:4096
	s_waitcnt lgkmcnt(10)
	v_pk_mul_f32 v[168:169], v[236:237], v[100:101] op_sel_hi:[1,0]
	v_pk_mul_f32 v[170:171], v[238:239], v[100:101] op_sel:[0,1]
	v_pk_fma_f32 v[168:169], v[240:241], v[102:103], v[168:169] op_sel_hi:[1,0,1]
	v_pk_fma_f32 v[170:171], v[242:243], v[102:103], v[170:171] op_sel:[0,1,0]
	v_pk_fma_f32 v[168:169], v[244:245], v[104:105], v[168:169] op_sel_hi:[1,0,1]
	v_pk_fma_f32 v[170:171], v[246:247], v[104:105], v[170:171] op_sel:[0,1,0]
	v_pk_fma_f32 v[168:169], v[248:249], v[106:107], v[168:169] op_sel_hi:[1,0,1]
	v_pk_fma_f32 v[170:171], v[250:251], v[106:107], v[170:171] op_sel:[0,1,0]
	ds_read_b128 v[100:103], v252 offset:5136
	ds_read_b128 v[104:107], v252 offset:5216
	v_pk_add_f32 v[168:169], v[168:169], v[170:171]
	s_waitcnt lgkmcnt(10)
	v_pk_mul_f32 v[236:237], v[236:237], v[108:109] op_sel_hi:[1,0]
	v_pk_mul_f32 v[238:239], v[238:239], v[108:109] op_sel:[0,1]
	v_pk_mul_f32 v[240:241], v[240:241], v[110:111] op_sel_hi:[1,0]
	v_pk_mul_f32 v[242:243], v[242:243], v[110:111] op_sel:[0,1]
	v_pk_mul_f32 v[244:245], v[244:245], v[112:113] op_sel_hi:[1,0]
	v_pk_mul_f32 v[246:247], v[246:247], v[112:113] op_sel:[0,1]
	v_pk_mul_f32 v[248:249], v[248:249], v[114:115] op_sel_hi:[1,0]
	v_pk_mul_f32 v[250:251], v[250:251], v[114:115] op_sel:[0,1]
	v_add_f32_dpp v168, v168, v168 quad_perm:[1,0,3,2] row_mask:0xf bank_mask:0xf bound_ctrl:1
	v_add_f32_dpp v169, v169, v169 quad_perm:[1,0,3,2] row_mask:0xf bank_mask:0xf bound_ctrl:1
	ds_read_b128 v[108:111], v252 offset:5120
	v_add_f32_dpp v168, v168, v168 quad_perm:[2,3,0,1] row_mask:0xf bank_mask:0xf bound_ctrl:1
	v_add_f32_dpp v169, v169, v169 quad_perm:[2,3,0,1] row_mask:0xf bank_mask:0xf bound_ctrl:1
	ds_read_b128 v[112:115], v252 offset:5200
	v_add_f32_dpp v168, v168, v168 row_half_mirror row_mask:0xf bank_mask:0xf bound_ctrl:1
	v_add_f32_dpp v169, v169, v169 row_half_mirror row_mask:0xf bank_mask:0xf bound_ctrl:1
	s_waitcnt lgkmcnt(10)
	v_pk_fma_f32 v[236:237], v[168:169], v[116:117], v[236:237] op_sel_hi:[1,0,1]
	v_pk_fma_f32 v[238:239], v[168:169], v[116:117], v[238:239] op_sel:[0,1,0]
	v_pk_fma_f32 v[240:241], v[168:169], v[118:119], v[240:241] op_sel_hi:[1,0,1]
	v_pk_fma_f32 v[242:243], v[168:169], v[118:119], v[242:243] op_sel:[0,1,0]
	v_pk_fma_f32 v[244:245], v[168:169], v[120:121], v[244:245] op_sel_hi:[1,0,1]
	v_pk_fma_f32 v[246:247], v[168:169], v[120:121], v[246:247] op_sel:[0,1,0]
	v_pk_fma_f32 v[248:249], v[168:169], v[122:123], v[248:249] op_sel_hi:[1,0,1]
	v_pk_fma_f32 v[250:251], v[168:169], v[122:123], v[250:251] op_sel:[0,1,0]
	ds_read_b128 v[116:119], v252 offset:5152
	ds_read_b128 v[120:123], v252 offset:5232
	s_waitcnt lgkmcnt(9)
	v_pk_fma_f32 v[236:237], v[166:167], v[124:125], v[236:237] op_sel_hi:[1,0,1]
	v_pk_fma_f32 v[238:239], v[166:167], v[124:125], v[238:239] op_sel:[0,1,0]
	v_pk_fma_f32 v[240:241], v[166:167], v[126:127], v[240:241] op_sel_hi:[1,0,1]
	v_pk_fma_f32 v[242:243], v[166:167], v[126:127], v[242:243] op_sel:[0,1,0]
	v_pk_fma_f32 v[244:245], v[166:167], v[128:129], v[244:245] op_sel_hi:[1,0,1]
	v_pk_fma_f32 v[246:247], v[166:167], v[128:129], v[246:247] op_sel:[0,1,0]
	v_pk_fma_f32 v[248:249], v[166:167], v[130:131], v[248:249] op_sel_hi:[1,0,1]
	v_pk_fma_f32 v[250:251], v[166:167], v[130:131], v[250:251] op_sel:[0,1,0]
	ds_read_b128 v[124:127], v252 offset:5168
	ds_read_b128 v[128:131], v252 offset:5248
	ds_read_b64 v[166:167], v253 offset:1024
	s_waitcnt lgkmcnt(10)
; #define LAS __attribute__((address_space(3)))
; template <int CTRL> __device__ __forceinline__ float dppf(float v) { return __builtin_bit_cast(float, __builtin_amdgcn_update_dpp(0, __builtin_bit_cast(int, v), CTRL, 0xF, 0xF, true)); }
; #define LO2(v) __builtin_shufflevector(v, v, 0, 1)
; #define HI2(v) __builtin_shufflevector(v, v, 2, 3)
; __device__ __forceinline__ void phase_scan(const Args& a, LAS unsigned char* lds) {
;     ...
;                 for (int s = 0; s < TC; ++s) {
;                     const LAS float* o = obase + (s + 1) * 320;
;                     const f32x4 now = *(const LAS f32x4*)(o), noa = *(const LAS f32x4*)(o + 4), nob = *(const LAS f32x4*)(o + 8), nok = *(const LAS f32x4*)(o + 12), norr = *(const LAS f32x4*)(o + 16);
;                     const f32x2 nvv = *(const LAS f32x2*)(vbase + (s + 1) * 64);
;                     const f32x2 p = pkfma_b<1>(C3, HI2(oa), pkfma_b<0>(C2, HI2(oa), pkfma_b<1>(C1, LO2(oa), pkmul_b<0>(C0, LO2(oa)))));
;                     float sa0 = p.x, sa1 = p.y;
;                     sa0 = reduce16(sa0); asm volatile("" : "+v"(sa0)); sa1 = reduce16(sa1);
;                     const f32x2 sap = {sa0, sa1};
;                     C0 = pkfma_b<0>(vv, LO2(ok), pkfma_b<0>(sap, LO2(ob), pkmul_b<0>(C0, LO2(ow))));
;                     C1 = pkfma_b<1>(vv, LO2(ok), pkfma_b<1>(sap, LO2(ob), pkmul_b<1>(C1, LO2(ow))));
;                     C2 = pkfma_b<0>(vv, HI2(ok), pkfma_b<0>(sap, HI2(ob), pkmul_b<0>(C2, HI2(ow))));
;                     C3 = pkfma_b<1>(vv, HI2(ok), pkfma_b<1>(sap, HI2(ob), pkmul_b<1>(C3, HI2(ow))));
;                     const f32x2 q = pkfma_b<1>(C3, HI2(orr), pkfma_b<0>(C2, HI2(orr), pkfma_b<1>(C1, LO2(orr), pkmul_b<0>(C0, LO2(orr)))));
;                     float y0 = q.x, y1 = q.y;
;                     y0 += dppf<0xB1>(y0); y1 += dppf<0xB1>(y1);
;                     *(LAS f32x2*)(yb + ((s * 32 + (r0 >> 1)) * 8 + ((lane >> 1) & 7)) * 2) = (f32x2){y0, y1};
;                     ow = now; oa = noa; ob = nob; ok = nok; orr = norr; vv = nvv;
;                 }
	v_pk_mul_f32 v[172:173], v[236:237], v[132:133] op_sel_hi:[1,0]
	v_pk_mul_f32 v[174:175], v[238:239], v[132:133] op_sel:[0,1]
	v_pk_fma_f32 v[172:173], v[240:241], v[134:135], v[172:173] op_sel_hi:[1,0,1]
	v_pk_fma_f32 v[174:175], v[242:243], v[134:135], v[174:175] op_sel:[0,1,0]
	v_pk_fma_f32 v[172:173], v[244:245], v[136:137], v[172:173] op_sel_hi:[1,0,1]
	v_pk_fma_f32 v[174:175], v[246:247], v[136:137], v[174:175] op_sel:[0,1,0]
	v_pk_fma_f32 v[172:173], v[248:249], v[138:139], v[172:173] op_sel_hi:[1,0,1]
	v_pk_fma_f32 v[174:175], v[250:251], v[138:139], v[174:175] op_sel:[0,1,0]
	ds_read_b128 v[132:135], v252 offset:5184
	ds_read_b128 v[136:139], v252 offset:5264
	v_pk_add_f32 v[172:173], v[172:173], v[174:175]
	ds_write_b64 v254, v[172:173] offset:6144
	s_waitcnt lgkmcnt(10)
	v_pk_mul_f32 v[168:169], v[236:237], v[100:101] op_sel_hi:[1,0]
	v_pk_mul_f32 v[170:171], v[238:239], v[100:101] op_sel:[0,1]
	v_pk_fma_f32 v[168:169], v[240:241], v[102:103], v[168:169] op_sel_hi:[1,0,1]
	v_pk_fma_f32 v[170:171], v[242:243], v[102:103], v[170:171] op_sel:[0,1,0]
	v_pk_fma_f32 v[168:169], v[244:245], v[104:105], v[168:169] op_sel_hi:[1,0,1]
	v_pk_fma_f32 v[170:171], v[246:247], v[104:105], v[170:171] op_sel:[0,1,0]
	v_pk_fma_f32 v[168:169], v[248:249], v[106:107], v[168:169] op_sel_hi:[1,0,1]
	v_pk_fma_f32 v[170:171], v[250:251], v[106:107], v[170:171] op_sel:[0,1,0]
	ds_read_b128 v[100:103], v252 offset:6416
	ds_read_b128 v[104:107], v252 offset:6496
	v_pk_add_f32 v[168:169], v[168:169], v[170:171]
	s_waitcnt lgkmcnt(10)
	v_pk_mul_f32 v[236:237], v[236:237], v[108:109] op_sel_hi:[1,0]
	v_pk_mul_f32 v[238:239], v[238:239], v[108:109] op_sel:[0,1]
	v_pk_mul_f32 v[240:241], v[240:241], v[110:111] op_sel_hi:[1,0]
	v_pk_mul_f32 v[242:243], v[242:243], v[110:111] op_sel:[0,1]
	v_pk_mul_f32 v[244:245], v[244:245], v[112:113] op_sel_hi:[1,0]
	v_pk_mul_f32 v[246:247], v[246:247], v[112:113] op_sel:[0,1]
	v_pk_mul_f32 v[248:249], v[248:249], v[114:115] op_sel_hi:[1,0]
	v_pk_mul_f32 v[250:251], v[250:251], v[114:115] op_sel:[0,1]
	v_add_f32_dpp v168, v168, v168 quad_perm:[1,0,3,2] row_mask:0xf bank_mask:0xf bound_ctrl:1
	v_add_f32_dpp v169, v169, v169 quad_perm:[1,0,3,2] row_mask:0xf bank_mask:0xf bound_ctrl:1
	ds_read_b128 v[108:111], v252 offset:6400
	v_add_f32_dpp v168, v168, v168 quad_perm:[2,3,0,1] row_mask:0xf bank_mask:0xf bound_ctrl:1
	v_add_f32_dpp v169, v169, v169 quad_perm:[2,3,0,1] row_mask:0xf bank_mask:0xf bound_ctrl:1
	ds_read_b128 v[112:115], v252 offset:6480
	v_add_f32_dpp v168, v168, v168 row_half_mirror row_mask:0xf bank_mask:0xf bound_ctrl:1
	v_add_f32_dpp v169, v169, v169 row_half_mirror row_mask:0xf bank_mask:0xf bound_ctrl:1
	s_waitcnt lgkmcnt(10)
	v_pk_fma_f32 v[236:237], v[168:169], v[116:117], v[236:237] op_sel_hi:[1,0,1]
	v_pk_fma_f32 v[238:239], v[168:169], v[116:117], v[238:239] op_sel:[0,1,0]
	v_pk_fma_f32 v[240:241], v[168:169], v[118:119], v[240:241] op_sel_hi:[1,0,1]
	v_pk_fma_f32 v[242:243], v[168:169], v[118:119], v[242:243] op_sel:[0,1,0]
	v_pk_fma_f32 v[244:245], v[168:169], v[120:121], v[244:245] op_sel_hi:[1,0,1]
	v_pk_fma_f32 v[246:247], v[168:169], v[120:121], v[246:247] op_sel:[0,1,0]
	v_pk_fma_f32 v[248:249], v[168:169], v[122:123], v[248:249] op_sel_hi:[1,0,1]
	v_pk_fma_f32 v[250:251], v[168:169], v[122:123], v[250:251] op_sel:[0,1,0]
	ds_read_b128 v[116:119], v252 offset:6432
	ds_read_b128 v[120:123], v252 offset:6512
	s_waitcnt lgkmcnt(9)
	v_pk_fma_f32 v[236:237], v[166:167], v[124:125], v[236:237] op_sel_hi:[1,0,1]
	v_pk_fma_f32 v[238:239], v[166:167], v[124:125], v[238:239] op_sel:[0,1,0]
	v_pk_fma_f32 v[240:241], v[166:167], v[126:127], v[240:241] op_sel_hi:[1,0,1]
	v_pk_fma_f32 v[242:243], v[166:167], v[126:127], v[242:243] op_sel:[0,1,0]
	v_pk_fma_f32 v[244:245], v[166:167], v[128:129], v[244:245] op_sel_hi:[1,0,1]
	v_pk_fma_f32 v[246:247], v[166:167], v[128:129], v[246:247] op_sel:[0,1,0]
	v_pk_fma_f32 v[248:249], v[166:167], v[130:131], v[248:249] op_sel_hi:[1,0,1]
	v_pk_fma_f32 v[250:251], v[166:167], v[130:131], v[250:251] op_sel:[0,1,0]
	ds_read_b128 v[124:127], v252 offset:6448
	ds_read_b128 v[128:131], v252 offset:6528
	ds_read_b64 v[166:167], v253 offset:1280
	s_waitcnt lgkmcnt(10)
	v_pk_mul_f32 v[172:173], v[236:237], v[132:133] op_sel_hi:[1,0]
	v_pk_mul_f32 v[174:175], v[238:239], v[132:133] op_sel:[0,1]
	v_pk_fma_f32 v[172:173], v[240:241], v[134:135], v[172:173] op_sel_hi:[1,0,1]
	v_pk_fma_f32 v[174:175], v[242:243], v[134:135], v[174:175] op_sel:[0,1,0]
	v_pk_fma_f32 v[172:173], v[244:245], v[136:137], v[172:173] op_sel_hi:[1,0,1]
	v_pk_fma_f32 v[174:175], v[246:247], v[136:137], v[174:175] op_sel:[0,1,0]
	v_pk_fma_f32 v[172:173], v[248:249], v[138:139], v[172:173] op_sel_hi:[1,0,1]
	v_pk_fma_f32 v[174:175], v[250:251], v[138:139], v[174:175] op_sel:[0,1,0]
	ds_read_b128 v[132:135], v252 offset:6464
	ds_read_b128 v[136:139], v252 offset:6544
	v_pk_add_f32 v[172:173], v[172:173], v[174:175]
	ds_write_b64 v254, v[172:173] offset:8192
	s_waitcnt lgkmcnt(10)
	v_pk_mul_f32 v[168:169], v[236:237], v[100:101] op_sel_hi:[1,0]
	v_pk_mul_f32 v[170:171], v[238:239], v[100:101] op_sel:[0,1]
	v_pk_fma_f32 v[168:169], v[240:241], v[102:103], v[168:169] op_sel_hi:[1,0,1]
	v_pk_fma_f32 v[170:171], v[242:243], v[102:103], v[170:171] op_sel:[0,1,0]
	v_pk_fma_f32 v[168:169], v[244:245], v[104:105], v[168:169] op_sel_hi:[1,0,1]
	v_pk_fma_f32 v[170:171], v[246:247], v[104:105], v[170:171] op_sel:[0,1,0]
	v_pk_fma_f32 v[168:169], v[248:249], v[106:107], v[168:169] op_sel_hi:[1,0,1]
	v_pk_fma_f32 v[170:171], v[250:251], v[106:107], v[170:171] op_sel:[0,1,0]
	ds_read_b128 v[100:103], v252 offset:7696
	ds_read_b128 v[104:107], v252 offset:7776
	v_pk_add_f32 v[168:169], v[168:169], v[170:171]
	s_waitcnt lgkmcnt(10)
; #define LAS __attribute__((address_space(3)))
; template <int CTRL> __device__ __forceinline__ float dppf(float v) { return __builtin_bit_cast(float, __builtin_amdgcn_update_dpp(0, __builtin_bit_cast(int, v), CTRL, 0xF, 0xF, true)); }
; #define LO2(v) __builtin_shufflevector(v, v, 0, 1)
; #define HI2(v) __builtin_shufflevector(v, v, 2, 3)
; __device__ __forceinline__ void phase_scan(const Args& a, LAS unsigned char* lds) {
;     ...
;                 for (int s = 0; s < TC; ++s) {
;                     const LAS float* o = obase + (s + 1) * 320;
;                     const f32x4 now = *(const LAS f32x4*)(o), noa = *(const LAS f32x4*)(o + 4), nob = *(const LAS f32x4*)(o + 8), nok = *(const LAS f32x4*)(o + 12), norr = *(const LAS f32x4*)(o + 16);
;                     const f32x2 nvv = *(const LAS f32x2*)(vbase + (s + 1) * 64);
;                     const f32x2 p = pkfma_b<1>(C3, HI2(oa), pkfma_b<0>(C2, HI2(oa), pkfma_b<1>(C1, LO2(oa), pkmul_b<0>(C0, LO2(oa)))));
;                     float sa0 = p.x, sa1 = p.y;
;                     sa0 = reduce16(sa0); asm volatile("" : "+v"(sa0)); sa1 = reduce16(sa1);
;                     const f32x2 sap = {sa0, sa1};
;                     C0 = pkfma_b<0>(vv, LO2(ok), pkfma_b<0>(sap, LO2(ob), pkmul_b<0>(C0, LO2(ow))));
;                     C1 = pkfma_b<1>(vv, LO2(ok), pkfma_b<1>(sap, LO2(ob), pkmul_b<1>(C1, LO2(ow))));
;                     C2 = pkfma_b<0>(vv, HI2(ok), pkfma_b<0>(sap, HI2(ob), pkmul_b<0>(C2, HI2(ow))));
;                     C3 = pkfma_b<1>(vv, HI2(ok), pkfma_b<1>(sap, HI2(ob), pkmul_b<1>(C3, HI2(ow))));
;                     const f32x2 q = pkfma_b<1>(C3, HI2(orr), pkfma_b<0>(C2, HI2(orr), pkfma_b<1>(C1, LO2(orr), pkmul_b<0>(C0, LO2(orr)))));
;                     float y0 = q.x, y1 = q.y;
;                     y0 += dppf<0xB1>(y0); y1 += dppf<0xB1>(y1);
;                     *(LAS f32x2*)(yb + ((s * 32 + (r0 >> 1)) * 8 + ((lane >> 1) & 7)) * 2) = (f32x2){y0, y1};
;                     ow = now; oa = noa; ob = nob; ok = nok; orr = norr; vv = nvv;
;                 }
	v_pk_mul_f32 v[236:237], v[236:237], v[108:109] op_sel_hi:[1,0]
	v_pk_mul_f32 v[238:239], v[238:239], v[108:109] op_sel:[0,1]
	v_pk_mul_f32 v[240:241], v[240:241], v[110:111] op_sel_hi:[1,0]
	v_pk_mul_f32 v[242:243], v[242:243], v[110:111] op_sel:[0,1]
	v_pk_mul_f32 v[244:245], v[244:245], v[112:113] op_sel_hi:[1,0]
	v_pk_mul_f32 v[246:247], v[246:247], v[112:113] op_sel:[0,1]
	v_pk_mul_f32 v[248:249], v[248:249], v[114:115] op_sel_hi:[1,0]
	v_pk_mul_f32 v[250:251], v[250:251], v[114:115] op_sel:[0,1]
	v_add_f32_dpp v168, v168, v168 quad_perm:[1,0,3,2] row_mask:0xf bank_mask:0xf bound_ctrl:1
	v_add_f32_dpp v169, v169, v169 quad_perm:[1,0,3,2] row_mask:0xf bank_mask:0xf bound_ctrl:1
	ds_read_b128 v[108:111], v252 offset:7680
	v_add_f32_dpp v168, v168, v168 quad_perm:[2,3,0,1] row_mask:0xf bank_mask:0xf bound_ctrl:1
	v_add_f32_dpp v169, v169, v169 quad_perm:[2,3,0,1] row_mask:0xf bank_mask:0xf bound_ctrl:1
	ds_read_b128 v[112:115], v252 offset:7760
	v_add_f32_dpp v168, v168, v168 row_half_mirror row_mask:0xf bank_mask:0xf bound_ctrl:1
	v_add_f32_dpp v169, v169, v169 row_half_mirror row_mask:0xf bank_mask:0xf bound_ctrl:1
	s_waitcnt lgkmcnt(10)
	v_pk_fma_f32 v[236:237], v[168:169], v[116:117], v[236:237] op_sel_hi:[1,0,1]
	v_pk_fma_f32 v[238:239], v[168:169], v[116:117], v[238:239] op_sel:[0,1,0]
	v_pk_fma_f32 v[240:241], v[168:169], v[118:119], v[240:241] op_sel_hi:[1,0,1]
	v_pk_fma_f32 v[242:243], v[168:169], v[118:119], v[242:243] op_sel:[0,1,0]
	v_pk_fma_f32 v[244:245], v[168:169], v[120:121], v[244:245] op_sel_hi:[1,0,1]
	v_pk_fma_f32 v[246:247], v[168:169], v[120:121], v[246:247] op_sel:[0,1,0]
	v_pk_fma_f32 v[248:249], v[168:169], v[122:123], v[248:249] op_sel_hi:[1,0,1]
	v_pk_fma_f32 v[250:251], v[168:169], v[122:123], v[250:251] op_sel:[0,1,0]
	ds_read_b128 v[116:119], v252 offset:7712
	ds_read_b128 v[120:123], v252 offset:7792
	s_waitcnt lgkmcnt(9)
	v_pk_fma_f32 v[236:237], v[166:167], v[124:125], v[236:237] op_sel_hi:[1,0,1]
	v_pk_fma_f32 v[238:239], v[166:167], v[124:125], v[238:239] op_sel:[0,1,0]
	v_pk_fma_f32 v[240:241], v[166:167], v[126:127], v[240:241] op_sel_hi:[1,0,1]
	v_pk_fma_f32 v[242:243], v[166:167], v[126:127], v[242:243] op_sel:[0,1,0]
	v_pk_fma_f32 v[244:245], v[166:167], v[128:129], v[244:245] op_sel_hi:[1,0,1]
	v_pk_fma_f32 v[246:247], v[166:167], v[128:129], v[246:247] op_sel:[0,1,0]
	v_pk_fma_f32 v[248:249], v[166:167], v[130:131], v[248:249] op_sel_hi:[1,0,1]
	v_pk_fma_f32 v[250:251], v[166:167], v[130:131], v[250:251] op_sel:[0,1,0]
	ds_read_b128 v[124:127], v252 offset:7728
	ds_read_b128 v[128:131], v252 offset:7808
	ds_read_b64 v[166:167], v253 offset:1536
	s_waitcnt lgkmcnt(10)
	v_pk_mul_f32 v[172:173], v[236:237], v[132:133] op_sel_hi:[1,0]
	v_pk_mul_f32 v[174:175], v[238:239], v[132:133] op_sel:[0,1]
	v_pk_fma_f32 v[172:173], v[240:241], v[134:135], v[172:173] op_sel_hi:[1,0,1]
	v_pk_fma_f32 v[174:175], v[242:243], v[134:135], v[174:175] op_sel:[0,1,0]
	v_pk_fma_f32 v[172:173], v[244:245], v[136:137], v[172:173] op_sel_hi:[1,0,1]
	v_pk_fma_f32 v[174:175], v[246:247], v[136:137], v[174:175] op_sel:[0,1,0]
	v_pk_fma_f32 v[172:173], v[248:249], v[138:139], v[172:173] op_sel_hi:[1,0,1]
	v_pk_fma_f32 v[174:175], v[250:251], v[138:139], v[174:175] op_sel:[0,1,0]
	ds_read_b128 v[132:135], v252 offset:7744
	ds_read_b128 v[136:139], v252 offset:7824
	v_pk_add_f32 v[172:173], v[172:173], v[174:175]
	ds_write_b64 v254, v[172:173] offset:10240
	s_waitcnt lgkmcnt(10)
	v_pk_mul_f32 v[168:169], v[236:237], v[100:101] op_sel_hi:[1,0]
	v_pk_mul_f32 v[170:171], v[238:239], v[100:101] op_sel:[0,1]
	v_pk_fma_f32 v[168:169], v[240:241], v[102:103], v[168:169] op_sel_hi:[1,0,1]
	v_pk_fma_f32 v[170:171], v[242:243], v[102:103], v[170:171] op_sel:[0,1,0]
	v_pk_fma_f32 v[168:169], v[244:245], v[104:105], v[168:169] op_sel_hi:[1,0,1]
	v_pk_fma_f32 v[170:171], v[246:247], v[104:105], v[170:171] op_sel:[0,1,0]
	v_pk_fma_f32 v[168:169], v[248:249], v[106:107], v[168:169] op_sel_hi:[1,0,1]
	v_pk_fma_f32 v[170:171], v[250:251], v[106:107], v[170:171] op_sel:[0,1,0]
	ds_read_b128 v[100:103], v252 offset:8976
	ds_read_b128 v[104:107], v252 offset:9056
	v_pk_add_f32 v[168:169], v[168:169], v[170:171]
	s_waitcnt lgkmcnt(10)
	v_pk_mul_f32 v[236:237], v[236:237], v[108:109] op_sel_hi:[1,0]
	v_pk_mul_f32 v[238:239], v[238:239], v[108:109] op_sel:[0,1]
	v_pk_mul_f32 v[240:241], v[240:241], v[110:111] op_sel_hi:[1,0]
	v_pk_mul_f32 v[242:243], v[242:243], v[110:111] op_sel:[0,1]
	v_pk_mul_f32 v[244:245], v[244:245], v[112:113] op_sel_hi:[1,0]
	v_pk_mul_f32 v[246:247], v[246:247], v[112:113] op_sel:[0,1]
	v_pk_mul_f32 v[248:249], v[248:249], v[114:115] op_sel_hi:[1,0]
	v_pk_mul_f32 v[250:251], v[250:251], v[114:115] op_sel:[0,1]
	v_add_f32_dpp v168, v168, v168 quad_perm:[1,0,3,2] row_mask:0xf bank_mask:0xf bound_ctrl:1
	v_add_f32_dpp v169, v169, v169 quad_perm:[1,0,3,2] row_mask:0xf bank_mask:0xf bound_ctrl:1
	ds_read_b128 v[108:111], v252 offset:8960
	v_add_f32_dpp v168, v168, v168 quad_perm:[2,3,0,1] row_mask:0xf bank_mask:0xf bound_ctrl:1
	v_add_f32_dpp v169, v169, v169 quad_perm:[2,3,0,1] row_mask:0xf bank_mask:0xf bound_ctrl:1
	ds_read_b128 v[112:115], v252 offset:9040
	v_add_f32_dpp v168, v168, v168 row_half_mirror row_mask:0xf bank_mask:0xf bound_ctrl:1
	v_add_f32_dpp v169, v169, v169 row_half_mirror row_mask:0xf bank_mask:0xf bound_ctrl:1
	s_waitcnt lgkmcnt(10)
; #define LAS __attribute__((address_space(3)))
; template <int CTRL> __device__ __forceinline__ float dppf(float v) { return __builtin_bit_cast(float, __builtin_amdgcn_update_dpp(0, __builtin_bit_cast(int, v), CTRL, 0xF, 0xF, true)); }
; #define LO2(v) __builtin_shufflevector(v, v, 0, 1)
; #define HI2(v) __builtin_shufflevector(v, v, 2, 3)
; __device__ __forceinline__ void phase_scan(const Args& a, LAS unsigned char* lds) {
;     ...
;                 for (int s = 0; s < TC; ++s) {
;                     const LAS float* o = obase + (s + 1) * 320;
;                     const f32x4 now = *(const LAS f32x4*)(o), noa = *(const LAS f32x4*)(o + 4), nob = *(const LAS f32x4*)(o + 8), nok = *(const LAS f32x4*)(o + 12), norr = *(const LAS f32x4*)(o + 16);
;                     const f32x2 nvv = *(const LAS f32x2*)(vbase + (s + 1) * 64);
;                     const f32x2 p = pkfma_b<1>(C3, HI2(oa), pkfma_b<0>(C2, HI2(oa), pkfma_b<1>(C1, LO2(oa), pkmul_b<0>(C0, LO2(oa)))));
;                     float sa0 = p.x, sa1 = p.y;
;                     sa0 = reduce16(sa0); asm volatile("" : "+v"(sa0)); sa1 = reduce16(sa1);
;                     const f32x2 sap = {sa0, sa1};
;                     C0 = pkfma_b<0>(vv, LO2(ok), pkfma_b<0>(sap, LO2(ob), pkmul_b<0>(C0, LO2(ow))));
;                     C1 = pkfma_b<1>(vv, LO2(ok), pkfma_b<1>(sap, LO2(ob), pkmul_b<1>(C1, LO2(ow))));
;                     C2 = pkfma_b<0>(vv, HI2(ok), pkfma_b<0>(sap, HI2(ob), pkmul_b<0>(C2, HI2(ow))));
;                     C3 = pkfma_b<1>(vv, HI2(ok), pkfma_b<1>(sap, HI2(ob), pkmul_b<1>(C3, HI2(ow))));
;                     const f32x2 q = pkfma_b<1>(C3, HI2(orr), pkfma_b<0>(C2, HI2(orr), pkfma_b<1>(C1, LO2(orr), pkmul_b<0>(C0, LO2(orr)))));
;                     float y0 = q.x, y1 = q.y;
;                     y0 += dppf<0xB1>(y0); y1 += dppf<0xB1>(y1);
;                     *(LAS f32x2*)(yb + ((s * 32 + (r0 >> 1)) * 8 + ((lane >> 1) & 7)) * 2) = (f32x2){y0, y1};
;                     ow = now; oa = noa; ob = nob; ok = nok; orr = norr; vv = nvv;
;                 }
	v_pk_fma_f32 v[236:237], v[168:169], v[116:117], v[236:237] op_sel_hi:[1,0,1]
	v_pk_fma_f32 v[238:239], v[168:169], v[116:117], v[238:239] op_sel:[0,1,0]
	v_pk_fma_f32 v[240:241], v[168:169], v[118:119], v[240:241] op_sel_hi:[1,0,1]
	v_pk_fma_f32 v[242:243], v[168:169], v[118:119], v[242:243] op_sel:[0,1,0]
	v_pk_fma_f32 v[244:245], v[168:169], v[120:121], v[244:245] op_sel_hi:[1,0,1]
	v_pk_fma_f32 v[246:247], v[168:169], v[120:121], v[246:247] op_sel:[0,1,0]
	v_pk_fma_f32 v[248:249], v[168:169], v[122:123], v[248:249] op_sel_hi:[1,0,1]
	v_pk_fma_f32 v[250:251], v[168:169], v[122:123], v[250:251] op_sel:[0,1,0]
	ds_read_b128 v[116:119], v252 offset:8992
	ds_read_b128 v[120:123], v252 offset:9072
	s_waitcnt lgkmcnt(9)
	v_pk_fma_f32 v[236:237], v[166:167], v[124:125], v[236:237] op_sel_hi:[1,0,1]
	v_pk_fma_f32 v[238:239], v[166:167], v[124:125], v[238:239] op_sel:[0,1,0]
	v_pk_fma_f32 v[240:241], v[166:167], v[126:127], v[240:241] op_sel_hi:[1,0,1]
	v_pk_fma_f32 v[242:243], v[166:167], v[126:127], v[242:243] op_sel:[0,1,0]
	v_pk_fma_f32 v[244:245], v[166:167], v[128:129], v[244:245] op_sel_hi:[1,0,1]
	v_pk_fma_f32 v[246:247], v[166:167], v[128:129], v[246:247] op_sel:[0,1,0]
	v_pk_fma_f32 v[248:249], v[166:167], v[130:131], v[248:249] op_sel_hi:[1,0,1]
	v_pk_fma_f32 v[250:251], v[166:167], v[130:131], v[250:251] op_sel:[0,1,0]
	ds_read_b128 v[124:127], v252 offset:9008
	ds_read_b128 v[128:131], v252 offset:9088
	ds_read_b64 v[166:167], v253 offset:1792
	s_waitcnt lgkmcnt(10)
	v_pk_mul_f32 v[172:173], v[236:237], v[132:133] op_sel_hi:[1,0]
	v_pk_mul_f32 v[174:175], v[238:239], v[132:133] op_sel:[0,1]
	v_pk_fma_f32 v[172:173], v[240:241], v[134:135], v[172:173] op_sel_hi:[1,0,1]
	v_pk_fma_f32 v[174:175], v[242:243], v[134:135], v[174:175] op_sel:[0,1,0]
	v_pk_fma_f32 v[172:173], v[244:245], v[136:137], v[172:173] op_sel_hi:[1,0,1]
	v_pk_fma_f32 v[174:175], v[246:247], v[136:137], v[174:175] op_sel:[0,1,0]
	v_pk_fma_f32 v[172:173], v[248:249], v[138:139], v[172:173] op_sel_hi:[1,0,1]
	v_pk_fma_f32 v[174:175], v[250:251], v[138:139], v[174:175] op_sel:[0,1,0]
	ds_read_b128 v[132:135], v252 offset:9024
	ds_read_b128 v[136:139], v252 offset:9104
	v_pk_add_f32 v[172:173], v[172:173], v[174:175]
	ds_write_b64 v254, v[172:173] offset:12288
	s_waitcnt lgkmcnt(10)
	v_pk_mul_f32 v[168:169], v[236:237], v[100:101] op_sel_hi:[1,0]
	v_pk_mul_f32 v[170:171], v[238:239], v[100:101] op_sel:[0,1]
	v_pk_fma_f32 v[168:169], v[240:241], v[102:103], v[168:169] op_sel_hi:[1,0,1]
	v_pk_fma_f32 v[170:171], v[242:243], v[102:103], v[170:171] op_sel:[0,1,0]
	v_pk_fma_f32 v[168:169], v[244:245], v[104:105], v[168:169] op_sel_hi:[1,0,1]
	v_pk_fma_f32 v[170:171], v[246:247], v[104:105], v[170:171] op_sel:[0,1,0]
	v_pk_fma_f32 v[168:169], v[248:249], v[106:107], v[168:169] op_sel_hi:[1,0,1]
	v_pk_fma_f32 v[170:171], v[250:251], v[106:107], v[170:171] op_sel:[0,1,0]
	ds_read_b128 v[100:103], v252 offset:10256
	ds_read_b128 v[104:107], v252 offset:10336
	v_pk_add_f32 v[168:169], v[168:169], v[170:171]
	s_waitcnt lgkmcnt(10)
	v_pk_mul_f32 v[236:237], v[236:237], v[108:109] op_sel_hi:[1,0]
	v_pk_mul_f32 v[238:239], v[238:239], v[108:109] op_sel:[0,1]
	v_pk_mul_f32 v[240:241], v[240:241], v[110:111] op_sel_hi:[1,0]
	v_pk_mul_f32 v[242:243], v[242:243], v[110:111] op_sel:[0,1]
	v_pk_mul_f32 v[244:245], v[244:245], v[112:113] op_sel_hi:[1,0]
	v_pk_mul_f32 v[246:247], v[246:247], v[112:113] op_sel:[0,1]
	v_pk_mul_f32 v[248:249], v[248:249], v[114:115] op_sel_hi:[1,0]
	v_pk_mul_f32 v[250:251], v[250:251], v[114:115] op_sel:[0,1]
	v_add_f32_dpp v168, v168, v168 quad_perm:[1,0,3,2] row_mask:0xf bank_mask:0xf bound_ctrl:1
	v_add_f32_dpp v169, v169, v169 quad_perm:[1,0,3,2] row_mask:0xf bank_mask:0xf bound_ctrl:1
	ds_read_b128 v[108:111], v252 offset:10240
	v_add_f32_dpp v168, v168, v168 quad_perm:[2,3,0,1] row_mask:0xf bank_mask:0xf bound_ctrl:1
	v_add_f32_dpp v169, v169, v169 quad_perm:[2,3,0,1] row_mask:0xf bank_mask:0xf bound_ctrl:1
	ds_read_b128 v[112:115], v252 offset:10320
	v_add_f32_dpp v168, v168, v168 row_half_mirror row_mask:0xf bank_mask:0xf bound_ctrl:1
	v_add_f32_dpp v169, v169, v169 row_half_mirror row_mask:0xf bank_mask:0xf bound_ctrl:1
	s_waitcnt lgkmcnt(10)
	v_pk_fma_f32 v[236:237], v[168:169], v[116:117], v[236:237] op_sel_hi:[1,0,1]
	v_pk_fma_f32 v[238:239], v[168:169], v[116:117], v[238:239] op_sel:[0,1,0]
	v_pk_fma_f32 v[240:241], v[168:169], v[118:119], v[240:241] op_sel_hi:[1,0,1]
	v_pk_fma_f32 v[242:243], v[168:169], v[118:119], v[242:243] op_sel:[0,1,0]
	v_pk_fma_f32 v[244:245], v[168:169], v[120:121], v[244:245] op_sel_hi:[1,0,1]
	v_pk_fma_f32 v[246:247], v[168:169], v[120:121], v[246:247] op_sel:[0,1,0]
	v_pk_fma_f32 v[248:249], v[168:169], v[122:123], v[248:249] op_sel_hi:[1,0,1]
	v_pk_fma_f32 v[250:251], v[168:169], v[122:123], v[250:251] op_sel:[0,1,0]
	ds_read_b128 v[116:119], v252 offset:10272
	ds_read_b128 v[120:123], v252 offset:10352
	s_waitcnt lgkmcnt(9)
	v_pk_fma_f32 v[236:237], v[166:167], v[124:125], v[236:237] op_sel_hi:[1,0,1]
	v_pk_fma_f32 v[238:239], v[166:167], v[124:125], v[238:239] op_sel:[0,1,0]
	v_pk_fma_f32 v[240:241], v[166:167], v[126:127], v[240:241] op_sel_hi:[1,0,1]
	v_pk_fma_f32 v[242:243], v[166:167], v[126:127], v[242:243] op_sel:[0,1,0]
	v_pk_fma_f32 v[244:245], v[166:167], v[128:129], v[244:245] op_sel_hi:[1,0,1]
	v_pk_fma_f32 v[246:247], v[166:167], v[128:129], v[246:247] op_sel:[0,1,0]
	v_pk_fma_f32 v[248:249], v[166:167], v[130:131], v[248:249] op_sel_hi:[1,0,1]
	v_pk_fma_f32 v[250:251], v[166:167], v[130:131], v[250:251] op_sel:[0,1,0]
	ds_read_b128 v[124:127], v252 offset:10288
	ds_read_b128 v[128:131], v252 offset:10368
	ds_read_b64 v[166:167], v253 offset:2048
	s_waitcnt lgkmcnt(10)
; #define LAS __attribute__((address_space(3)))
; template <int CTRL> __device__ __forceinline__ float dppf(float v) { return __builtin_bit_cast(float, __builtin_amdgcn_update_dpp(0, __builtin_bit_cast(int, v), CTRL, 0xF, 0xF, true)); }
; #define LO2(v) __builtin_shufflevector(v, v, 0, 1)
; #define HI2(v) __builtin_shufflevector(v, v, 2, 3)
; __device__ __forceinline__ void phase_scan(const Args& a, LAS unsigned char* lds) {
;     ...
;                 for (int s = 0; s < TC; ++s) {
;                     const LAS float* o = obase + (s + 1) * 320;
;                     const f32x4 now = *(const LAS f32x4*)(o), noa = *(const LAS f32x4*)(o + 4), nob = *(const LAS f32x4*)(o + 8), nok = *(const LAS f32x4*)(o + 12), norr = *(const LAS f32x4*)(o + 16);
;                     const f32x2 nvv = *(const LAS f32x2*)(vbase + (s + 1) * 64);
;                     const f32x2 p = pkfma_b<1>(C3, HI2(oa), pkfma_b<0>(C2, HI2(oa), pkfma_b<1>(C1, LO2(oa), pkmul_b<0>(C0, LO2(oa)))));
;                     float sa0 = p.x, sa1 = p.y;
;                     sa0 = reduce16(sa0); asm volatile("" : "+v"(sa0)); sa1 = reduce16(sa1);
;                     const f32x2 sap = {sa0, sa1};
;                     C0 = pkfma_b<0>(vv, LO2(ok), pkfma_b<0>(sap, LO2(ob), pkmul_b<0>(C0, LO2(ow))));
;                     C1 = pkfma_b<1>(vv, LO2(ok), pkfma_b<1>(sap, LO2(ob), pkmul_b<1>(C1, LO2(ow))));
;                     C2 = pkfma_b<0>(vv, HI2(ok), pkfma_b<0>(sap, HI2(ob), pkmul_b<0>(C2, HI2(ow))));
;                     C3 = pkfma_b<1>(vv, HI2(ok), pkfma_b<1>(sap, HI2(ob), pkmul_b<1>(C3, HI2(ow))));
;                     const f32x2 q = pkfma_b<1>(C3, HI2(orr), pkfma_b<0>(C2, HI2(orr), pkfma_b<1>(C1, LO2(orr), pkmul_b<0>(C0, LO2(orr)))));
;                     float y0 = q.x, y1 = q.y;
;                     y0 += dppf<0xB1>(y0); y1 += dppf<0xB1>(y1);
;                     *(LAS f32x2*)(yb + ((s * 32 + (r0 >> 1)) * 8 + ((lane >> 1) & 7)) * 2) = (f32x2){y0, y1};
;                     ow = now; oa = noa; ob = nob; ok = nok; orr = norr; vv = nvv;
;                 }
	v_pk_mul_f32 v[172:173], v[236:237], v[132:133] op_sel_hi:[1,0]
	v_pk_mul_f32 v[174:175], v[238:239], v[132:133] op_sel:[0,1]
	v_pk_fma_f32 v[172:173], v[240:241], v[134:135], v[172:173] op_sel_hi:[1,0,1]
	v_pk_fma_f32 v[174:175], v[242:243], v[134:135], v[174:175] op_sel:[0,1,0]
	v_pk_fma_f32 v[172:173], v[244:245], v[136:137], v[172:173] op_sel_hi:[1,0,1]
	v_pk_fma_f32 v[174:175], v[246:247], v[136:137], v[174:175] op_sel:[0,1,0]
	v_pk_fma_f32 v[172:173], v[248:249], v[138:139], v[172:173] op_sel_hi:[1,0,1]
	v_pk_fma_f32 v[174:175], v[250:251], v[138:139], v[174:175] op_sel:[0,1,0]
	ds_read_b128 v[132:135], v252 offset:10304
	ds_read_b128 v[136:139], v252 offset:10384
	v_pk_add_f32 v[172:173], v[172:173], v[174:175]
	ds_write_b64 v254, v[172:173] offset:14336
	s_waitcnt lgkmcnt(10)
	v_pk_mul_f32 v[168:169], v[236:237], v[100:101] op_sel_hi:[1,0]
	v_pk_mul_f32 v[170:171], v[238:239], v[100:101] op_sel:[0,1]
	v_pk_fma_f32 v[168:169], v[240:241], v[102:103], v[168:169] op_sel_hi:[1,0,1]
	v_pk_fma_f32 v[170:171], v[242:243], v[102:103], v[170:171] op_sel:[0,1,0]
	v_pk_fma_f32 v[168:169], v[244:245], v[104:105], v[168:169] op_sel_hi:[1,0,1]
	v_pk_fma_f32 v[170:171], v[246:247], v[104:105], v[170:171] op_sel:[0,1,0]
	v_pk_fma_f32 v[168:169], v[248:249], v[106:107], v[168:169] op_sel_hi:[1,0,1]
	v_pk_fma_f32 v[170:171], v[250:251], v[106:107], v[170:171] op_sel:[0,1,0]
	ds_read_b128 v[100:103], v252 offset:11536
	ds_read_b128 v[104:107], v252 offset:11616
	v_pk_add_f32 v[168:169], v[168:169], v[170:171]
	s_waitcnt lgkmcnt(10)
	v_pk_mul_f32 v[236:237], v[236:237], v[108:109] op_sel_hi:[1,0]
	v_pk_mul_f32 v[238:239], v[238:239], v[108:109] op_sel:[0,1]
	v_pk_mul_f32 v[240:241], v[240:241], v[110:111] op_sel_hi:[1,0]
	v_pk_mul_f32 v[242:243], v[242:243], v[110:111] op_sel:[0,1]
	v_pk_mul_f32 v[244:245], v[244:245], v[112:113] op_sel_hi:[1,0]
	v_pk_mul_f32 v[246:247], v[246:247], v[112:113] op_sel:[0,1]
	v_pk_mul_f32 v[248:249], v[248:249], v[114:115] op_sel_hi:[1,0]
	v_pk_mul_f32 v[250:251], v[250:251], v[114:115] op_sel:[0,1]
	v_add_f32_dpp v168, v168, v168 quad_perm:[1,0,3,2] row_mask:0xf bank_mask:0xf bound_ctrl:1
	v_add_f32_dpp v169, v169, v169 quad_perm:[1,0,3,2] row_mask:0xf bank_mask:0xf bound_ctrl:1
	ds_read_b128 v[108:111], v252 offset:11520
	v_add_f32_dpp v168, v168, v168 quad_perm:[2,3,0,1] row_mask:0xf bank_mask:0xf bound_ctrl:1
	v_add_f32_dpp v169, v169, v169 quad_perm:[2,3,0,1] row_mask:0xf bank_mask:0xf bound_ctrl:1
	ds_read_b128 v[112:115], v252 offset:11600
	v_add_f32_dpp v168, v168, v168 row_half_mirror row_mask:0xf bank_mask:0xf bound_ctrl:1
	v_add_f32_dpp v169, v169, v169 row_half_mirror row_mask:0xf bank_mask:0xf bound_ctrl:1
	s_waitcnt lgkmcnt(10)
	v_pk_fma_f32 v[236:237], v[168:169], v[116:117], v[236:237] op_sel_hi:[1,0,1]
	v_pk_fma_f32 v[238:239], v[168:169], v[116:117], v[238:239] op_sel:[0,1,0]
	v_pk_fma_f32 v[240:241], v[168:169], v[118:119], v[240:241] op_sel_hi:[1,0,1]
	v_pk_fma_f32 v[242:243], v[168:169], v[118:119], v[242:243] op_sel:[0,1,0]
	v_pk_fma_f32 v[244:245], v[168:169], v[120:121], v[244:245] op_sel_hi:[1,0,1]
	v_pk_fma_f32 v[246:247], v[168:169], v[120:121], v[246:247] op_sel:[0,1,0]
	v_pk_fma_f32 v[248:249], v[168:169], v[122:123], v[248:249] op_sel_hi:[1,0,1]
	v_pk_fma_f32 v[250:251], v[168:169], v[122:123], v[250:251] op_sel:[0,1,0]
	ds_read_b128 v[116:119], v252 offset:11552
	ds_read_b128 v[120:123], v252 offset:11632
	s_waitcnt lgkmcnt(9)
	v_pk_fma_f32 v[236:237], v[166:167], v[124:125], v[236:237] op_sel_hi:[1,0,1]
	v_pk_fma_f32 v[238:239], v[166:167], v[124:125], v[238:239] op_sel:[0,1,0]
	v_pk_fma_f32 v[240:241], v[166:167], v[126:127], v[240:241] op_sel_hi:[1,0,1]
	v_pk_fma_f32 v[242:243], v[166:167], v[126:127], v[242:243] op_sel:[0,1,0]
	v_pk_fma_f32 v[244:245], v[166:167], v[128:129], v[244:245] op_sel_hi:[1,0,1]
	v_pk_fma_f32 v[246:247], v[166:167], v[128:129], v[246:247] op_sel:[0,1,0]
	v_pk_fma_f32 v[248:249], v[166:167], v[130:131], v[248:249] op_sel_hi:[1,0,1]
	v_pk_fma_f32 v[250:251], v[166:167], v[130:131], v[250:251] op_sel:[0,1,0]
	ds_read_b128 v[124:127], v252 offset:11568
	ds_read_b128 v[128:131], v252 offset:11648
	ds_read_b64 v[166:167], v253 offset:2304
	s_waitcnt lgkmcnt(10)
	v_pk_mul_f32 v[172:173], v[236:237], v[132:133] op_sel_hi:[1,0]
	v_pk_mul_f32 v[174:175], v[238:239], v[132:133] op_sel:[0,1]
	v_pk_fma_f32 v[172:173], v[240:241], v[134:135], v[172:173] op_sel_hi:[1,0,1]
	v_pk_fma_f32 v[174:175], v[242:243], v[134:135], v[174:175] op_sel:[0,1,0]
	v_pk_fma_f32 v[172:173], v[244:245], v[136:137], v[172:173] op_sel_hi:[1,0,1]
	v_pk_fma_f32 v[174:175], v[246:247], v[136:137], v[174:175] op_sel:[0,1,0]
	v_pk_fma_f32 v[172:173], v[248:249], v[138:139], v[172:173] op_sel_hi:[1,0,1]
	v_pk_fma_f32 v[174:175], v[250:251], v[138:139], v[174:175] op_sel:[0,1,0]
	ds_read_b128 v[132:135], v252 offset:11584
	ds_read_b128 v[136:139], v252 offset:11664
	v_pk_add_f32 v[172:173], v[172:173], v[174:175]
	ds_write_b64 v254, v[172:173] offset:16384
	s_waitcnt lgkmcnt(10)
	v_pk_mul_f32 v[168:169], v[236:237], v[100:101] op_sel_hi:[1,0]
	v_pk_mul_f32 v[170:171], v[238:239], v[100:101] op_sel:[0,1]
	v_pk_fma_f32 v[168:169], v[240:241], v[102:103], v[168:169] op_sel_hi:[1,0,1]
	v_pk_fma_f32 v[170:171], v[242:243], v[102:103], v[170:171] op_sel:[0,1,0]
	v_pk_fma_f32 v[168:169], v[244:245], v[104:105], v[168:169] op_sel_hi:[1,0,1]
	v_pk_fma_f32 v[170:171], v[246:247], v[104:105], v[170:171] op_sel:[0,1,0]
	v_pk_fma_f32 v[168:169], v[248:249], v[106:107], v[168:169] op_sel_hi:[1,0,1]
	v_pk_fma_f32 v[170:171], v[250:251], v[106:107], v[170:171] op_sel:[0,1,0]
	ds_read_b128 v[100:103], v252 offset:12816
	ds_read_b128 v[104:107], v252 offset:12896
	v_pk_add_f32 v[168:169], v[168:169], v[170:171]
	s_waitcnt lgkmcnt(10)
; #define LAS __attribute__((address_space(3)))
; template <int CTRL> __device__ __forceinline__ float dppf(float v) { return __builtin_bit_cast(float, __builtin_amdgcn_update_dpp(0, __builtin_bit_cast(int, v), CTRL, 0xF, 0xF, true)); }
; #define LO2(v) __builtin_shufflevector(v, v, 0, 1)
; #define HI2(v) __builtin_shufflevector(v, v, 2, 3)
; __device__ __forceinline__ void phase_scan(const Args& a, LAS unsigned char* lds) {
;     ...
;                 for (int s = 0; s < TC; ++s) {
;                     const LAS float* o = obase + (s + 1) * 320;
;                     const f32x4 now = *(const LAS f32x4*)(o), noa = *(const LAS f32x4*)(o + 4), nob = *(const LAS f32x4*)(o + 8), nok = *(const LAS f32x4*)(o + 12), norr = *(const LAS f32x4*)(o + 16);
;                     const f32x2 nvv = *(const LAS f32x2*)(vbase + (s + 1) * 64);
;                     const f32x2 p = pkfma_b<1>(C3, HI2(oa), pkfma_b<0>(C2, HI2(oa), pkfma_b<1>(C1, LO2(oa), pkmul_b<0>(C0, LO2(oa)))));
;                     float sa0 = p.x, sa1 = p.y;
;                     sa0 = reduce16(sa0); asm volatile("" : "+v"(sa0)); sa1 = reduce16(sa1);
;                     const f32x2 sap = {sa0, sa1};
;                     C0 = pkfma_b<0>(vv, LO2(ok), pkfma_b<0>(sap, LO2(ob), pkmul_b<0>(C0, LO2(ow))));
;                     C1 = pkfma_b<1>(vv, LO2(ok), pkfma_b<1>(sap, LO2(ob), pkmul_b<1>(C1, LO2(ow))));
;                     C2 = pkfma_b<0>(vv, HI2(ok), pkfma_b<0>(sap, HI2(ob), pkmul_b<0>(C2, HI2(ow))));
;                     C3 = pkfma_b<1>(vv, HI2(ok), pkfma_b<1>(sap, HI2(ob), pkmul_b<1>(C3, HI2(ow))));
;                     const f32x2 q = pkfma_b<1>(C3, HI2(orr), pkfma_b<0>(C2, HI2(orr), pkfma_b<1>(C1, LO2(orr), pkmul_b<0>(C0, LO2(orr)))));
;                     float y0 = q.x, y1 = q.y;
;                     y0 += dppf<0xB1>(y0); y1 += dppf<0xB1>(y1);
;                     *(LAS f32x2*)(yb + ((s * 32 + (r0 >> 1)) * 8 + ((lane >> 1) & 7)) * 2) = (f32x2){y0, y1};
;                     ow = now; oa = noa; ob = nob; ok = nok; orr = norr; vv = nvv;
;                 }
	v_pk_mul_f32 v[236:237], v[236:237], v[108:109] op_sel_hi:[1,0]
	v_pk_mul_f32 v[238:239], v[238:239], v[108:109] op_sel:[0,1]
	v_pk_mul_f32 v[240:241], v[240:241], v[110:111] op_sel_hi:[1,0]
	v_pk_mul_f32 v[242:243], v[242:243], v[110:111] op_sel:[0,1]
	v_pk_mul_f32 v[244:245], v[244:245], v[112:113] op_sel_hi:[1,0]
	v_pk_mul_f32 v[246:247], v[246:247], v[112:113] op_sel:[0,1]
	v_pk_mul_f32 v[248:249], v[248:249], v[114:115] op_sel_hi:[1,0]
	v_pk_mul_f32 v[250:251], v[250:251], v[114:115] op_sel:[0,1]
	v_add_f32_dpp v168, v168, v168 quad_perm:[1,0,3,2] row_mask:0xf bank_mask:0xf bound_ctrl:1
	v_add_f32_dpp v169, v169, v169 quad_perm:[1,0,3,2] row_mask:0xf bank_mask:0xf bound_ctrl:1
	ds_read_b128 v[108:111], v252 offset:12800
	v_add_f32_dpp v168, v168, v168 quad_perm:[2,3,0,1] row_mask:0xf bank_mask:0xf bound_ctrl:1
	v_add_f32_dpp v169, v169, v169 quad_perm:[2,3,0,1] row_mask:0xf bank_mask:0xf bound_ctrl:1
	ds_read_b128 v[112:115], v252 offset:12880
	v_add_f32_dpp v168, v168, v168 row_half_mirror row_mask:0xf bank_mask:0xf bound_ctrl:1
	v_add_f32_dpp v169, v169, v169 row_half_mirror row_mask:0xf bank_mask:0xf bound_ctrl:1
	s_waitcnt lgkmcnt(10)
	v_pk_fma_f32 v[236:237], v[168:169], v[116:117], v[236:237] op_sel_hi:[1,0,1]
	v_pk_fma_f32 v[238:239], v[168:169], v[116:117], v[238:239] op_sel:[0,1,0]
	v_pk_fma_f32 v[240:241], v[168:169], v[118:119], v[240:241] op_sel_hi:[1,0,1]
	v_pk_fma_f32 v[242:243], v[168:169], v[118:119], v[242:243] op_sel:[0,1,0]
	v_pk_fma_f32 v[244:245], v[168:169], v[120:121], v[244:245] op_sel_hi:[1,0,1]
	v_pk_fma_f32 v[246:247], v[168:169], v[120:121], v[246:247] op_sel:[0,1,0]
	v_pk_fma_f32 v[248:249], v[168:169], v[122:123], v[248:249] op_sel_hi:[1,0,1]
	v_pk_fma_f32 v[250:251], v[168:169], v[122:123], v[250:251] op_sel:[0,1,0]
	ds_read_b128 v[116:119], v252 offset:12832
	ds_read_b128 v[120:123], v252 offset:12912
	s_waitcnt lgkmcnt(9)
	v_pk_fma_f32 v[236:237], v[166:167], v[124:125], v[236:237] op_sel_hi:[1,0,1]
	v_pk_fma_f32 v[238:239], v[166:167], v[124:125], v[238:239] op_sel:[0,1,0]
	v_pk_fma_f32 v[240:241], v[166:167], v[126:127], v[240:241] op_sel_hi:[1,0,1]
	v_pk_fma_f32 v[242:243], v[166:167], v[126:127], v[242:243] op_sel:[0,1,0]
	v_pk_fma_f32 v[244:245], v[166:167], v[128:129], v[244:245] op_sel_hi:[1,0,1]
	v_pk_fma_f32 v[246:247], v[166:167], v[128:129], v[246:247] op_sel:[0,1,0]
	v_pk_fma_f32 v[248:249], v[166:167], v[130:131], v[248:249] op_sel_hi:[1,0,1]
	v_pk_fma_f32 v[250:251], v[166:167], v[130:131], v[250:251] op_sel:[0,1,0]
	ds_read_b128 v[124:127], v252 offset:12848
	ds_read_b128 v[128:131], v252 offset:12928
	ds_read_b64 v[166:167], v253 offset:2560
	s_waitcnt lgkmcnt(10)
	v_pk_mul_f32 v[172:173], v[236:237], v[132:133] op_sel_hi:[1,0]
	v_pk_mul_f32 v[174:175], v[238:239], v[132:133] op_sel:[0,1]
	v_pk_fma_f32 v[172:173], v[240:241], v[134:135], v[172:173] op_sel_hi:[1,0,1]
	v_pk_fma_f32 v[174:175], v[242:243], v[134:135], v[174:175] op_sel:[0,1,0]
	v_pk_fma_f32 v[172:173], v[244:245], v[136:137], v[172:173] op_sel_hi:[1,0,1]
	v_pk_fma_f32 v[174:175], v[246:247], v[136:137], v[174:175] op_sel:[0,1,0]
	v_pk_fma_f32 v[172:173], v[248:249], v[138:139], v[172:173] op_sel_hi:[1,0,1]
	v_pk_fma_f32 v[174:175], v[250:251], v[138:139], v[174:175] op_sel:[0,1,0]
	ds_read_b128 v[132:135], v252 offset:12864
	ds_read_b128 v[136:139], v252 offset:12944
	v_pk_add_f32 v[172:173], v[172:173], v[174:175]
	ds_write_b64 v254, v[172:173] offset:18432
	s_waitcnt lgkmcnt(10)
	v_pk_mul_f32 v[168:169], v[236:237], v[100:101] op_sel_hi:[1,0]
	v_pk_mul_f32 v[170:171], v[238:239], v[100:101] op_sel:[0,1]
	v_pk_fma_f32 v[168:169], v[240:241], v[102:103], v[168:169] op_sel_hi:[1,0,1]
	v_pk_fma_f32 v[170:171], v[242:243], v[102:103], v[170:171] op_sel:[0,1,0]
	v_pk_fma_f32 v[168:169], v[244:245], v[104:105], v[168:169] op_sel_hi:[1,0,1]
	v_pk_fma_f32 v[170:171], v[246:247], v[104:105], v[170:171] op_sel:[0,1,0]
	v_pk_fma_f32 v[168:169], v[248:249], v[106:107], v[168:169] op_sel_hi:[1,0,1]
	v_pk_fma_f32 v[170:171], v[250:251], v[106:107], v[170:171] op_sel:[0,1,0]
	ds_read_b128 v[100:103], v252 offset:14096
	ds_read_b128 v[104:107], v252 offset:14176
	v_pk_add_f32 v[168:169], v[168:169], v[170:171]
	s_waitcnt lgkmcnt(10)
	v_pk_mul_f32 v[236:237], v[236:237], v[108:109] op_sel_hi:[1,0]
	v_pk_mul_f32 v[238:239], v[238:239], v[108:109] op_sel:[0,1]
	v_pk_mul_f32 v[240:241], v[240:241], v[110:111] op_sel_hi:[1,0]
	v_pk_mul_f32 v[242:243], v[242:243], v[110:111] op_sel:[0,1]
	v_pk_mul_f32 v[244:245], v[244:245], v[112:113] op_sel_hi:[1,0]
	v_pk_mul_f32 v[246:247], v[246:247], v[112:113] op_sel:[0,1]
	v_pk_mul_f32 v[248:249], v[248:249], v[114:115] op_sel_hi:[1,0]
	v_pk_mul_f32 v[250:251], v[250:251], v[114:115] op_sel:[0,1]
	v_add_f32_dpp v168, v168, v168 quad_perm:[1,0,3,2] row_mask:0xf bank_mask:0xf bound_ctrl:1
	v_add_f32_dpp v169, v169, v169 quad_perm:[1,0,3,2] row_mask:0xf bank_mask:0xf bound_ctrl:1
	ds_read_b128 v[108:111], v252 offset:14080
	v_add_f32_dpp v168, v168, v168 quad_perm:[2,3,0,1] row_mask:0xf bank_mask:0xf bound_ctrl:1
	v_add_f32_dpp v169, v169, v169 quad_perm:[2,3,0,1] row_mask:0xf bank_mask:0xf bound_ctrl:1
	ds_read_b128 v[112:115], v252 offset:14160
	v_add_f32_dpp v168, v168, v168 row_half_mirror row_mask:0xf bank_mask:0xf bound_ctrl:1
	v_add_f32_dpp v169, v169, v169 row_half_mirror row_mask:0xf bank_mask:0xf bound_ctrl:1
	s_waitcnt lgkmcnt(10)
; #define LAS __attribute__((address_space(3)))
; template <int CTRL> __device__ __forceinline__ float dppf(float v) { return __builtin_bit_cast(float, __builtin_amdgcn_update_dpp(0, __builtin_bit_cast(int, v), CTRL, 0xF, 0xF, true)); }
; #define LO2(v) __builtin_shufflevector(v, v, 0, 1)
; #define HI2(v) __builtin_shufflevector(v, v, 2, 3)
; __device__ __forceinline__ void phase_scan(const Args& a, LAS unsigned char* lds) {
;     ...
;                 for (int s = 0; s < TC; ++s) {
;                     const LAS float* o = obase + (s + 1) * 320;
;                     const f32x4 now = *(const LAS f32x4*)(o), noa = *(const LAS f32x4*)(o + 4), nob = *(const LAS f32x4*)(o + 8), nok = *(const LAS f32x4*)(o + 12), norr = *(const LAS f32x4*)(o + 16);
;                     const f32x2 nvv = *(const LAS f32x2*)(vbase + (s + 1) * 64);
;                     const f32x2 p = pkfma_b<1>(C3, HI2(oa), pkfma_b<0>(C2, HI2(oa), pkfma_b<1>(C1, LO2(oa), pkmul_b<0>(C0, LO2(oa)))));
;                     float sa0 = p.x, sa1 = p.y;
;                     sa0 = reduce16(sa0); asm volatile("" : "+v"(sa0)); sa1 = reduce16(sa1);
;                     const f32x2 sap = {sa0, sa1};
;                     C0 = pkfma_b<0>(vv, LO2(ok), pkfma_b<0>(sap, LO2(ob), pkmul_b<0>(C0, LO2(ow))));
;                     C1 = pkfma_b<1>(vv, LO2(ok), pkfma_b<1>(sap, LO2(ob), pkmul_b<1>(C1, LO2(ow))));
;                     C2 = pkfma_b<0>(vv, HI2(ok), pkfma_b<0>(sap, HI2(ob), pkmul_b<0>(C2, HI2(ow))));
;                     C3 = pkfma_b<1>(vv, HI2(ok), pkfma_b<1>(sap, HI2(ob), pkmul_b<1>(C3, HI2(ow))));
;                     const f32x2 q = pkfma_b<1>(C3, HI2(orr), pkfma_b<0>(C2, HI2(orr), pkfma_b<1>(C1, LO2(orr), pkmul_b<0>(C0, LO2(orr)))));
;                     float y0 = q.x, y1 = q.y;
;                     y0 += dppf<0xB1>(y0); y1 += dppf<0xB1>(y1);
;                     *(LAS f32x2*)(yb + ((s * 32 + (r0 >> 1)) * 8 + ((lane >> 1) & 7)) * 2) = (f32x2){y0, y1};
;                     ow = now; oa = noa; ob = nob; ok = nok; orr = norr; vv = nvv;
;                 }
	v_pk_fma_f32 v[236:237], v[168:169], v[116:117], v[236:237] op_sel_hi:[1,0,1]
	v_pk_fma_f32 v[238:239], v[168:169], v[116:117], v[238:239] op_sel:[0,1,0]
	v_pk_fma_f32 v[240:241], v[168:169], v[118:119], v[240:241] op_sel_hi:[1,0,1]
	v_pk_fma_f32 v[242:243], v[168:169], v[118:119], v[242:243] op_sel:[0,1,0]
	v_pk_fma_f32 v[244:245], v[168:169], v[120:121], v[244:245] op_sel_hi:[1,0,1]
	v_pk_fma_f32 v[246:247], v[168:169], v[120:121], v[246:247] op_sel:[0,1,0]
	v_pk_fma_f32 v[248:249], v[168:169], v[122:123], v[248:249] op_sel_hi:[1,0,1]
	v_pk_fma_f32 v[250:251], v[168:169], v[122:123], v[250:251] op_sel:[0,1,0]
	ds_read_b128 v[116:119], v252 offset:14112
	ds_read_b128 v[120:123], v252 offset:14192
	s_waitcnt lgkmcnt(9)
	v_pk_fma_f32 v[236:237], v[166:167], v[124:125], v[236:237] op_sel_hi:[1,0,1]
	v_pk_fma_f32 v[238:239], v[166:167], v[124:125], v[238:239] op_sel:[0,1,0]
	v_pk_fma_f32 v[240:241], v[166:167], v[126:127], v[240:241] op_sel_hi:[1,0,1]
	v_pk_fma_f32 v[242:243], v[166:167], v[126:127], v[242:243] op_sel:[0,1,0]
	v_pk_fma_f32 v[244:245], v[166:167], v[128:129], v[244:245] op_sel_hi:[1,0,1]
	v_pk_fma_f32 v[246:247], v[166:167], v[128:129], v[246:247] op_sel:[0,1,0]
	v_pk_fma_f32 v[248:249], v[166:167], v[130:131], v[248:249] op_sel_hi:[1,0,1]
	v_pk_fma_f32 v[250:251], v[166:167], v[130:131], v[250:251] op_sel:[0,1,0]
	ds_read_b128 v[124:127], v252 offset:14128
	ds_read_b128 v[128:131], v252 offset:14208
	ds_read_b64 v[166:167], v253 offset:2816
	s_waitcnt lgkmcnt(10)
	v_pk_mul_f32 v[172:173], v[236:237], v[132:133] op_sel_hi:[1,0]
	v_pk_mul_f32 v[174:175], v[238:239], v[132:133] op_sel:[0,1]
	v_pk_fma_f32 v[172:173], v[240:241], v[134:135], v[172:173] op_sel_hi:[1,0,1]
	v_pk_fma_f32 v[174:175], v[242:243], v[134:135], v[174:175] op_sel:[0,1,0]
	v_pk_fma_f32 v[172:173], v[244:245], v[136:137], v[172:173] op_sel_hi:[1,0,1]
	v_pk_fma_f32 v[174:175], v[246:247], v[136:137], v[174:175] op_sel:[0,1,0]
	v_pk_fma_f32 v[172:173], v[248:249], v[138:139], v[172:173] op_sel_hi:[1,0,1]
	v_pk_fma_f32 v[174:175], v[250:251], v[138:139], v[174:175] op_sel:[0,1,0]
	ds_read_b128 v[132:135], v252 offset:14144
	ds_read_b128 v[136:139], v252 offset:14224
	v_pk_add_f32 v[172:173], v[172:173], v[174:175]
	ds_write_b64 v254, v[172:173] offset:20480
	s_waitcnt lgkmcnt(10)
	v_pk_mul_f32 v[168:169], v[236:237], v[100:101] op_sel_hi:[1,0]
	v_pk_mul_f32 v[170:171], v[238:239], v[100:101] op_sel:[0,1]
	v_pk_fma_f32 v[168:169], v[240:241], v[102:103], v[168:169] op_sel_hi:[1,0,1]
	v_pk_fma_f32 v[170:171], v[242:243], v[102:103], v[170:171] op_sel:[0,1,0]
	v_pk_fma_f32 v[168:169], v[244:245], v[104:105], v[168:169] op_sel_hi:[1,0,1]
	v_pk_fma_f32 v[170:171], v[246:247], v[104:105], v[170:171] op_sel:[0,1,0]
	v_pk_fma_f32 v[168:169], v[248:249], v[106:107], v[168:169] op_sel_hi:[1,0,1]
	v_pk_fma_f32 v[170:171], v[250:251], v[106:107], v[170:171] op_sel:[0,1,0]
	ds_read_b128 v[100:103], v252 offset:15376
	ds_read_b128 v[104:107], v252 offset:15456
	v_pk_add_f32 v[168:169], v[168:169], v[170:171]
	s_waitcnt lgkmcnt(10)
	v_pk_mul_f32 v[236:237], v[236:237], v[108:109] op_sel_hi:[1,0]
	v_pk_mul_f32 v[238:239], v[238:239], v[108:109] op_sel:[0,1]
	v_pk_mul_f32 v[240:241], v[240:241], v[110:111] op_sel_hi:[1,0]
	v_pk_mul_f32 v[242:243], v[242:243], v[110:111] op_sel:[0,1]
	v_pk_mul_f32 v[244:245], v[244:245], v[112:113] op_sel_hi:[1,0]
	v_pk_mul_f32 v[246:247], v[246:247], v[112:113] op_sel:[0,1]
	v_pk_mul_f32 v[248:249], v[248:249], v[114:115] op_sel_hi:[1,0]
	v_pk_mul_f32 v[250:251], v[250:251], v[114:115] op_sel:[0,1]
	v_add_f32_dpp v168, v168, v168 quad_perm:[1,0,3,2] row_mask:0xf bank_mask:0xf bound_ctrl:1
	v_add_f32_dpp v169, v169, v169 quad_perm:[1,0,3,2] row_mask:0xf bank_mask:0xf bound_ctrl:1
	ds_read_b128 v[108:111], v252 offset:15360
	v_add_f32_dpp v168, v168, v168 quad_perm:[2,3,0,1] row_mask:0xf bank_mask:0xf bound_ctrl:1
	v_add_f32_dpp v169, v169, v169 quad_perm:[2,3,0,1] row_mask:0xf bank_mask:0xf bound_ctrl:1
	ds_read_b128 v[112:115], v252 offset:15440
	v_add_f32_dpp v168, v168, v168 row_half_mirror row_mask:0xf bank_mask:0xf bound_ctrl:1
	v_add_f32_dpp v169, v169, v169 row_half_mirror row_mask:0xf bank_mask:0xf bound_ctrl:1
	s_waitcnt lgkmcnt(10)
	v_pk_fma_f32 v[236:237], v[168:169], v[116:117], v[236:237] op_sel_hi:[1,0,1]
	v_pk_fma_f32 v[238:239], v[168:169], v[116:117], v[238:239] op_sel:[0,1,0]
	v_pk_fma_f32 v[240:241], v[168:169], v[118:119], v[240:241] op_sel_hi:[1,0,1]
	v_pk_fma_f32 v[242:243], v[168:169], v[118:119], v[242:243] op_sel:[0,1,0]
	v_pk_fma_f32 v[244:245], v[168:169], v[120:121], v[244:245] op_sel_hi:[1,0,1]
	v_pk_fma_f32 v[246:247], v[168:169], v[120:121], v[246:247] op_sel:[0,1,0]
	v_pk_fma_f32 v[248:249], v[168:169], v[122:123], v[248:249] op_sel_hi:[1,0,1]
	v_pk_fma_f32 v[250:251], v[168:169], v[122:123], v[250:251] op_sel:[0,1,0]
	ds_read_b128 v[116:119], v252 offset:15392
	ds_read_b128 v[120:123], v252 offset:15472
	s_waitcnt lgkmcnt(9)
	v_pk_fma_f32 v[236:237], v[166:167], v[124:125], v[236:237] op_sel_hi:[1,0,1]
	v_pk_fma_f32 v[238:239], v[166:167], v[124:125], v[238:239] op_sel:[0,1,0]
	v_pk_fma_f32 v[240:241], v[166:167], v[126:127], v[240:241] op_sel_hi:[1,0,1]
	v_pk_fma_f32 v[242:243], v[166:167], v[126:127], v[242:243] op_sel:[0,1,0]
	v_pk_fma_f32 v[244:245], v[166:167], v[128:129], v[244:245] op_sel_hi:[1,0,1]
	v_pk_fma_f32 v[246:247], v[166:167], v[128:129], v[246:247] op_sel:[0,1,0]
	v_pk_fma_f32 v[248:249], v[166:167], v[130:131], v[248:249] op_sel_hi:[1,0,1]
	v_pk_fma_f32 v[250:251], v[166:167], v[130:131], v[250:251] op_sel:[0,1,0]
	ds_read_b128 v[124:127], v252 offset:15408
	ds_read_b128 v[128:131], v252 offset:15488
	ds_read_b64 v[166:167], v253 offset:3072
	s_waitcnt lgkmcnt(10)
	v_pk_mul_f32 v[172:173], v[236:237], v[132:133] op_sel_hi:[1,0]
	v_pk_mul_f32 v[174:175], v[238:239], v[132:133] op_sel:[0,1]
	v_pk_fma_f32 v[172:173], v[240:241], v[134:135], v[172:173] op_sel_hi:[1,0,1]
	v_pk_fma_f32 v[174:175], v[242:243], v[134:135], v[174:175] op_sel:[0,1,0]
	v_pk_fma_f32 v[172:173], v[244:245], v[136:137], v[172:173] op_sel_hi:[1,0,1]
	v_pk_fma_f32 v[174:175], v[246:247], v[136:137], v[174:175] op_sel:[0,1,0]
	v_pk_fma_f32 v[172:173], v[248:249], v[138:139], v[172:173] op_sel_hi:[1,0,1]
	v_pk_fma_f32 v[174:175], v[250:251], v[138:139], v[174:175] op_sel:[0,1,0]
	ds_read_b128 v[132:135], v252 offset:15424
	ds_read_b128 v[136:139], v252 offset:15504
	v_pk_add_f32 v[172:173], v[172:173], v[174:175]
	ds_write_b64 v254, v[172:173] offset:22528
	s_barrier
; #define LAS __attribute__((address_space(3)))
; template <int CTRL> __device__ __forceinline__ float dppf(float v) { return __builtin_bit_cast(float, __builtin_amdgcn_update_dpp(0, __builtin_bit_cast(int, v), CTRL, 0xF, 0xF, true)); }
; #define LO2(v) __builtin_shufflevector(v, v, 0, 1)
; #define HI2(v) __builtin_shufflevector(v, v, 2, 3)
; __device__ __forceinline__ void phase_scan(const Args& a, LAS unsigned char* lds) {
;     ...
;                 for (int s = 0; s < TC; ++s) {
;                     const LAS float* o = obase + (s + 1) * 320;
;                     const f32x4 now = *(const LAS f32x4*)(o), noa = *(const LAS f32x4*)(o + 4), nob = *(const LAS f32x4*)(o + 8), nok = *(const LAS f32x4*)(o + 12), norr = *(const LAS f32x4*)(o + 16);
;                     const f32x2 nvv = *(const LAS f32x2*)(vbase + (s + 1) * 64);
;                     const f32x2 p = pkfma_b<1>(C3, HI2(oa), pkfma_b<0>(C2, HI2(oa), pkfma_b<1>(C1, LO2(oa), pkmul_b<0>(C0, LO2(oa)))));
;                     float sa0 = p.x, sa1 = p.y;
;                     sa0 = reduce16(sa0); asm volatile("" : "+v"(sa0)); sa1 = reduce16(sa1);
;                     const f32x2 sap = {sa0, sa1};
;                     C0 = pkfma_b<0>(vv, LO2(ok), pkfma_b<0>(sap, LO2(ob), pkmul_b<0>(C0, LO2(ow))));
;                     C1 = pkfma_b<1>(vv, LO2(ok), pkfma_b<1>(sap, LO2(ob), pkmul_b<1>(C1, LO2(ow))));
;                     C2 = pkfma_b<0>(vv, HI2(ok), pkfma_b<0>(sap, HI2(ob), pkmul_b<0>(C2, HI2(ow))));
;                     C3 = pkfma_b<1>(vv, HI2(ok), pkfma_b<1>(sap, HI2(ob), pkmul_b<1>(C3, HI2(ow))));
;                     const f32x2 q = pkfma_b<1>(C3, HI2(orr), pkfma_b<0>(C2, HI2(orr), pkfma_b<1>(C1, LO2(orr), pkmul_b<0>(C0, LO2(orr)))));
;                     float y0 = q.x, y1 = q.y;
;                     y0 += dppf<0xB1>(y0); y1 += dppf<0xB1>(y1);
;                     *(LAS f32x2*)(yb + ((s * 32 + (r0 >> 1)) * 8 + ((lane >> 1) & 7)) * 2) = (f32x2){y0, y1};
;                     ow = now; oa = noa; ob = nob; ok = nok; orr = norr; vv = nvv;
;                 }
	s_waitcnt lgkmcnt(10)
	v_pk_mul_f32 v[168:169], v[236:237], v[100:101] op_sel_hi:[1,0]
	v_pk_mul_f32 v[170:171], v[238:239], v[100:101] op_sel:[0,1]
	v_pk_fma_f32 v[168:169], v[240:241], v[102:103], v[168:169] op_sel_hi:[1,0,1]
	v_pk_fma_f32 v[170:171], v[242:243], v[102:103], v[170:171] op_sel:[0,1,0]
	v_pk_fma_f32 v[168:169], v[244:245], v[104:105], v[168:169] op_sel_hi:[1,0,1]
	v_pk_fma_f32 v[170:171], v[246:247], v[104:105], v[170:171] op_sel:[0,1,0]
	v_pk_fma_f32 v[168:169], v[248:249], v[106:107], v[168:169] op_sel_hi:[1,0,1]
	v_pk_fma_f32 v[170:171], v[250:251], v[106:107], v[170:171] op_sel:[0,1,0]
	ds_read_b128 v[100:103], v252 offset:16656
	ds_read_b128 v[104:107], v252 offset:16736
	v_pk_add_f32 v[168:169], v[168:169], v[170:171]
	s_waitcnt lgkmcnt(10)
	v_pk_mul_f32 v[236:237], v[236:237], v[108:109] op_sel_hi:[1,0]
	v_pk_mul_f32 v[238:239], v[238:239], v[108:109] op_sel:[0,1]
	v_pk_mul_f32 v[240:241], v[240:241], v[110:111] op_sel_hi:[1,0]
	v_pk_mul_f32 v[242:243], v[242:243], v[110:111] op_sel:[0,1]
	v_pk_mul_f32 v[244:245], v[244:245], v[112:113] op_sel_hi:[1,0]
	v_pk_mul_f32 v[246:247], v[246:247], v[112:113] op_sel:[0,1]
	v_pk_mul_f32 v[248:249], v[248:249], v[114:115] op_sel_hi:[1,0]
	v_pk_mul_f32 v[250:251], v[250:251], v[114:115] op_sel:[0,1]
	v_add_f32_dpp v168, v168, v168 quad_perm:[1,0,3,2] row_mask:0xf bank_mask:0xf bound_ctrl:1
	v_add_f32_dpp v169, v169, v169 quad_perm:[1,0,3,2] row_mask:0xf bank_mask:0xf bound_ctrl:1
	ds_read_b128 v[108:111], v252 offset:16640
	v_add_f32_dpp v168, v168, v168 quad_perm:[2,3,0,1] row_mask:0xf bank_mask:0xf bound_ctrl:1
	v_add_f32_dpp v169, v169, v169 quad_perm:[2,3,0,1] row_mask:0xf bank_mask:0xf bound_ctrl:1
	ds_read_b128 v[112:115], v252 offset:16720
	v_add_f32_dpp v168, v168, v168 row_half_mirror row_mask:0xf bank_mask:0xf bound_ctrl:1
	v_add_f32_dpp v169, v169, v169 row_half_mirror row_mask:0xf bank_mask:0xf bound_ctrl:1
	s_waitcnt lgkmcnt(10)
	v_pk_fma_f32 v[236:237], v[168:169], v[116:117], v[236:237] op_sel_hi:[1,0,1]
	v_pk_fma_f32 v[238:239], v[168:169], v[116:117], v[238:239] op_sel:[0,1,0]
	v_pk_fma_f32 v[240:241], v[168:169], v[118:119], v[240:241] op_sel_hi:[1,0,1]
	v_pk_fma_f32 v[242:243], v[168:169], v[118:119], v[242:243] op_sel:[0,1,0]
	v_pk_fma_f32 v[244:245], v[168:169], v[120:121], v[244:245] op_sel_hi:[1,0,1]
	v_pk_fma_f32 v[246:247], v[168:169], v[120:121], v[246:247] op_sel:[0,1,0]
	v_pk_fma_f32 v[248:249], v[168:169], v[122:123], v[248:249] op_sel_hi:[1,0,1]
	v_pk_fma_f32 v[250:251], v[168:169], v[122:123], v[250:251] op_sel:[0,1,0]
	ds_read_b128 v[116:119], v252 offset:16672
	ds_read_b128 v[120:123], v252 offset:16752
	s_waitcnt lgkmcnt(9)
	v_pk_fma_f32 v[236:237], v[166:167], v[124:125], v[236:237] op_sel_hi:[1,0,1]
	v_pk_fma_f32 v[238:239], v[166:167], v[124:125], v[238:239] op_sel:[0,1,0]
	v_pk_fma_f32 v[240:241], v[166:167], v[126:127], v[240:241] op_sel_hi:[1,0,1]
	v_pk_fma_f32 v[242:243], v[166:167], v[126:127], v[242:243] op_sel:[0,1,0]
	v_pk_fma_f32 v[244:245], v[166:167], v[128:129], v[244:245] op_sel_hi:[1,0,1]
	v_pk_fma_f32 v[246:247], v[166:167], v[128:129], v[246:247] op_sel:[0,1,0]
	v_pk_fma_f32 v[248:249], v[166:167], v[130:131], v[248:249] op_sel_hi:[1,0,1]
	v_pk_fma_f32 v[250:251], v[166:167], v[130:131], v[250:251] op_sel:[0,1,0]
	ds_read_b128 v[124:127], v252 offset:16688
	ds_read_b128 v[128:131], v252 offset:16768
	ds_read_b64 v[166:167], v253 offset:3328
	s_waitcnt lgkmcnt(10)
	v_pk_mul_f32 v[172:173], v[236:237], v[132:133] op_sel_hi:[1,0]
	v_pk_mul_f32 v[174:175], v[238:239], v[132:133] op_sel:[0,1]
	v_pk_fma_f32 v[172:173], v[240:241], v[134:135], v[172:173] op_sel_hi:[1,0,1]
	v_pk_fma_f32 v[174:175], v[242:243], v[134:135], v[174:175] op_sel:[0,1,0]
	v_pk_fma_f32 v[172:173], v[244:245], v[136:137], v[172:173] op_sel_hi:[1,0,1]
	v_pk_fma_f32 v[174:175], v[246:247], v[136:137], v[174:175] op_sel:[0,1,0]
	v_pk_fma_f32 v[172:173], v[248:249], v[138:139], v[172:173] op_sel_hi:[1,0,1]
	v_pk_fma_f32 v[174:175], v[250:251], v[138:139], v[174:175] op_sel:[0,1,0]
	ds_read_b128 v[132:135], v252 offset:16704
	ds_read_b128 v[136:139], v252 offset:16784
	v_pk_add_f32 v[172:173], v[172:173], v[174:175]
	ds_write_b64 v254, v[172:173] offset:24576
	s_waitcnt lgkmcnt(10)
	v_pk_mul_f32 v[168:169], v[236:237], v[100:101] op_sel_hi:[1,0]
	v_pk_mul_f32 v[170:171], v[238:239], v[100:101] op_sel:[0,1]
	v_pk_fma_f32 v[168:169], v[240:241], v[102:103], v[168:169] op_sel_hi:[1,0,1]
	v_pk_fma_f32 v[170:171], v[242:243], v[102:103], v[170:171] op_sel:[0,1,0]
	v_pk_fma_f32 v[168:169], v[244:245], v[104:105], v[168:169] op_sel_hi:[1,0,1]
	v_pk_fma_f32 v[170:171], v[246:247], v[104:105], v[170:171] op_sel:[0,1,0]
	v_pk_fma_f32 v[168:169], v[248:249], v[106:107], v[168:169] op_sel_hi:[1,0,1]
	v_pk_fma_f32 v[170:171], v[250:251], v[106:107], v[170:171] op_sel:[0,1,0]
	ds_read_b128 v[100:103], v252 offset:17936
	ds_read_b128 v[104:107], v252 offset:18016
	v_pk_add_f32 v[168:169], v[168:169], v[170:171]
	s_waitcnt lgkmcnt(10)
	v_pk_mul_f32 v[236:237], v[236:237], v[108:109] op_sel_hi:[1,0]
	v_pk_mul_f32 v[238:239], v[238:239], v[108:109] op_sel:[0,1]
	v_pk_mul_f32 v[240:241], v[240:241], v[110:111] op_sel_hi:[1,0]
	v_pk_mul_f32 v[242:243], v[242:243], v[110:111] op_sel:[0,1]
	v_pk_mul_f32 v[244:245], v[244:245], v[112:113] op_sel_hi:[1,0]
	v_pk_mul_f32 v[246:247], v[246:247], v[112:113] op_sel:[0,1]
	v_pk_mul_f32 v[248:249], v[248:249], v[114:115] op_sel_hi:[1,0]
	v_pk_mul_f32 v[250:251], v[250:251], v[114:115] op_sel:[0,1]
	v_add_f32_dpp v168, v168, v168 quad_perm:[1,0,3,2] row_mask:0xf bank_mask:0xf bound_ctrl:1
	v_add_f32_dpp v169, v169, v169 quad_perm:[1,0,3,2] row_mask:0xf bank_mask:0xf bound_ctrl:1
	ds_read_b128 v[108:111], v252 offset:17920
	v_add_f32_dpp v168, v168, v168 quad_perm:[2,3,0,1] row_mask:0xf bank_mask:0xf bound_ctrl:1
	v_add_f32_dpp v169, v169, v169 quad_perm:[2,3,0,1] row_mask:0xf bank_mask:0xf bound_ctrl:1
	ds_read_b128 v[112:115], v252 offset:18000
	v_add_f32_dpp v168, v168, v168 row_half_mirror row_mask:0xf bank_mask:0xf bound_ctrl:1
	v_add_f32_dpp v169, v169, v169 row_half_mirror row_mask:0xf bank_mask:0xf bound_ctrl:1
	s_waitcnt lgkmcnt(10)
; #define LAS __attribute__((address_space(3)))
; template <int CTRL> __device__ __forceinline__ float dppf(float v) { return __builtin_bit_cast(float, __builtin_amdgcn_update_dpp(0, __builtin_bit_cast(int, v), CTRL, 0xF, 0xF, true)); }
; #define LO2(v) __builtin_shufflevector(v, v, 0, 1)
; #define HI2(v) __builtin_shufflevector(v, v, 2, 3)
; __device__ __forceinline__ void phase_scan(const Args& a, LAS unsigned char* lds) {
;     ...
;                 for (int s = 0; s < TC; ++s) {
;                     const LAS float* o = obase + (s + 1) * 320;
;                     const f32x4 now = *(const LAS f32x4*)(o), noa = *(const LAS f32x4*)(o + 4), nob = *(const LAS f32x4*)(o + 8), nok = *(const LAS f32x4*)(o + 12), norr = *(const LAS f32x4*)(o + 16);
;                     const f32x2 nvv = *(const LAS f32x2*)(vbase + (s + 1) * 64);
;                     const f32x2 p = pkfma_b<1>(C3, HI2(oa), pkfma_b<0>(C2, HI2(oa), pkfma_b<1>(C1, LO2(oa), pkmul_b<0>(C0, LO2(oa)))));
;                     float sa0 = p.x, sa1 = p.y;
;                     sa0 = reduce16(sa0); asm volatile("" : "+v"(sa0)); sa1 = reduce16(sa1);
;                     const f32x2 sap = {sa0, sa1};
;                     C0 = pkfma_b<0>(vv, LO2(ok), pkfma_b<0>(sap, LO2(ob), pkmul_b<0>(C0, LO2(ow))));
;                     C1 = pkfma_b<1>(vv, LO2(ok), pkfma_b<1>(sap, LO2(ob), pkmul_b<1>(C1, LO2(ow))));
;                     C2 = pkfma_b<0>(vv, HI2(ok), pkfma_b<0>(sap, HI2(ob), pkmul_b<0>(C2, HI2(ow))));
;                     C3 = pkfma_b<1>(vv, HI2(ok), pkfma_b<1>(sap, HI2(ob), pkmul_b<1>(C3, HI2(ow))));
;                     const f32x2 q = pkfma_b<1>(C3, HI2(orr), pkfma_b<0>(C2, HI2(orr), pkfma_b<1>(C1, LO2(orr), pkmul_b<0>(C0, LO2(orr)))));
;                     float y0 = q.x, y1 = q.y;
;                     y0 += dppf<0xB1>(y0); y1 += dppf<0xB1>(y1);
;                     *(LAS f32x2*)(yb + ((s * 32 + (r0 >> 1)) * 8 + ((lane >> 1) & 7)) * 2) = (f32x2){y0, y1};
;                     ow = now; oa = noa; ob = nob; ok = nok; orr = norr; vv = nvv;
;                 }
	v_pk_fma_f32 v[236:237], v[168:169], v[116:117], v[236:237] op_sel_hi:[1,0,1]
	v_pk_fma_f32 v[238:239], v[168:169], v[116:117], v[238:239] op_sel:[0,1,0]
	v_pk_fma_f32 v[240:241], v[168:169], v[118:119], v[240:241] op_sel_hi:[1,0,1]
	v_pk_fma_f32 v[242:243], v[168:169], v[118:119], v[242:243] op_sel:[0,1,0]
	v_pk_fma_f32 v[244:245], v[168:169], v[120:121], v[244:245] op_sel_hi:[1,0,1]
	v_pk_fma_f32 v[246:247], v[168:169], v[120:121], v[246:247] op_sel:[0,1,0]
	v_pk_fma_f32 v[248:249], v[168:169], v[122:123], v[248:249] op_sel_hi:[1,0,1]
	v_pk_fma_f32 v[250:251], v[168:169], v[122:123], v[250:251] op_sel:[0,1,0]
	ds_read_b128 v[116:119], v252 offset:17952
	ds_read_b128 v[120:123], v252 offset:18032
	s_waitcnt lgkmcnt(9)
	v_pk_fma_f32 v[236:237], v[166:167], v[124:125], v[236:237] op_sel_hi:[1,0,1]
	v_pk_fma_f32 v[238:239], v[166:167], v[124:125], v[238:239] op_sel:[0,1,0]
	v_pk_fma_f32 v[240:241], v[166:167], v[126:127], v[240:241] op_sel_hi:[1,0,1]
	v_pk_fma_f32 v[242:243], v[166:167], v[126:127], v[242:243] op_sel:[0,1,0]
	v_pk_fma_f32 v[244:245], v[166:167], v[128:129], v[244:245] op_sel_hi:[1,0,1]
	v_pk_fma_f32 v[246:247], v[166:167], v[128:129], v[246:247] op_sel:[0,1,0]
	v_pk_fma_f32 v[248:249], v[166:167], v[130:131], v[248:249] op_sel_hi:[1,0,1]
	v_pk_fma_f32 v[250:251], v[166:167], v[130:131], v[250:251] op_sel:[0,1,0]
	ds_read_b128 v[124:127], v252 offset:17968
	ds_read_b128 v[128:131], v252 offset:18048
	ds_read_b64 v[166:167], v253 offset:3584
	s_waitcnt lgkmcnt(10)
	v_pk_mul_f32 v[172:173], v[236:237], v[132:133] op_sel_hi:[1,0]
	v_pk_mul_f32 v[174:175], v[238:239], v[132:133] op_sel:[0,1]
	v_pk_fma_f32 v[172:173], v[240:241], v[134:135], v[172:173] op_sel_hi:[1,0,1]
	v_pk_fma_f32 v[174:175], v[242:243], v[134:135], v[174:175] op_sel:[0,1,0]
	v_pk_fma_f32 v[172:173], v[244:245], v[136:137], v[172:173] op_sel_hi:[1,0,1]
	v_pk_fma_f32 v[174:175], v[246:247], v[136:137], v[174:175] op_sel:[0,1,0]
	v_pk_fma_f32 v[172:173], v[248:249], v[138:139], v[172:173] op_sel_hi:[1,0,1]
	v_pk_fma_f32 v[174:175], v[250:251], v[138:139], v[174:175] op_sel:[0,1,0]
	ds_read_b128 v[132:135], v252 offset:17984
	ds_read_b128 v[136:139], v252 offset:18064
	v_pk_add_f32 v[172:173], v[172:173], v[174:175]
	ds_write_b64 v254, v[172:173] offset:26624
	s_waitcnt lgkmcnt(10)
	v_pk_mul_f32 v[168:169], v[236:237], v[100:101] op_sel_hi:[1,0]
	v_pk_mul_f32 v[170:171], v[238:239], v[100:101] op_sel:[0,1]
	v_pk_fma_f32 v[168:169], v[240:241], v[102:103], v[168:169] op_sel_hi:[1,0,1]
	v_pk_fma_f32 v[170:171], v[242:243], v[102:103], v[170:171] op_sel:[0,1,0]
	v_pk_fma_f32 v[168:169], v[244:245], v[104:105], v[168:169] op_sel_hi:[1,0,1]
	v_pk_fma_f32 v[170:171], v[246:247], v[104:105], v[170:171] op_sel:[0,1,0]
	v_pk_fma_f32 v[168:169], v[248:249], v[106:107], v[168:169] op_sel_hi:[1,0,1]
	v_pk_fma_f32 v[170:171], v[250:251], v[106:107], v[170:171] op_sel:[0,1,0]
	ds_read_b128 v[100:103], v252 offset:19216
	ds_read_b128 v[104:107], v252 offset:19296
	v_pk_add_f32 v[168:169], v[168:169], v[170:171]
	s_waitcnt lgkmcnt(10)
	v_pk_mul_f32 v[236:237], v[236:237], v[108:109] op_sel_hi:[1,0]
	v_pk_mul_f32 v[238:239], v[238:239], v[108:109] op_sel:[0,1]
	v_pk_mul_f32 v[240:241], v[240:241], v[110:111] op_sel_hi:[1,0]
	v_pk_mul_f32 v[242:243], v[242:243], v[110:111] op_sel:[0,1]
	v_pk_mul_f32 v[244:245], v[244:245], v[112:113] op_sel_hi:[1,0]
	v_pk_mul_f32 v[246:247], v[246:247], v[112:113] op_sel:[0,1]
	v_pk_mul_f32 v[248:249], v[248:249], v[114:115] op_sel_hi:[1,0]
	v_pk_mul_f32 v[250:251], v[250:251], v[114:115] op_sel:[0,1]
	v_add_f32_dpp v168, v168, v168 quad_perm:[1,0,3,2] row_mask:0xf bank_mask:0xf bound_ctrl:1
	v_add_f32_dpp v169, v169, v169 quad_perm:[1,0,3,2] row_mask:0xf bank_mask:0xf bound_ctrl:1
	ds_read_b128 v[108:111], v252 offset:19200
	v_add_f32_dpp v168, v168, v168 quad_perm:[2,3,0,1] row_mask:0xf bank_mask:0xf bound_ctrl:1
	v_add_f32_dpp v169, v169, v169 quad_perm:[2,3,0,1] row_mask:0xf bank_mask:0xf bound_ctrl:1
	ds_read_b128 v[112:115], v252 offset:19280
	v_add_f32_dpp v168, v168, v168 row_half_mirror row_mask:0xf bank_mask:0xf bound_ctrl:1
	v_add_f32_dpp v169, v169, v169 row_half_mirror row_mask:0xf bank_mask:0xf bound_ctrl:1
	s_waitcnt lgkmcnt(10)
	v_pk_fma_f32 v[236:237], v[168:169], v[116:117], v[236:237] op_sel_hi:[1,0,1]
	v_pk_fma_f32 v[238:239], v[168:169], v[116:117], v[238:239] op_sel:[0,1,0]
	v_pk_fma_f32 v[240:241], v[168:169], v[118:119], v[240:241] op_sel_hi:[1,0,1]
	v_pk_fma_f32 v[242:243], v[168:169], v[118:119], v[242:243] op_sel:[0,1,0]
	v_pk_fma_f32 v[244:245], v[168:169], v[120:121], v[244:245] op_sel_hi:[1,0,1]
	v_pk_fma_f32 v[246:247], v[168:169], v[120:121], v[246:247] op_sel:[0,1,0]
	v_pk_fma_f32 v[248:249], v[168:169], v[122:123], v[248:249] op_sel_hi:[1,0,1]
	v_pk_fma_f32 v[250:251], v[168:169], v[122:123], v[250:251] op_sel:[0,1,0]
	ds_read_b128 v[116:119], v252 offset:19232
	ds_read_b128 v[120:123], v252 offset:19312
	s_waitcnt lgkmcnt(9)
	v_pk_fma_f32 v[236:237], v[166:167], v[124:125], v[236:237] op_sel_hi:[1,0,1]
	v_pk_fma_f32 v[238:239], v[166:167], v[124:125], v[238:239] op_sel:[0,1,0]
	v_pk_fma_f32 v[240:241], v[166:167], v[126:127], v[240:241] op_sel_hi:[1,0,1]
	v_pk_fma_f32 v[242:243], v[166:167], v[126:127], v[242:243] op_sel:[0,1,0]
	v_pk_fma_f32 v[244:245], v[166:167], v[128:129], v[244:245] op_sel_hi:[1,0,1]
	v_pk_fma_f32 v[246:247], v[166:167], v[128:129], v[246:247] op_sel:[0,1,0]
	v_pk_fma_f32 v[248:249], v[166:167], v[130:131], v[248:249] op_sel_hi:[1,0,1]
	v_pk_fma_f32 v[250:251], v[166:167], v[130:131], v[250:251] op_sel:[0,1,0]
	ds_read_b128 v[124:127], v252 offset:19248
	ds_read_b128 v[128:131], v252 offset:19328
	ds_read_b64 v[166:167], v253 offset:3840
	s_waitcnt lgkmcnt(10)
; #define LAS __attribute__((address_space(3)))
; template <int CTRL> __device__ __forceinline__ float dppf(float v) { return __builtin_bit_cast(float, __builtin_amdgcn_update_dpp(0, __builtin_bit_cast(int, v), CTRL, 0xF, 0xF, true)); }
; #define LO2(v) __builtin_shufflevector(v, v, 0, 1)
; #define HI2(v) __builtin_shufflevector(v, v, 2, 3)
; __device__ __forceinline__ void phase_scan(const Args& a, LAS unsigned char* lds) {
;     ...
;                 for (int s = 0; s < TC; ++s) {
;                     const LAS float* o = obase + (s + 1) * 320;
;                     const f32x4 now = *(const LAS f32x4*)(o), noa = *(const LAS f32x4*)(o + 4), nob = *(const LAS f32x4*)(o + 8), nok = *(const LAS f32x4*)(o + 12), norr = *(const LAS f32x4*)(o + 16);
;                     const f32x2 nvv = *(const LAS f32x2*)(vbase + (s + 1) * 64);
;                     const f32x2 p = pkfma_b<1>(C3, HI2(oa), pkfma_b<0>(C2, HI2(oa), pkfma_b<1>(C1, LO2(oa), pkmul_b<0>(C0, LO2(oa)))));
;                     float sa0 = p.x, sa1 = p.y;
;                     sa0 = reduce16(sa0); asm volatile("" : "+v"(sa0)); sa1 = reduce16(sa1);
;                     const f32x2 sap = {sa0, sa1};
;                     C0 = pkfma_b<0>(vv, LO2(ok), pkfma_b<0>(sap, LO2(ob), pkmul_b<0>(C0, LO2(ow))));
;                     C1 = pkfma_b<1>(vv, LO2(ok), pkfma_b<1>(sap, LO2(ob), pkmul_b<1>(C1, LO2(ow))));
;                     C2 = pkfma_b<0>(vv, HI2(ok), pkfma_b<0>(sap, HI2(ob), pkmul_b<0>(C2, HI2(ow))));
;                     C3 = pkfma_b<1>(vv, HI2(ok), pkfma_b<1>(sap, HI2(ob), pkmul_b<1>(C3, HI2(ow))));
;                     const f32x2 q = pkfma_b<1>(C3, HI2(orr), pkfma_b<0>(C2, HI2(orr), pkfma_b<1>(C1, LO2(orr), pkmul_b<0>(C0, LO2(orr)))));
;                     float y0 = q.x, y1 = q.y;
;                     y0 += dppf<0xB1>(y0); y1 += dppf<0xB1>(y1);
;                     *(LAS f32x2*)(yb + ((s * 32 + (r0 >> 1)) * 8 + ((lane >> 1) & 7)) * 2) = (f32x2){y0, y1};
;                     ow = now; oa = noa; ob = nob; ok = nok; orr = norr; vv = nvv;
;                 }
;             }
;             __syncthreads();
	v_pk_mul_f32 v[172:173], v[236:237], v[132:133] op_sel_hi:[1,0]
	v_pk_mul_f32 v[174:175], v[238:239], v[132:133] op_sel:[0,1]
	v_pk_fma_f32 v[172:173], v[240:241], v[134:135], v[172:173] op_sel_hi:[1,0,1]
	v_pk_fma_f32 v[174:175], v[242:243], v[134:135], v[174:175] op_sel:[0,1,0]
	v_pk_fma_f32 v[172:173], v[244:245], v[136:137], v[172:173] op_sel_hi:[1,0,1]
	v_pk_fma_f32 v[174:175], v[246:247], v[136:137], v[174:175] op_sel:[0,1,0]
	v_pk_fma_f32 v[172:173], v[248:249], v[138:139], v[172:173] op_sel_hi:[1,0,1]
	v_pk_fma_f32 v[174:175], v[250:251], v[138:139], v[174:175] op_sel:[0,1,0]
	ds_read_b128 v[132:135], v252 offset:19264
	ds_read_b128 v[136:139], v252 offset:19344
	v_pk_add_f32 v[172:173], v[172:173], v[174:175]
	ds_write_b64 v254, v[172:173] offset:28672
	s_waitcnt lgkmcnt(10)
	v_pk_mul_f32 v[168:169], v[236:237], v[100:101] op_sel_hi:[1,0]
	v_pk_mul_f32 v[170:171], v[238:239], v[100:101] op_sel:[0,1]
	v_pk_fma_f32 v[168:169], v[240:241], v[102:103], v[168:169] op_sel_hi:[1,0,1]
	v_pk_fma_f32 v[170:171], v[242:243], v[102:103], v[170:171] op_sel:[0,1,0]
	v_pk_fma_f32 v[168:169], v[244:245], v[104:105], v[168:169] op_sel_hi:[1,0,1]
	v_pk_fma_f32 v[170:171], v[246:247], v[104:105], v[170:171] op_sel:[0,1,0]
	v_pk_fma_f32 v[168:169], v[248:249], v[106:107], v[168:169] op_sel_hi:[1,0,1]
	v_pk_fma_f32 v[170:171], v[250:251], v[106:107], v[170:171] op_sel:[0,1,0]
	ds_read_b128 v[100:103], v176 offset:16
	ds_read_b128 v[104:107], v176 offset:96
	v_pk_add_f32 v[168:169], v[168:169], v[170:171]
	s_waitcnt lgkmcnt(10)
	v_pk_mul_f32 v[236:237], v[236:237], v[108:109] op_sel_hi:[1,0]
	v_pk_mul_f32 v[238:239], v[238:239], v[108:109] op_sel:[0,1]
	v_pk_mul_f32 v[240:241], v[240:241], v[110:111] op_sel_hi:[1,0]
	v_pk_mul_f32 v[242:243], v[242:243], v[110:111] op_sel:[0,1]
	v_pk_mul_f32 v[244:245], v[244:245], v[112:113] op_sel_hi:[1,0]
	v_pk_mul_f32 v[246:247], v[246:247], v[112:113] op_sel:[0,1]
	v_pk_mul_f32 v[248:249], v[248:249], v[114:115] op_sel_hi:[1,0]
	v_pk_mul_f32 v[250:251], v[250:251], v[114:115] op_sel:[0,1]
	v_add_f32_dpp v168, v168, v168 quad_perm:[1,0,3,2] row_mask:0xf bank_mask:0xf bound_ctrl:1
	v_add_f32_dpp v169, v169, v169 quad_perm:[1,0,3,2] row_mask:0xf bank_mask:0xf bound_ctrl:1
	ds_read_b128 v[108:111], v176
	v_add_f32_dpp v168, v168, v168 quad_perm:[2,3,0,1] row_mask:0xf bank_mask:0xf bound_ctrl:1
	v_add_f32_dpp v169, v169, v169 quad_perm:[2,3,0,1] row_mask:0xf bank_mask:0xf bound_ctrl:1
	ds_read_b128 v[112:115], v176 offset:80
	v_add_f32_dpp v168, v168, v168 row_half_mirror row_mask:0xf bank_mask:0xf bound_ctrl:1
	v_add_f32_dpp v169, v169, v169 row_half_mirror row_mask:0xf bank_mask:0xf bound_ctrl:1
	s_waitcnt lgkmcnt(10)
	v_pk_fma_f32 v[236:237], v[168:169], v[116:117], v[236:237] op_sel_hi:[1,0,1]
	v_pk_fma_f32 v[238:239], v[168:169], v[116:117], v[238:239] op_sel:[0,1,0]
	v_pk_fma_f32 v[240:241], v[168:169], v[118:119], v[240:241] op_sel_hi:[1,0,1]
	v_pk_fma_f32 v[242:243], v[168:169], v[118:119], v[242:243] op_sel:[0,1,0]
	v_pk_fma_f32 v[244:245], v[168:169], v[120:121], v[244:245] op_sel_hi:[1,0,1]
	v_pk_fma_f32 v[246:247], v[168:169], v[120:121], v[246:247] op_sel:[0,1,0]
	v_pk_fma_f32 v[248:249], v[168:169], v[122:123], v[248:249] op_sel_hi:[1,0,1]
	v_pk_fma_f32 v[250:251], v[168:169], v[122:123], v[250:251] op_sel:[0,1,0]
	ds_read_b128 v[116:119], v176 offset:32
	ds_read_b128 v[120:123], v176 offset:112
	s_waitcnt lgkmcnt(9)
	v_pk_fma_f32 v[236:237], v[166:167], v[124:125], v[236:237] op_sel_hi:[1,0,1]
	v_pk_fma_f32 v[238:239], v[166:167], v[124:125], v[238:239] op_sel:[0,1,0]
	v_pk_fma_f32 v[240:241], v[166:167], v[126:127], v[240:241] op_sel_hi:[1,0,1]
	v_pk_fma_f32 v[242:243], v[166:167], v[126:127], v[242:243] op_sel:[0,1,0]
	v_pk_fma_f32 v[244:245], v[166:167], v[128:129], v[244:245] op_sel_hi:[1,0,1]
	v_pk_fma_f32 v[246:247], v[166:167], v[128:129], v[246:247] op_sel:[0,1,0]
	v_pk_fma_f32 v[248:249], v[166:167], v[130:131], v[248:249] op_sel_hi:[1,0,1]
	v_pk_fma_f32 v[250:251], v[166:167], v[130:131], v[250:251] op_sel:[0,1,0]
	ds_read_b128 v[124:127], v176 offset:48
	ds_read_b128 v[128:131], v176 offset:128
	ds_read_b64 v[166:167], v177
	s_waitcnt lgkmcnt(10)
	v_pk_mul_f32 v[172:173], v[236:237], v[132:133] op_sel_hi:[1,0]
	v_pk_mul_f32 v[174:175], v[238:239], v[132:133] op_sel:[0,1]
	v_pk_fma_f32 v[172:173], v[240:241], v[134:135], v[172:173] op_sel_hi:[1,0,1]
	v_pk_fma_f32 v[174:175], v[242:243], v[134:135], v[174:175] op_sel:[0,1,0]
	v_pk_fma_f32 v[172:173], v[244:245], v[136:137], v[172:173] op_sel_hi:[1,0,1]
	v_pk_fma_f32 v[174:175], v[246:247], v[136:137], v[174:175] op_sel:[0,1,0]
	v_pk_fma_f32 v[172:173], v[248:249], v[138:139], v[172:173] op_sel_hi:[1,0,1]
	v_pk_fma_f32 v[174:175], v[250:251], v[138:139], v[174:175] op_sel:[0,1,0]
	ds_read_b128 v[132:135], v176 offset:64
	ds_read_b128 v[136:139], v176 offset:144
	v_pk_add_f32 v[172:173], v[172:173], v[174:175]
	ds_write_b64 v254, v[172:173] offset:30720
	s_waitcnt lgkmcnt(0)
	s_barrier
	v_add_u32_e32 v252, s42, v252
	v_add_u32_e32 v253, s43, v253
	v_add_u32_e32 v254, s44, v254
	v_subrev_u32_e32 v176, s42, v176
	v_subrev_u32_e32 v177, s43, v177
	s_sub_i32 s42, 0, s42
	s_sub_i32 s43, 0, s43
	s_sub_i32 s44, 0, s44
	s_add_i32 s23, s23, 1
	s_cmpk_lg_u32 s23, 0x100
	s_cbranch_scc1 .LW_rloop
	s_setprio 0
	s_branch .LBB0_2062

; __device__ __forceinline__ int opaque_tid() { int t = threadIdx.x; asm volatile("" : "+v"(t)); return t; }
; __device__ __forceinline__ unsigned cvt_pk_bf16(float lo, float hi) { unsigned r; asm volatile("v_cvt_pk_bf16_f32 %0, %1, %2" : "=v"(r) : "v"(lo), "v"(hi)); return r; }
; __device__ __forceinline__ void phase_norm_mod(const float* x, const float* mod_shift, const float* mod_scale, bf16_t* H, int) {
;     const int tid = opaque_tid(), lane = tid & 63, wave = tid >> 6;
;     const int gw = blockIdx.x * NWAVES + wave, NGW = gridDim.x * NWAVES;
;     constexpr int NR = 4;
;     for (int m0 = gw; m0 < M; m0 += NR * NGW) {
;         f32x4 v[NR][4];
; #pragma unroll
;         for (int r = 0; r < NR; ++r) { const int m = M - 1 - (m0 + r * NGW < M ? m0 + r * NGW : m0); const f32x4* xr = (const f32x4*)(x + (size_t)m * D) + lane;
; #pragma unroll
;             for (int j = 0; j < 4; ++j) v[r][j] = xr[64 * j]; }
; #pragma unroll
;         for (int r = 0; r < NR; ++r) { const int m = M - 1 - (m0 + r * NGW); if (m >= 0) {
;             const int b = m >> 12; float s = 0.f;
; #pragma unroll
;             for (int j = 0; j < 4; ++j) s += (v[r][j].x * v[r][j].x + v[r][j].y * v[r][j].y) + (v[r][j].z * v[r][j].z + v[r][j].w * v[r][j].w);
;             const float rstd = 1.0f / sqrtf(wave_sum(s) * (1.f / D) + 1e-6f);
;             const f32x4* sh = (const f32x4*)(mod_shift + (size_t)b * 6144) + lane;
;             const f32x4* sc = (const f32x4*)(mod_scale + (size_t)b * 6144) + lane;
;             u32x2* o = (u32x2*)(H + (size_t)m * D) + lane;
; #pragma unroll
;             for (int j = 0; j < 4; ++j) { const f32x4 a = sh[64 * j], c = sc[64 * j]; const f32x4 h = v[r][j] * rstd * (c + 1.0f) + a;
;                 u32x2 w; w.x = cvt_pk_bf16(h.x, h.y); w.y = cvt_pk_bf16(h.z, h.w); o[64 * j] = w; } } }
.LBB0_2203:
	s_cmp_lt_i32 s90, 13
	s_cselect_b64 s[8:9], -1, 0
	s_and_b64 s[0:1], s[8:9], s[0:1]
	s_andn2_b64 vcc, exec, s[0:1]
	s_cbranch_vccnz .LBB0_2214
	s_mov_b64 s[10:11], exec
	v_lshrrev_b32_e32 v176, 6, v180
	v_and_b32_e32 v177, 63, v180
	v_readfirstlane_b32 s0, v176
	v_lshlrev_b32_e32 v176, 4, v177
	v_lshlrev_b32_e32 v177, 3, v177
	v_mov_b32_e32 v170, 0x358637bd
	v_mov_b32_e32 v171, 0x260
	s_lshl_b32 s1, s24, 3
	s_add_i32 s0, s0, s1
	s_lshl_b32 s2, s28, 3
	s_mul_i32 s1, s2, 3
	s_mov_b32 s18, s0
	s_add_i32 s19, s0, s2
	s_add_i32 s20, s19, s2
	s_cmp_lt_u32 s0, 0x10000
	s_cbranch_scc0 .LNb_done
	s_cmp_lt_u32 s18, 0x10000
	s_cselect_b32 s3, s18, s0
	s_sub_u32 s3, 0xffff, s3
	s_lshl_b32 s4, s3, 12
	s_add_u32 s6, s86, s4
	s_addc_u32 s7, s87, 0
	s_lshr_b32 s4, s3, 12
	s_mul_i32 s4, s4, 0x6000
	s_add_u32 s12, s88, s4
	s_addc_u32 s13, s89, 0
	s_add_u32 s14, s12, 0x164000
	s_addc_u32 s15, s13, 0
	s_add_u32 s12, s12, 0x163000
	s_addc_u32 s13, s13, 0
	global_load_dwordx4 v[0:3], v176, s[6:7]
	global_load_dwordx4 v[4:7], v176, s[6:7] offset:1024
	global_load_dwordx4 v[8:11], v176, s[6:7] offset:2048
	global_load_dwordx4 v[12:15], v176, s[6:7] offset:3072
	global_load_dwordx4 v[16:19], v176, s[14:15]
	global_load_dwordx4 v[20:23], v176, s[14:15] offset:1024
	global_load_dwordx4 v[24:27], v176, s[14:15] offset:2048
	global_load_dwordx4 v[28:31], v176, s[14:15] offset:3072
	global_load_dwordx4 v[32:35], v176, s[12:13]
	global_load_dwordx4 v[36:39], v176, s[12:13] offset:1024
	global_load_dwordx4 v[40:43], v176, s[12:13] offset:2048
	global_load_dwordx4 v[44:47], v176, s[12:13] offset:3072
	s_cmp_lt_u32 s19, 0x10000
	s_cselect_b32 s3, s19, s0
	s_sub_u32 s3, 0xffff, s3
	s_lshl_b32 s4, s3, 12
	s_add_u32 s6, s86, s4
	s_addc_u32 s7, s87, 0
	s_lshr_b32 s4, s3, 12
	s_mul_i32 s4, s4, 0x6000
	s_add_u32 s12, s88, s4
	s_addc_u32 s13, s89, 0
	s_add_u32 s14, s12, 0x164000
	s_addc_u32 s15, s13, 0
	s_add_u32 s12, s12, 0x163000
	s_addc_u32 s13, s13, 0
	global_load_dwordx4 v[48:51], v176, s[6:7]
	global_load_dwordx4 v[52:55], v176, s[6:7] offset:1024
	global_load_dwordx4 v[56:59], v176, s[6:7] offset:2048
	global_load_dwordx4 v[60:63], v176, s[6:7] offset:3072
	global_load_dwordx4 v[64:67], v176, s[14:15]
	global_load_dwordx4 v[68:71], v176, s[14:15] offset:1024
	global_load_dwordx4 v[72:75], v176, s[14:15] offset:2048
	global_load_dwordx4 v[76:79], v176, s[14:15] offset:3072
	global_load_dwordx4 v[80:83], v176, s[12:13]
	global_load_dwordx4 v[84:87], v176, s[12:13] offset:1024
	global_load_dwordx4 v[88:91], v176, s[12:13] offset:2048
	global_load_dwordx4 v[92:95], v176, s[12:13] offset:3072
	s_cmp_lt_u32 s20, 0x10000
	s_cselect_b32 s3, s20, s0
	s_sub_u32 s3, 0xffff, s3
	s_lshl_b32 s4, s3, 12
	s_add_u32 s6, s86, s4
	s_addc_u32 s7, s87, 0
	s_lshr_b32 s4, s3, 12
	s_mul_i32 s4, s4, 0x6000
	s_add_u32 s12, s88, s4
	s_addc_u32 s13, s89, 0
	s_add_u32 s14, s12, 0x164000
	s_addc_u32 s15, s13, 0
	s_add_u32 s12, s12, 0x163000
	s_addc_u32 s13, s13, 0
	global_load_dwordx4 v[96:99], v176, s[6:7]
	global_load_dwordx4 v[100:103], v176, s[6:7] offset:1024
	global_load_dwordx4 v[104:107], v176, s[6:7] offset:2048
	global_load_dwordx4 v[108:111], v176, s[6:7] offset:3072
	global_load_dwordx4 v[112:115], v176, s[14:15]
	global_load_dwordx4 v[116:119], v176, s[14:15] offset:1024
	global_load_dwordx4 v[120:123], v176, s[14:15] offset:2048
	global_load_dwordx4 v[124:127], v176, s[14:15] offset:3072
	global_load_dwordx4 v[128:131], v176, s[12:13]
	global_load_dwordx4 v[132:135], v176, s[12:13] offset:1024
	global_load_dwordx4 v[136:139], v176, s[12:13] offset:2048
	global_load_dwordx4 v[140:143], v176, s[12:13] offset:3072
.LNb_loop:
	s_cmp_lt_u32 s18, 0x10000
	s_cbranch_scc0 .LNb_done
	s_waitcnt vmcnt(24)
	v_pk_mul_f32 v[172:173], v[0:1], v[0:1]
	v_pk_mul_f32 v[174:175], v[2:3], v[2:3]
	v_pk_fma_f32 v[172:173], v[4:5], v[4:5], v[172:173]
	v_pk_fma_f32 v[174:175], v[6:7], v[6:7], v[174:175]
	v_pk_fma_f32 v[172:173], v[8:9], v[8:9], v[172:173]
	v_pk_fma_f32 v[174:175], v[10:11], v[10:11], v[174:175]
	v_pk_fma_f32 v[172:173], v[12:13], v[12:13], v[172:173]
	v_pk_fma_f32 v[174:175], v[14:15], v[14:15], v[174:175]
	v_pk_add_f32 v[172:173], v[172:173], v[174:175]
	s_sub_u32 s3, 0xffff, s18
	s_lshl_b32 s4, s3, 11
	v_add_f32_e32 v160, v172, v173
	s_add_u32 s16, s88, s4
	s_addc_u32 s17, s89, 0
	s_nop 1
	v_add_f32_dpp v160, v160, v160 quad_perm:[1,0,3,2] row_mask:0xf bank_mask:0xf bound_ctrl:1
	s_nop 1
	v_add_f32_dpp v160, v160, v160 quad_perm:[2,3,0,1] row_mask:0xf bank_mask:0xf bound_ctrl:1
	s_nop 1
	v_add_f32_dpp v160, v160, v160 row_half_mirror row_mask:0xf bank_mask:0xf bound_ctrl:1
	s_nop 1
	v_add_f32_dpp v160, v160, v160 row_mirror row_mask:0xf bank_mask:0xf bound_ctrl:1
	s_add_u32 s16, s16, 0x3c00000
	s_addc_u32 s17, s17, 0
	v_readlane_b32 s4, v160, 0
	v_readlane_b32 s5, v160, 16
	v_readlane_b32 s21, v160, 32
	v_readlane_b32 s22, v160, 48
	s_nop 1
	v_mov_b32_e32 v160, s4
	v_add_f32_e32 v160, s5, v160
	v_add_f32_e32 v160, s21, v160
	v_add_f32_e32 v160, s22, v160
	v_fmamk_f32 v160, v160, 0x3a800000, v170
	s_mov_b32 s23, 0xf800000
	v_mul_f32_e32 v161, 0x4f800000, v160
	v_cmp_gt_f32_e32 vcc, s23, v160
	s_nop 1
	v_cndmask_b32_e32 v162, v160, v161, vcc
	v_sqrt_f32_e32 v164, v162
	s_nop 0
	v_add_u32_e32 v165, -1, v164
	v_add_u32_e32 v166, 1, v164
	v_fma_f32 v167, -v165, v164, v162
	v_fma_f32 v168, -v166, v164, v162
	v_cmp_ge_f32_e64 s[4:5], 0, v167
	s_nop 1
	v_cndmask_b32_e64 v164, v164, v165, s[4:5]
	v_cmp_lt_f32_e64 s[4:5], 0, v168
	s_nop 1
	v_cndmask_b32_e64 v164, v164, v166, s[4:5]
	v_mul_f32_e32 v165, 0x37800000, v164
	v_cndmask_b32_e32 v164, v164, v165, vcc
	v_cmp_class_f32_e32 vcc, v162, v171
; __device__ __forceinline__ unsigned cvt_pk_bf16(float lo, float hi) { unsigned r; asm volatile("v_cvt_pk_bf16_f32 %0, %1, %2" : "=v"(r) : "v"(lo), "v"(hi)); return r; }
; __device__ __forceinline__ void phase_norm_mod(const float* x, const float* mod_shift, const float* mod_scale, bf16_t* H, int) {
;     ...
;         for (int r = 0; r < NR; ++r) { const int m = M - 1 - (m0 + r * NGW < M ? m0 + r * NGW : m0); const f32x4* xr = (const f32x4*)(x + (size_t)m * D) + lane;
; #pragma unroll
;             for (int j = 0; j < 4; ++j) v[r][j] = xr[64 * j]; }
; #pragma unroll
;         for (int r = 0; r < NR; ++r) { const int m = M - 1 - (m0 + r * NGW); if (m >= 0) {
;             const int b = m >> 12; float s = 0.f;
; #pragma unroll
;             for (int j = 0; j < 4; ++j) s += (v[r][j].x * v[r][j].x + v[r][j].y * v[r][j].y) + (v[r][j].z * v[r][j].z + v[r][j].w * v[r][j].w);
;             const float rstd = 1.0f / sqrtf(wave_sum(s) * (1.f / D) + 1e-6f);
;             const f32x4* sh = (const f32x4*)(mod_shift + (size_t)b * 6144) + lane;
;             const f32x4* sc = (const f32x4*)(mod_scale + (size_t)b * 6144) + lane;
;             u32x2* o = (u32x2*)(H + (size_t)m * D) + lane;
; #pragma unroll
;             for (int j = 0; j < 4; ++j) { const f32x4 a = sh[64 * j], c = sc[64 * j]; const f32x4 h = v[r][j] * rstd * (c + 1.0f) + a;
;                 u32x2 w; w.x = cvt_pk_bf16(h.x, h.y); w.y = cvt_pk_bf16(h.z, h.w); o[64 * j] = w; } } }
	s_nop 1
	v_cndmask_b32_e32 v162, v164, v162, vcc
	v_div_scale_f32 v164, s[4:5], v162, v162, 1.0
	v_rcp_f32_e32 v165, v164
	v_div_scale_f32 v166, vcc, 1.0, v162, 1.0
	v_fma_f32 v167, -v164, v165, 1.0
	v_fmac_f32_e32 v165, v167, v165
	v_mul_f32_e32 v167, v166, v165
	v_fma_f32 v168, -v164, v167, v166
	v_fmac_f32_e32 v167, v168, v165
	v_fma_f32 v164, -v164, v167, v166
	v_div_fmas_f32 v164, v164, v165, v167
	v_div_fixup_f32 v162, v164, v162, 1.0
	v_pk_mul_f32 v[0:1], v[0:1], v[162:163] op_sel_hi:[1,0]
	v_pk_mul_f32 v[2:3], v[2:3], v[162:163] op_sel_hi:[1,0]
	v_pk_add_f32 v[16:17], v[16:17], 1.0 op_sel_hi:[1,0]
	v_pk_add_f32 v[18:19], v[18:19], 1.0 op_sel_hi:[1,0]
	v_pk_fma_f32 v[0:1], v[16:17], v[0:1], v[32:33]
	v_pk_fma_f32 v[2:3], v[18:19], v[2:3], v[34:35]
	v_cvt_pk_bf16_f32 v152, v0, v1
	v_cvt_pk_bf16_f32 v153, v2, v3
	v_pk_mul_f32 v[4:5], v[4:5], v[162:163] op_sel_hi:[1,0]
	v_pk_mul_f32 v[6:7], v[6:7], v[162:163] op_sel_hi:[1,0]
	v_pk_add_f32 v[20:21], v[20:21], 1.0 op_sel_hi:[1,0]
	v_pk_add_f32 v[22:23], v[22:23], 1.0 op_sel_hi:[1,0]
	v_pk_fma_f32 v[4:5], v[20:21], v[4:5], v[36:37]
	v_pk_fma_f32 v[6:7], v[22:23], v[6:7], v[38:39]
	v_cvt_pk_bf16_f32 v154, v4, v5
	v_cvt_pk_bf16_f32 v155, v6, v7
	v_pk_mul_f32 v[8:9], v[8:9], v[162:163] op_sel_hi:[1,0]
	v_pk_mul_f32 v[10:11], v[10:11], v[162:163] op_sel_hi:[1,0]
	v_pk_add_f32 v[24:25], v[24:25], 1.0 op_sel_hi:[1,0]
	v_pk_add_f32 v[26:27], v[26:27], 1.0 op_sel_hi:[1,0]
	v_pk_fma_f32 v[8:9], v[24:25], v[8:9], v[40:41]
	v_pk_fma_f32 v[10:11], v[26:27], v[10:11], v[42:43]
	v_cvt_pk_bf16_f32 v156, v8, v9
	v_cvt_pk_bf16_f32 v157, v10, v11
	v_pk_mul_f32 v[12:13], v[12:13], v[162:163] op_sel_hi:[1,0]
	v_pk_mul_f32 v[14:15], v[14:15], v[162:163] op_sel_hi:[1,0]
	v_pk_add_f32 v[28:29], v[28:29], 1.0 op_sel_hi:[1,0]
	v_pk_add_f32 v[30:31], v[30:31], 1.0 op_sel_hi:[1,0]
	v_pk_fma_f32 v[12:13], v[28:29], v[12:13], v[44:45]
	v_pk_fma_f32 v[14:15], v[30:31], v[14:15], v[46:47]
	v_cvt_pk_bf16_f32 v158, v12, v13
	v_cvt_pk_bf16_f32 v159, v14, v15
	global_store_dwordx2 v177, v[152:153], s[16:17]
	global_store_dwordx2 v177, v[154:155], s[16:17] offset:512
	global_store_dwordx2 v177, v[156:157], s[16:17] offset:1024
	global_store_dwordx2 v177, v[158:159], s[16:17] offset:1536
	s_add_i32 s18, s18, s1
	s_cmp_lt_u32 s18, 0x10000
	s_cselect_b32 s3, s18, s0
	s_sub_u32 s3, 0xffff, s3
	s_lshl_b32 s4, s3, 12
	s_add_u32 s6, s86, s4
	s_addc_u32 s7, s87, 0
	s_lshr_b32 s4, s3, 12
	s_mul_i32 s4, s4, 0x6000
	s_add_u32 s12, s88, s4
	s_addc_u32 s13, s89, 0
	s_add_u32 s14, s12, 0x164000
	s_addc_u32 s15, s13, 0
	s_add_u32 s12, s12, 0x163000
	s_addc_u32 s13, s13, 0
	global_load_dwordx4 v[0:3], v176, s[6:7]
	global_load_dwordx4 v[4:7], v176, s[6:7] offset:1024
	global_load_dwordx4 v[8:11], v176, s[6:7] offset:2048
	global_load_dwordx4 v[12:15], v176, s[6:7] offset:3072
	global_load_dwordx4 v[16:19], v176, s[14:15]
	global_load_dwordx4 v[20:23], v176, s[14:15] offset:1024
	global_load_dwordx4 v[24:27], v176, s[14:15] offset:2048
	global_load_dwordx4 v[28:31], v176, s[14:15] offset:3072
	global_load_dwordx4 v[32:35], v176, s[12:13]
	global_load_dwordx4 v[36:39], v176, s[12:13] offset:1024
	global_load_dwordx4 v[40:43], v176, s[12:13] offset:2048
	global_load_dwordx4 v[44:47], v176, s[12:13] offset:3072
	s_cmp_lt_u32 s19, 0x10000
	s_cbranch_scc0 .LNb_done
	s_waitcnt vmcnt(24)
	v_pk_mul_f32 v[172:173], v[48:49], v[48:49]
	v_pk_mul_f32 v[174:175], v[50:51], v[50:51]
	v_pk_fma_f32 v[172:173], v[52:53], v[52:53], v[172:173]
	v_pk_fma_f32 v[174:175], v[54:55], v[54:55], v[174:175]
	v_pk_fma_f32 v[172:173], v[56:57], v[56:57], v[172:173]
	v_pk_fma_f32 v[174:175], v[58:59], v[58:59], v[174:175]
	v_pk_fma_f32 v[172:173], v[60:61], v[60:61], v[172:173]
	v_pk_fma_f32 v[174:175], v[62:63], v[62:63], v[174:175]
	v_pk_add_f32 v[172:173], v[172:173], v[174:175]
	s_sub_u32 s3, 0xffff, s19
	s_lshl_b32 s4, s3, 11
	v_add_f32_e32 v160, v172, v173
	s_add_u32 s16, s88, s4
	s_addc_u32 s17, s89, 0
	s_nop 1
	v_add_f32_dpp v160, v160, v160 quad_perm:[1,0,3,2] row_mask:0xf bank_mask:0xf bound_ctrl:1
	s_nop 1
	v_add_f32_dpp v160, v160, v160 quad_perm:[2,3,0,1] row_mask:0xf bank_mask:0xf bound_ctrl:1
	s_nop 1
	v_add_f32_dpp v160, v160, v160 row_half_mirror row_mask:0xf bank_mask:0xf bound_ctrl:1
	s_nop 1
	v_add_f32_dpp v160, v160, v160 row_mirror row_mask:0xf bank_mask:0xf bound_ctrl:1
	s_add_u32 s16, s16, 0x3c00000
	s_addc_u32 s17, s17, 0
	v_readlane_b32 s4, v160, 0
	v_readlane_b32 s5, v160, 16
	v_readlane_b32 s21, v160, 32
	v_readlane_b32 s22, v160, 48
	s_nop 1
	v_mov_b32_e32 v160, s4
	v_add_f32_e32 v160, s5, v160
	v_add_f32_e32 v160, s21, v160
	v_add_f32_e32 v160, s22, v160
	v_fmamk_f32 v160, v160, 0x3a800000, v170
	s_mov_b32 s23, 0xf800000
	v_mul_f32_e32 v161, 0x4f800000, v160
	v_cmp_gt_f32_e32 vcc, s23, v160
	s_nop 1
	v_cndmask_b32_e32 v162, v160, v161, vcc
	v_sqrt_f32_e32 v164, v162
	s_nop 0
	v_add_u32_e32 v165, -1, v164
	v_add_u32_e32 v166, 1, v164
	v_fma_f32 v167, -v165, v164, v162
	v_fma_f32 v168, -v166, v164, v162
	v_cmp_ge_f32_e64 s[4:5], 0, v167
	s_nop 1
	v_cndmask_b32_e64 v164, v164, v165, s[4:5]
	v_cmp_lt_f32_e64 s[4:5], 0, v168
	s_nop 1
	v_cndmask_b32_e64 v164, v164, v166, s[4:5]
	v_mul_f32_e32 v165, 0x37800000, v164
	v_cndmask_b32_e32 v164, v164, v165, vcc
	v_cmp_class_f32_e32 vcc, v162, v171
	s_nop 1
	v_cndmask_b32_e32 v162, v164, v162, vcc
	v_div_scale_f32 v164, s[4:5], v162, v162, 1.0
	v_rcp_f32_e32 v165, v164
	v_div_scale_f32 v166, vcc, 1.0, v162, 1.0
	v_fma_f32 v167, -v164, v165, 1.0
	v_fmac_f32_e32 v165, v167, v165
	v_mul_f32_e32 v167, v166, v165
	v_fma_f32 v168, -v164, v167, v166
	v_fmac_f32_e32 v167, v168, v165
	v_fma_f32 v164, -v164, v167, v166
; __device__ __forceinline__ unsigned cvt_pk_bf16(float lo, float hi) { unsigned r; asm volatile("v_cvt_pk_bf16_f32 %0, %1, %2" : "=v"(r) : "v"(lo), "v"(hi)); return r; }
; __device__ __forceinline__ void phase_norm_mod(const float* x, const float* mod_shift, const float* mod_scale, bf16_t* H, int) {
;     ...
;         for (int r = 0; r < NR; ++r) { const int m = M - 1 - (m0 + r * NGW < M ? m0 + r * NGW : m0); const f32x4* xr = (const f32x4*)(x + (size_t)m * D) + lane;
; #pragma unroll
;             for (int j = 0; j < 4; ++j) v[r][j] = xr[64 * j]; }
; #pragma unroll
;         for (int r = 0; r < NR; ++r) { const int m = M - 1 - (m0 + r * NGW); if (m >= 0) {
;             const int b = m >> 12; float s = 0.f;
; #pragma unroll
;             for (int j = 0; j < 4; ++j) s += (v[r][j].x * v[r][j].x + v[r][j].y * v[r][j].y) + (v[r][j].z * v[r][j].z + v[r][j].w * v[r][j].w);
;             const float rstd = 1.0f / sqrtf(wave_sum(s) * (1.f / D) + 1e-6f);
;             const f32x4* sh = (const f32x4*)(mod_shift + (size_t)b * 6144) + lane;
;             const f32x4* sc = (const f32x4*)(mod_scale + (size_t)b * 6144) + lane;
;             u32x2* o = (u32x2*)(H + (size_t)m * D) + lane;
; #pragma unroll
;             for (int j = 0; j < 4; ++j) { const f32x4 a = sh[64 * j], c = sc[64 * j]; const f32x4 h = v[r][j] * rstd * (c + 1.0f) + a;
;                 u32x2 w; w.x = cvt_pk_bf16(h.x, h.y); w.y = cvt_pk_bf16(h.z, h.w); o[64 * j] = w; } } }
	v_div_fmas_f32 v164, v164, v165, v167
	v_div_fixup_f32 v162, v164, v162, 1.0
	v_pk_mul_f32 v[48:49], v[48:49], v[162:163] op_sel_hi:[1,0]
	v_pk_mul_f32 v[50:51], v[50:51], v[162:163] op_sel_hi:[1,0]
	v_pk_add_f32 v[64:65], v[64:65], 1.0 op_sel_hi:[1,0]
	v_pk_add_f32 v[66:67], v[66:67], 1.0 op_sel_hi:[1,0]
	v_pk_fma_f32 v[48:49], v[64:65], v[48:49], v[80:81]
	v_pk_fma_f32 v[50:51], v[66:67], v[50:51], v[82:83]
	v_cvt_pk_bf16_f32 v152, v48, v49
	v_cvt_pk_bf16_f32 v153, v50, v51
	v_pk_mul_f32 v[52:53], v[52:53], v[162:163] op_sel_hi:[1,0]
	v_pk_mul_f32 v[54:55], v[54:55], v[162:163] op_sel_hi:[1,0]
	v_pk_add_f32 v[68:69], v[68:69], 1.0 op_sel_hi:[1,0]
	v_pk_add_f32 v[70:71], v[70:71], 1.0 op_sel_hi:[1,0]
	v_pk_fma_f32 v[52:53], v[68:69], v[52:53], v[84:85]
	v_pk_fma_f32 v[54:55], v[70:71], v[54:55], v[86:87]
	v_cvt_pk_bf16_f32 v154, v52, v53
	v_cvt_pk_bf16_f32 v155, v54, v55
	v_pk_mul_f32 v[56:57], v[56:57], v[162:163] op_sel_hi:[1,0]
	v_pk_mul_f32 v[58:59], v[58:59], v[162:163] op_sel_hi:[1,0]
	v_pk_add_f32 v[72:73], v[72:73], 1.0 op_sel_hi:[1,0]
	v_pk_add_f32 v[74:75], v[74:75], 1.0 op_sel_hi:[1,0]
	v_pk_fma_f32 v[56:57], v[72:73], v[56:57], v[88:89]
	v_pk_fma_f32 v[58:59], v[74:75], v[58:59], v[90:91]
	v_cvt_pk_bf16_f32 v156, v56, v57
	v_cvt_pk_bf16_f32 v157, v58, v59
	v_pk_mul_f32 v[60:61], v[60:61], v[162:163] op_sel_hi:[1,0]
	v_pk_mul_f32 v[62:63], v[62:63], v[162:163] op_sel_hi:[1,0]
	v_pk_add_f32 v[76:77], v[76:77], 1.0 op_sel_hi:[1,0]
	v_pk_add_f32 v[78:79], v[78:79], 1.0 op_sel_hi:[1,0]
	v_pk_fma_f32 v[60:61], v[76:77], v[60:61], v[92:93]
	v_pk_fma_f32 v[62:63], v[78:79], v[62:63], v[94:95]
	v_cvt_pk_bf16_f32 v158, v60, v61
	v_cvt_pk_bf16_f32 v159, v62, v63
	global_store_dwordx2 v177, v[152:153], s[16:17]
	global_store_dwordx2 v177, v[154:155], s[16:17] offset:512
	global_store_dwordx2 v177, v[156:157], s[16:17] offset:1024
	global_store_dwordx2 v177, v[158:159], s[16:17] offset:1536
	s_add_i32 s19, s19, s1
	s_cmp_lt_u32 s19, 0x10000
	s_cselect_b32 s3, s19, s0
	s_sub_u32 s3, 0xffff, s3
	s_lshl_b32 s4, s3, 12
	s_add_u32 s6, s86, s4
	s_addc_u32 s7, s87, 0
	s_lshr_b32 s4, s3, 12
	s_mul_i32 s4, s4, 0x6000
	s_add_u32 s12, s88, s4
	s_addc_u32 s13, s89, 0
	s_add_u32 s14, s12, 0x164000
	s_addc_u32 s15, s13, 0
	s_add_u32 s12, s12, 0x163000
	s_addc_u32 s13, s13, 0
	global_load_dwordx4 v[48:51], v176, s[6:7]
	global_load_dwordx4 v[52:55], v176, s[6:7] offset:1024
	global_load_dwordx4 v[56:59], v176, s[6:7] offset:2048
	global_load_dwordx4 v[60:63], v176, s[6:7] offset:3072
	global_load_dwordx4 v[64:67], v176, s[14:15]
	global_load_dwordx4 v[68:71], v176, s[14:15] offset:1024
	global_load_dwordx4 v[72:75], v176, s[14:15] offset:2048
	global_load_dwordx4 v[76:79], v176, s[14:15] offset:3072
	global_load_dwordx4 v[80:83], v176, s[12:13]
	global_load_dwordx4 v[84:87], v176, s[12:13] offset:1024
	global_load_dwordx4 v[88:91], v176, s[12:13] offset:2048
	global_load_dwordx4 v[92:95], v176, s[12:13] offset:3072
	s_cmp_lt_u32 s20, 0x10000
	s_cbranch_scc0 .LNb_done
; __device__ __forceinline__ unsigned cvt_pk_bf16(float lo, float hi) { unsigned r; asm volatile("v_cvt_pk_bf16_f32 %0, %1, %2" : "=v"(r) : "v"(lo), "v"(hi)); return r; }
; __device__ __forceinline__ void phase_norm_mod(const float* x, const float* mod_shift, const float* mod_scale, bf16_t* H, int) {
;     ...
;         for (int r = 0; r < NR; ++r) { const int m = M - 1 - (m0 + r * NGW < M ? m0 + r * NGW : m0); const f32x4* xr = (const f32x4*)(x + (size_t)m * D) + lane;
; #pragma unroll
;             for (int j = 0; j < 4; ++j) v[r][j] = xr[64 * j]; }
; #pragma unroll
;         for (int r = 0; r < NR; ++r) { const int m = M - 1 - (m0 + r * NGW); if (m >= 0) {
;             const int b = m >> 12; float s = 0.f;
; #pragma unroll
;             for (int j = 0; j < 4; ++j) s += (v[r][j].x * v[r][j].x + v[r][j].y * v[r][j].y) + (v[r][j].z * v[r][j].z + v[r][j].w * v[r][j].w);
;             const float rstd = 1.0f / sqrtf(wave_sum(s) * (1.f / D) + 1e-6f);
;             const f32x4* sh = (const f32x4*)(mod_shift + (size_t)b * 6144) + lane;
;             const f32x4* sc = (const f32x4*)(mod_scale + (size_t)b * 6144) + lane;
;             u32x2* o = (u32x2*)(H + (size_t)m * D) + lane;
; #pragma unroll
;             for (int j = 0; j < 4; ++j) { const f32x4 a = sh[64 * j], c = sc[64 * j]; const f32x4 h = v[r][j] * rstd * (c + 1.0f) + a;
;                 u32x2 w; w.x = cvt_pk_bf16(h.x, h.y); w.y = cvt_pk_bf16(h.z, h.w); o[64 * j] = w; } } }
	s_waitcnt vmcnt(24)
	v_pk_mul_f32 v[172:173], v[96:97], v[96:97]
	v_pk_mul_f32 v[174:175], v[98:99], v[98:99]
	v_pk_fma_f32 v[172:173], v[100:101], v[100:101], v[172:173]
	v_pk_fma_f32 v[174:175], v[102:103], v[102:103], v[174:175]
	v_pk_fma_f32 v[172:173], v[104:105], v[104:105], v[172:173]
	v_pk_fma_f32 v[174:175], v[106:107], v[106:107], v[174:175]
	v_pk_fma_f32 v[172:173], v[108:109], v[108:109], v[172:173]
	v_pk_fma_f32 v[174:175], v[110:111], v[110:111], v[174:175]
	v_pk_add_f32 v[172:173], v[172:173], v[174:175]
	s_sub_u32 s3, 0xffff, s20
	s_lshl_b32 s4, s3, 11
	v_add_f32_e32 v160, v172, v173
	s_add_u32 s16, s88, s4
	s_addc_u32 s17, s89, 0
	s_nop 1
	v_add_f32_dpp v160, v160, v160 quad_perm:[1,0,3,2] row_mask:0xf bank_mask:0xf bound_ctrl:1
	s_nop 1
	v_add_f32_dpp v160, v160, v160 quad_perm:[2,3,0,1] row_mask:0xf bank_mask:0xf bound_ctrl:1
	s_nop 1
	v_add_f32_dpp v160, v160, v160 row_half_mirror row_mask:0xf bank_mask:0xf bound_ctrl:1
	s_nop 1
	v_add_f32_dpp v160, v160, v160 row_mirror row_mask:0xf bank_mask:0xf bound_ctrl:1
	s_add_u32 s16, s16, 0x3c00000
	s_addc_u32 s17, s17, 0
	v_readlane_b32 s4, v160, 0
	v_readlane_b32 s5, v160, 16
	v_readlane_b32 s21, v160, 32
	v_readlane_b32 s22, v160, 48
	s_nop 1
	v_mov_b32_e32 v160, s4
	v_add_f32_e32 v160, s5, v160
	v_add_f32_e32 v160, s21, v160
	v_add_f32_e32 v160, s22, v160
	v_fmamk_f32 v160, v160, 0x3a800000, v170
	s_mov_b32 s23, 0xf800000
	v_mul_f32_e32 v161, 0x4f800000, v160
	v_cmp_gt_f32_e32 vcc, s23, v160
	s_nop 1
	v_cndmask_b32_e32 v162, v160, v161, vcc
	v_sqrt_f32_e32 v164, v162
	s_nop 0
	v_add_u32_e32 v165, -1, v164
	v_add_u32_e32 v166, 1, v164
	v_fma_f32 v167, -v165, v164, v162
	v_fma_f32 v168, -v166, v164, v162
	v_cmp_ge_f32_e64 s[4:5], 0, v167
	s_nop 1
	v_cndmask_b32_e64 v164, v164, v165, s[4:5]
	v_cmp_lt_f32_e64 s[4:5], 0, v168
	s_nop 1
	v_cndmask_b32_e64 v164, v164, v166, s[4:5]
	v_mul_f32_e32 v165, 0x37800000, v164
	v_cndmask_b32_e32 v164, v164, v165, vcc
	v_cmp_class_f32_e32 vcc, v162, v171
	s_nop 1
	v_cndmask_b32_e32 v162, v164, v162, vcc
	v_div_scale_f32 v164, s[4:5], v162, v162, 1.0
	v_rcp_f32_e32 v165, v164
	v_div_scale_f32 v166, vcc, 1.0, v162, 1.0
	v_fma_f32 v167, -v164, v165, 1.0
	v_fmac_f32_e32 v165, v167, v165
	v_mul_f32_e32 v167, v166, v165
	v_fma_f32 v168, -v164, v167, v166
	v_fmac_f32_e32 v167, v168, v165
	v_fma_f32 v164, -v164, v167, v166
	v_div_fmas_f32 v164, v164, v165, v167
	v_div_fixup_f32 v162, v164, v162, 1.0
	v_pk_mul_f32 v[96:97], v[96:97], v[162:163] op_sel_hi:[1,0]
	v_pk_mul_f32 v[98:99], v[98:99], v[162:163] op_sel_hi:[1,0]
	v_pk_add_f32 v[112:113], v[112:113], 1.0 op_sel_hi:[1,0]
	v_pk_add_f32 v[114:115], v[114:115], 1.0 op_sel_hi:[1,0]
	v_pk_fma_f32 v[96:97], v[112:113], v[96:97], v[128:129]
	v_pk_fma_f32 v[98:99], v[114:115], v[98:99], v[130:131]
	v_cvt_pk_bf16_f32 v152, v96, v97
	v_cvt_pk_bf16_f32 v153, v98, v99
	v_pk_mul_f32 v[100:101], v[100:101], v[162:163] op_sel_hi:[1,0]
	v_pk_mul_f32 v[102:103], v[102:103], v[162:163] op_sel_hi:[1,0]
	v_pk_add_f32 v[116:117], v[116:117], 1.0 op_sel_hi:[1,0]
	v_pk_add_f32 v[118:119], v[118:119], 1.0 op_sel_hi:[1,0]
	v_pk_fma_f32 v[100:101], v[116:117], v[100:101], v[132:133]
	v_pk_fma_f32 v[102:103], v[118:119], v[102:103], v[134:135]
	v_cvt_pk_bf16_f32 v154, v100, v101
	v_cvt_pk_bf16_f32 v155, v102, v103
	v_pk_mul_f32 v[104:105], v[104:105], v[162:163] op_sel_hi:[1,0]
	v_pk_mul_f32 v[106:107], v[106:107], v[162:163] op_sel_hi:[1,0]
	v_pk_add_f32 v[120:121], v[120:121], 1.0 op_sel_hi:[1,0]
	v_pk_add_f32 v[122:123], v[122:123], 1.0 op_sel_hi:[1,0]
	v_pk_fma_f32 v[104:105], v[120:121], v[104:105], v[136:137]
	v_pk_fma_f32 v[106:107], v[122:123], v[106:107], v[138:139]
	v_cvt_pk_bf16_f32 v156, v104, v105
	v_cvt_pk_bf16_f32 v157, v106, v107
	v_pk_mul_f32 v[108:109], v[108:109], v[162:163] op_sel_hi:[1,0]
	v_pk_mul_f32 v[110:111], v[110:111], v[162:163] op_sel_hi:[1,0]
	v_pk_add_f32 v[124:125], v[124:125], 1.0 op_sel_hi:[1,0]
	v_pk_add_f32 v[126:127], v[126:127], 1.0 op_sel_hi:[1,0]
	v_pk_fma_f32 v[108:109], v[124:125], v[108:109], v[140:141]
	v_pk_fma_f32 v[110:111], v[126:127], v[110:111], v[142:143]
	v_cvt_pk_bf16_f32 v158, v108, v109
	v_cvt_pk_bf16_f32 v159, v110, v111
	global_store_dwordx2 v177, v[152:153], s[16:17]
	global_store_dwordx2 v177, v[154:155], s[16:17] offset:512
	global_store_dwordx2 v177, v[156:157], s[16:17] offset:1024
	global_store_dwordx2 v177, v[158:159], s[16:17] offset:1536
	s_add_i32 s20, s20, s1
	s_cmp_lt_u32 s20, 0x10000
	s_cselect_b32 s3, s20, s0
	s_sub_u32 s3, 0xffff, s3
	s_lshl_b32 s4, s3, 12
	s_add_u32 s6, s86, s4
	s_addc_u32 s7, s87, 0
	s_lshr_b32 s4, s3, 12
	s_mul_i32 s4, s4, 0x6000
	s_add_u32 s12, s88, s4
	s_addc_u32 s13, s89, 0
	s_add_u32 s14, s12, 0x164000
	s_addc_u32 s15, s13, 0
	s_add_u32 s12, s12, 0x163000
	s_addc_u32 s13, s13, 0
	global_load_dwordx4 v[96:99], v176, s[6:7]
	global_load_dwordx4 v[100:103], v176, s[6:7] offset:1024
	global_load_dwordx4 v[104:107], v176, s[6:7] offset:2048
	global_load_dwordx4 v[108:111], v176, s[6:7] offset:3072
	global_load_dwordx4 v[112:115], v176, s[14:15]
	global_load_dwordx4 v[116:119], v176, s[14:15] offset:1024
	global_load_dwordx4 v[120:123], v176, s[14:15] offset:2048
	global_load_dwordx4 v[124:127], v176, s[14:15] offset:3072
	global_load_dwordx4 v[128:131], v176, s[12:13]
	global_load_dwordx4 v[132:135], v176, s[12:13] offset:1024
	global_load_dwordx4 v[136:139], v176, s[12:13] offset:2048
	global_load_dwordx4 v[140:143], v176, s[12:13] offset:3072
	s_branch .LNb_loop
